# combo20 with every s_setprio removed from the GEMM K-loops (both wave halves at priority 0, age arbitration only)
# speedup vs baseline: 1.0024x; 1.0024x over previous
; #define PG8_STAGE(bufoff, gbase, voff) do { _Pragma("unroll") for (int _i = 0; _i < 2; ++_i) \
;         __builtin_amdgcn_global_load_lds((const unsigned*)((const char*)(gbase) + (voff)[_i]), (LAS unsigned*)(lds + (bufoff) + ldsw + _i * 8192), 16, 0, 0); } while (0)
; #define PG8_LDA(dst, b, h) do { _Pragma("unroll") for (int m = 0; m < 4; ++m) _Pragma("unroll") for (int k = 0; k < 2; ++k) dst[m][k] = *(const LAS bf16x8*)(lds + PG8_SA(b, h) + aoff + m * 2048 + k * 1024); } while (0)
; #define PG8_LDB(dst, b, h) do { _Pragma("unroll") for (int n = 0; n < 2; ++n) _Pragma("unroll") for (int k = 0; k < 2; ++k) dst[n][k] = *(const LAS bf16x8*)(lds + PG8_SB(b, h) + boff + n * 2048 + k * 1024); } while (0)
; #define PG8_MMA(ai, bj, At, Bt) do { __builtin_amdgcn_s_setprio(1); _Pragma("unroll") for (int m = 0; m < 4; ++m) _Pragma("unroll") for (int n = 0; n < 2; ++n) _Pragma("unroll") for (int k = 0; k < 2; ++k) \
;         acc[ai][bj][m][n] = __builtin_amdgcn_mfma_f32_16x16x32_bf16(Bt[n][k], At[m][k], acc[ai][bj][m][n], 0, 0, 0); __builtin_amdgcn_s_setprio(0); } while (0)
; #define PG8_WAIT_V(n) asm volatile("s_waitcnt vmcnt(" #n ")" ::: "memory")
; #define PG8_BAR __builtin_amdgcn_s_barrier()
; template <class Epi>
; __device__ __forceinline__ void gemm_phase(LAS unsigned char* lds, const Gemm g, const StaticOrder& S, const Epi& E, const int tid) {
;     ...
;         const bool has_next = S.next(ui + 1, nxt);
;         const char* nA = has_next ? PG8_APTR(nxt) : cA; const char* nB = has_next ? PG8_BPTR(nxt) : cB;
;         for (int t = 0; t < nt; t += 2) {
;             const bool last = (t == nt - 2);
;             const char* a1 = cA + (size_t)(t + 1) * kstep;
;             const char* a2 = last ? nA : cA + (size_t)(t + 2) * kstep; const char* b2 = last ? nB : cB + (size_t)(t + 2) * kstep;
;             const char* a3 = a2 + kstep; const char* b3 = b2 + kstep;
;             PG8_LDB(B0, 0, 0); PG8_LDB(B1, 0, 1); PG8_SCHED; PG8_LDA(At, 0, 0); PG8_STAGE(PG8_SA(1, 1), a1 + hsA, voffA);
;             PG8_WAIT_V(8); PG8_WAIT_L(0); PG8_BAR; PG8_MMA(0, 0, At, B0); PG8_MMA(0, 1, At, B1); PG8_BAR; PG8_SCHED;
;             PG8_LDA(At, 0, 1); PG8_STAGE(PG8_SB(0, 0), b2, voffB); PG8_STAGE(PG8_SB(0, 1), b2 + hsB, voffB); PG8_STAGE(PG8_SA(0, 0), a2, voffA);
;             PG8_WAIT_V(8); PG8_WAIT_L(0); PG8_BAR; PG8_MMA(1, 0, At, B0); PG8_MMA(1, 1, At, B1); PG8_BAR; PG8_SCHED;
.LBB0_160:
	s_ashr_i32 s15, s14, 31
	s_lshl_b64 s[16:17], s[14:15], 20
	s_add_u32 s16, s58, s16
	s_addc_u32 s17, s59, s17
	s_and_b64 s[18:19], s[36:37], exec
	s_cselect_b32 s15, s17, s35
	s_cselect_b32 s53, s16, s34
	s_ashr_i32 s13, s12, 31
	s_lshl_b64 s[18:19], s[12:13], 20
	s_add_u32 s18, s40, s18
	s_addc_u32 s19, s41, s19
	s_and_b64 s[38:39], s[36:37], exec
	s_cselect_b32 s13, s19, s1
	s_cselect_b32 s56, s18, s0
	s_add_u32 s34, s34, 0x80080
	s_addc_u32 s35, s35, 0
	s_add_u32 s57, s0, 0x100
	s_addc_u32 s58, s1, 0
	s_mov_b32 s59, -2
	s_add_u32 s0, s34, 0xfff80080
	s_addc_u32 s1, s35, -1
	s_add_i32 s24, 0, 0x10000
	s_cmp_eq_u32 s59, 28
	s_cselect_b32 s39, s15, s1
	s_cselect_b32 s38, s53, s0
	s_cselect_b32 s1, s13, s58
	s_cselect_b32 s0, s56, s57
	s_add_i32 s25, 0, 0x14000
	v_add_u32_e32 v154, s24, v143
	v_add_u32_e32 v166, s25, v143
	ds_read_b128 v[138:141], v154
	ds_read_b128 v[146:149], v154 offset:1024
	ds_read_b128 v[150:153], v154 offset:2048
	ds_read_b128 v[154:157], v154 offset:3072
	ds_read_b128 v[158:161], v166
	ds_read_b128 v[162:165], v166 offset:1024
	ds_read_b128 v[184:187], v166 offset:2048
	ds_read_b128 v[188:191], v166 offset:3072
	v_lshl_add_u64 v[166:167], s[34:35], 0, v[134:135]
	s_add_i32 m0, s42, 0xc000
	ds_read_b128 v[192:195], v145
	ds_read_b128 v[196:199], v145 offset:1024
	ds_read_b128 v[200:203], v145 offset:2048
	ds_read_b128 v[204:207], v145 offset:3072
	ds_read_b128 v[208:211], v145 offset:4096
	ds_read_b128 v[230:233], v145 offset:5120
	ds_read_b128 v[234:237], v145 offset:6144
	ds_read_b128 v[238:241], v145 offset:7168
	global_load_lds_dwordx4 v[166:167], off
	v_lshl_add_u64 v[166:167], s[34:35], 0, v[136:137]
	s_add_i32 m0, s42, 0xe000
	s_nop 0
	global_load_lds_dwordx4 v[166:167], off
	s_waitcnt vmcnt(8)
	s_waitcnt lgkmcnt(0)
	s_barrier
	v_mfma_f32_16x16x32_bf16 v[124:127], v[138:141], v[192:195], 0
	v_mfma_f32_16x16x32_bf16 v[116:119], v[150:153], v[192:195], 0
	v_mfma_f32_16x16x32_bf16 v[108:111], v[138:141], v[200:203], 0
	v_mfma_f32_16x16x32_bf16 v[100:103], v[150:153], v[200:203], 0
	v_mfma_f32_16x16x32_bf16 v[92:95], v[138:141], v[208:211], 0
	v_mfma_f32_16x16x32_bf16 v[84:87], v[150:153], v[208:211], 0
	v_mfma_f32_16x16x32_bf16 v[76:79], v[138:141], v[234:237], 0
	v_mfma_f32_16x16x32_bf16 v[68:71], v[150:153], v[234:237], 0
	v_mfma_f32_16x16x32_bf16 v[124:127], v[146:149], v[196:199], v[124:127]
	v_mfma_f32_16x16x32_bf16 v[116:119], v[154:157], v[196:199], v[116:119]
	v_mfma_f32_16x16x32_bf16 v[108:111], v[146:149], v[204:207], v[108:111]
	v_mfma_f32_16x16x32_bf16 v[100:103], v[154:157], v[204:207], v[100:103]
	v_mfma_f32_16x16x32_bf16 v[92:95], v[146:149], v[230:233], v[92:95]
	v_mfma_f32_16x16x32_bf16 v[84:87], v[154:157], v[230:233], v[84:87]
	v_mfma_f32_16x16x32_bf16 v[76:79], v[146:149], v[238:241], v[76:79]
	v_mfma_f32_16x16x32_bf16 v[68:71], v[154:157], v[238:241], v[68:71]
	v_mfma_f32_16x16x32_bf16 v[120:123], v[158:161], v[192:195], 0
	v_mfma_f32_16x16x32_bf16 v[112:115], v[184:187], v[192:195], 0
	v_mfma_f32_16x16x32_bf16 v[104:107], v[158:161], v[200:203], 0
	v_mfma_f32_16x16x32_bf16 v[96:99], v[184:187], v[200:203], 0
	v_mfma_f32_16x16x32_bf16 v[88:91], v[158:161], v[208:211], 0
	v_mfma_f32_16x16x32_bf16 v[80:83], v[184:187], v[208:211], 0
	v_mfma_f32_16x16x32_bf16 v[72:75], v[158:161], v[234:237], 0
	v_mfma_f32_16x16x32_bf16 v[64:67], v[184:187], v[234:237], 0
	v_mfma_f32_16x16x32_bf16 v[120:123], v[162:165], v[196:199], v[120:123]
	v_mfma_f32_16x16x32_bf16 v[112:115], v[188:191], v[196:199], v[112:115]
	v_mfma_f32_16x16x32_bf16 v[104:107], v[162:165], v[204:207], v[104:107]
	v_mfma_f32_16x16x32_bf16 v[96:99], v[188:191], v[204:207], v[96:99]
	v_mfma_f32_16x16x32_bf16 v[88:91], v[162:165], v[230:233], v[88:91]
	v_mfma_f32_16x16x32_bf16 v[80:83], v[188:191], v[230:233], v[80:83]
	v_mfma_f32_16x16x32_bf16 v[72:75], v[162:165], v[238:241], v[72:75]
	v_mfma_f32_16x16x32_bf16 v[64:67], v[188:191], v[238:241], v[64:67]
	s_barrier
	s_add_i32 s24, s24, s27
	v_lshl_add_u64 v[166:167], s[0:1], 0, v[168:169]
	s_mov_b32 m0, s24
	ds_read_b128 v[192:195], v145 offset:16384
	ds_read_b128 v[196:199], v145 offset:17408
	ds_read_b128 v[200:203], v145 offset:18432
	ds_read_b128 v[204:207], v145 offset:19456
	ds_read_b128 v[208:211], v145 offset:20480
	ds_read_b128 v[230:233], v145 offset:21504
	ds_read_b128 v[234:237], v145 offset:22528
	ds_read_b128 v[238:241], v145 offset:23552
	global_load_lds_dwordx4 v[166:167], off
	s_add_i32 m0, s24, 0x2000
	s_add_u32 s68, s0, 0x80000
	v_lshl_add_u64 v[212:213], s[0:1], 0, v[132:133]
	s_addc_u32 s69, s1, 0
	s_add_i32 s24, s25, s27
	global_load_lds_dwordx4 v[212:213], off
	v_lshl_add_u64 v[242:243], s[68:69], 0, v[168:169]
	s_mov_b32 m0, s24
	v_lshl_add_u64 v[244:245], s[38:39], 0, v[130:131]
	global_load_lds_dwordx4 v[242:243], off
	v_lshl_add_u64 v[242:243], s[68:69], 0, v[132:133]
	s_add_i32 m0, s24, 0x2000
	s_nop 0
	global_load_lds_dwordx4 v[242:243], off
	v_lshl_add_u64 v[242:243], s[38:39], 0, v[128:129]
	s_mov_b32 m0, s42
	s_nop 0
	global_load_lds_dwordx4 v[242:243], off
	s_mov_b32 m0, s43
	s_nop 0
	global_load_lds_dwordx4 v[244:245], off
	s_waitcnt vmcnt(8)
	s_waitcnt lgkmcnt(0)
	s_barrier
; #define PG8_STAGE(bufoff, gbase, voff) do { _Pragma("unroll") for (int _i = 0; _i < 2; ++_i) \
;         __builtin_amdgcn_global_load_lds((const unsigned*)((const char*)(gbase) + (voff)[_i]), (LAS unsigned*)(lds + (bufoff) + ldsw + _i * 8192), 16, 0, 0); } while (0)
; #define PG8_LDA(dst, b, h) do { _Pragma("unroll") for (int m = 0; m < 4; ++m) _Pragma("unroll") for (int k = 0; k < 2; ++k) dst[m][k] = *(const LAS bf16x8*)(lds + PG8_SA(b, h) + aoff + m * 2048 + k * 1024); } while (0)
; #define PG8_LDB(dst, b, h) do { _Pragma("unroll") for (int n = 0; n < 2; ++n) _Pragma("unroll") for (int k = 0; k < 2; ++k) dst[n][k] = *(const LAS bf16x8*)(lds + PG8_SB(b, h) + boff + n * 2048 + k * 1024); } while (0)
; #define PG8_MMA(ai, bj, At, Bt) do { __builtin_amdgcn_s_setprio(1); _Pragma("unroll") for (int m = 0; m < 4; ++m) _Pragma("unroll") for (int n = 0; n < 2; ++n) _Pragma("unroll") for (int k = 0; k < 2; ++k) \
;         acc[ai][bj][m][n] = __builtin_amdgcn_mfma_f32_16x16x32_bf16(Bt[n][k], At[m][k], acc[ai][bj][m][n], 0, 0, 0); __builtin_amdgcn_s_setprio(0); } while (0)
; #define PG8_WAIT_V(n) asm volatile("s_waitcnt vmcnt(" #n ")" ::: "memory")
; #define PG8_WAIT_L(n) asm volatile("s_waitcnt lgkmcnt(" #n ")" ::: "memory")
; #define PG8_BAR __builtin_amdgcn_s_barrier()
; #define PG8_SCHED __builtin_amdgcn_sched_barrier(0)
; template <class Epi>
; __device__ __forceinline__ void gemm_phase(LAS unsigned char* lds, const Gemm g, const StaticOrder& S, const Epi& E, const int tid) {
;     ...
;             PG8_WAIT_V(8); PG8_WAIT_L(0); PG8_BAR; PG8_MMA(1, 0, At, B0); PG8_MMA(1, 1, At, B1); PG8_BAR; PG8_SCHED;
;             PG8_LDB(B0, 1, 0); PG8_LDB(B1, 1, 1); PG8_SCHED; PG8_LDA(At, 1, 0); PG8_STAGE(PG8_SA(0, 1), a2 + hsA, voffA);
;             PG8_WAIT_V(8); PG8_WAIT_L(0); PG8_BAR; PG8_MMA(0, 0, At, B0); PG8_MMA(0, 1, At, B1); PG8_BAR; PG8_SCHED;
	v_mfma_f32_16x16x32_bf16 v[60:63], v[138:141], v[192:195], 0
	v_mfma_f32_16x16x32_bf16 v[52:55], v[150:153], v[192:195], 0
	v_mfma_f32_16x16x32_bf16 v[44:47], v[138:141], v[200:203], 0
	v_mfma_f32_16x16x32_bf16 v[36:39], v[150:153], v[200:203], 0
	v_mfma_f32_16x16x32_bf16 v[28:31], v[138:141], v[208:211], 0
	v_mfma_f32_16x16x32_bf16 v[20:23], v[150:153], v[208:211], 0
	v_mfma_f32_16x16x32_bf16 v[12:15], v[138:141], v[234:237], 0
	v_mfma_f32_16x16x32_bf16 v[4:7], v[150:153], v[234:237], 0
	v_mfma_f32_16x16x32_bf16 v[60:63], v[146:149], v[196:199], v[60:63]
	v_mfma_f32_16x16x32_bf16 v[52:55], v[154:157], v[196:199], v[52:55]
	v_mfma_f32_16x16x32_bf16 v[44:47], v[146:149], v[204:207], v[44:47]
	v_mfma_f32_16x16x32_bf16 v[36:39], v[154:157], v[204:207], v[36:39]
	v_mfma_f32_16x16x32_bf16 v[28:31], v[146:149], v[230:233], v[28:31]
	v_mfma_f32_16x16x32_bf16 v[20:23], v[154:157], v[230:233], v[20:23]
	v_mfma_f32_16x16x32_bf16 v[12:15], v[146:149], v[238:241], v[12:15]
	v_mfma_f32_16x16x32_bf16 v[4:7], v[154:157], v[238:241], v[4:7]
	v_mfma_f32_16x16x32_bf16 v[56:59], v[158:161], v[192:195], 0
	v_mfma_f32_16x16x32_bf16 v[48:51], v[184:187], v[192:195], 0
	v_mfma_f32_16x16x32_bf16 v[40:43], v[158:161], v[200:203], 0
	v_mfma_f32_16x16x32_bf16 v[32:35], v[184:187], v[200:203], 0
	v_mfma_f32_16x16x32_bf16 v[24:27], v[158:161], v[208:211], 0
	v_mfma_f32_16x16x32_bf16 v[16:19], v[184:187], v[208:211], 0
	v_mfma_f32_16x16x32_bf16 v[8:11], v[158:161], v[234:237], 0
	v_mfma_f32_16x16x32_bf16 v[0:3], v[184:187], v[234:237], 0
	v_mfma_f32_16x16x32_bf16 v[56:59], v[162:165], v[196:199], v[56:59]
	v_mfma_f32_16x16x32_bf16 v[48:51], v[188:191], v[196:199], v[48:51]
	v_mfma_f32_16x16x32_bf16 v[40:43], v[162:165], v[204:207], v[40:43]
	v_mfma_f32_16x16x32_bf16 v[32:35], v[188:191], v[204:207], v[32:35]
	v_mfma_f32_16x16x32_bf16 v[24:27], v[162:165], v[230:233], v[24:27]
	v_mfma_f32_16x16x32_bf16 v[16:19], v[188:191], v[230:233], v[16:19]
	v_mfma_f32_16x16x32_bf16 v[8:11], v[162:165], v[238:241], v[8:11]
	v_mfma_f32_16x16x32_bf16 v[0:3], v[188:191], v[238:241], v[0:3]
	s_barrier
	s_add_i32 s24, 0, 0x18000
	s_add_i32 s25, 0, 0x1c000
	v_add_u32_e32 v154, s24, v143
	v_add_u32_e32 v170, s25, v143
	ds_read_b128 v[138:141], v154
	ds_read_b128 v[146:149], v154 offset:1024
	ds_read_b128 v[150:153], v154 offset:2048
	ds_read_b128 v[154:157], v154 offset:3072
	ds_read_b128 v[158:161], v170
	ds_read_b128 v[162:165], v170 offset:1024
	ds_read_b128 v[184:187], v170 offset:2048
	ds_read_b128 v[188:191], v170 offset:3072
	s_add_u32 s38, s38, 0x80000
	s_addc_u32 s39, s39, 0
	s_mov_b32 m0, s44
	v_lshl_add_u64 v[246:247], s[38:39], 0, v[128:129]
	ds_read_b128 v[192:195], v145 offset:32768
	ds_read_b128 v[196:199], v145 offset:33792
	ds_read_b128 v[200:203], v145 offset:34816
	ds_read_b128 v[204:207], v145 offset:35840
	ds_read_b128 v[208:211], v145 offset:36864
	ds_read_b128 v[230:233], v145 offset:37888
	ds_read_b128 v[234:237], v145 offset:38912
	ds_read_b128 v[238:241], v145 offset:39936
	global_load_lds_dwordx4 v[246:247], off
	v_lshl_add_u64 v[246:247], s[38:39], 0, v[130:131]
	s_mov_b32 m0, s45
	s_nop 0
	global_load_lds_dwordx4 v[246:247], off
	s_waitcnt vmcnt(8)
	s_waitcnt lgkmcnt(0)
	s_barrier
	v_mfma_f32_16x16x32_bf16 v[124:127], v[138:141], v[192:195], v[124:127]
	v_mfma_f32_16x16x32_bf16 v[116:119], v[150:153], v[192:195], v[116:119]
	v_mfma_f32_16x16x32_bf16 v[108:111], v[138:141], v[200:203], v[108:111]
	v_mfma_f32_16x16x32_bf16 v[100:103], v[150:153], v[200:203], v[100:103]
	v_mfma_f32_16x16x32_bf16 v[92:95], v[138:141], v[208:211], v[92:95]
	v_mfma_f32_16x16x32_bf16 v[84:87], v[150:153], v[208:211], v[84:87]
	v_mfma_f32_16x16x32_bf16 v[76:79], v[138:141], v[234:237], v[76:79]
	v_mfma_f32_16x16x32_bf16 v[68:71], v[150:153], v[234:237], v[68:71]
	v_mfma_f32_16x16x32_bf16 v[124:127], v[146:149], v[196:199], v[124:127]
	v_mfma_f32_16x16x32_bf16 v[116:119], v[154:157], v[196:199], v[116:119]
	v_mfma_f32_16x16x32_bf16 v[108:111], v[146:149], v[204:207], v[108:111]
	v_mfma_f32_16x16x32_bf16 v[100:103], v[154:157], v[204:207], v[100:103]
	v_mfma_f32_16x16x32_bf16 v[92:95], v[146:149], v[230:233], v[92:95]
	v_mfma_f32_16x16x32_bf16 v[84:87], v[154:157], v[230:233], v[84:87]
	v_mfma_f32_16x16x32_bf16 v[76:79], v[146:149], v[238:241], v[76:79]
	v_mfma_f32_16x16x32_bf16 v[68:71], v[154:157], v[238:241], v[68:71]
	v_mfma_f32_16x16x32_bf16 v[120:123], v[158:161], v[192:195], v[120:123]
	v_mfma_f32_16x16x32_bf16 v[112:115], v[184:187], v[192:195], v[112:115]
	v_mfma_f32_16x16x32_bf16 v[104:107], v[158:161], v[200:203], v[104:107]
	v_mfma_f32_16x16x32_bf16 v[96:99], v[184:187], v[200:203], v[96:99]
	v_mfma_f32_16x16x32_bf16 v[88:91], v[158:161], v[208:211], v[88:91]
	v_mfma_f32_16x16x32_bf16 v[80:83], v[184:187], v[208:211], v[80:83]
	v_mfma_f32_16x16x32_bf16 v[72:75], v[158:161], v[234:237], v[72:75]
	v_mfma_f32_16x16x32_bf16 v[64:67], v[184:187], v[234:237], v[64:67]
	v_mfma_f32_16x16x32_bf16 v[120:123], v[162:165], v[196:199], v[120:123]
	v_mfma_f32_16x16x32_bf16 v[112:115], v[188:191], v[196:199], v[112:115]
	v_mfma_f32_16x16x32_bf16 v[104:107], v[162:165], v[204:207], v[104:107]
	v_mfma_f32_16x16x32_bf16 v[96:99], v[188:191], v[204:207], v[96:99]
	v_mfma_f32_16x16x32_bf16 v[88:91], v[162:165], v[230:233], v[88:91]
	v_mfma_f32_16x16x32_bf16 v[80:83], v[188:191], v[230:233], v[80:83]
	v_mfma_f32_16x16x32_bf16 v[72:75], v[162:165], v[238:241], v[72:75]
	v_mfma_f32_16x16x32_bf16 v[64:67], v[188:191], v[238:241], v[64:67]
	s_barrier
; #define PG8_STAGE(bufoff, gbase, voff) do { _Pragma("unroll") for (int _i = 0; _i < 2; ++_i) \
;         __builtin_amdgcn_global_load_lds((const unsigned*)((const char*)(gbase) + (voff)[_i]), (LAS unsigned*)(lds + (bufoff) + ldsw + _i * 8192), 16, 0, 0); } while (0)
; #define PG8_LDA(dst, b, h) do { _Pragma("unroll") for (int m = 0; m < 4; ++m) _Pragma("unroll") for (int k = 0; k < 2; ++k) dst[m][k] = *(const LAS bf16x8*)(lds + PG8_SA(b, h) + aoff + m * 2048 + k * 1024); } while (0)
; #define PG8_MMA(ai, bj, At, Bt) do { __builtin_amdgcn_s_setprio(1); _Pragma("unroll") for (int m = 0; m < 4; ++m) _Pragma("unroll") for (int n = 0; n < 2; ++n) _Pragma("unroll") for (int k = 0; k < 2; ++k) \
;         acc[ai][bj][m][n] = __builtin_amdgcn_mfma_f32_16x16x32_bf16(Bt[n][k], At[m][k], acc[ai][bj][m][n], 0, 0, 0); __builtin_amdgcn_s_setprio(0); } while (0)
; #define PG8_WAIT_V(n) asm volatile("s_waitcnt vmcnt(" #n ")" ::: "memory")
; #define PG8_WAIT_L(n) asm volatile("s_waitcnt lgkmcnt(" #n ")" ::: "memory")
; #define PG8_BAR __builtin_amdgcn_s_barrier()
; #define PG8_SCHED __builtin_amdgcn_sched_barrier(0)
; template <class Epi>
; __device__ __forceinline__ void gemm_phase(LAS unsigned char* lds, const Gemm g, const StaticOrder& S, const Epi& E, const int tid) {
;     ...
;             PG8_WAIT_V(8); PG8_WAIT_L(0); PG8_BAR; PG8_MMA(0, 0, At, B0); PG8_MMA(0, 1, At, B1); PG8_BAR; PG8_SCHED;
;             PG8_LDA(At, 1, 1); PG8_STAGE(PG8_SB(1, 0), b3, voffB); PG8_STAGE(PG8_SB(1, 1), b3 + hsB, voffB); PG8_STAGE(PG8_SA(1, 0), a3, voffA);
;             PG8_WAIT_V(8); PG8_WAIT_L(0); PG8_BAR; PG8_MMA(1, 0, At, B0); PG8_MMA(1, 1, At, B1); PG8_BAR; PG8_SCHED;
	s_add_i32 s24, s24, s27
	v_lshl_add_u64 v[166:167], v[166:167], 0, s[28:29]
	s_mov_b32 m0, s24
	ds_read_b128 v[192:195], v145 offset:49152
	ds_read_b128 v[196:199], v145 offset:50176
	ds_read_b128 v[200:203], v145 offset:51200
	ds_read_b128 v[204:207], v145 offset:52224
	ds_read_b128 v[208:211], v145 offset:53248
	ds_read_b128 v[230:233], v145 offset:54272
	ds_read_b128 v[234:237], v145 offset:55296
	ds_read_b128 v[238:241], v145 offset:56320
	global_load_lds_dwordx4 v[166:167], off
	s_add_i32 m0, s24, 0x2000
	s_add_u32 s0, s0, 0x80080
	v_lshl_add_u64 v[166:167], v[212:213], 0, s[28:29]
	s_addc_u32 s1, s1, 0
	s_add_i32 s24, s25, s27
	global_load_lds_dwordx4 v[166:167], off
	v_lshl_add_u64 v[166:167], s[0:1], 0, v[168:169]
	s_mov_b32 m0, s24
	s_nop 0
	global_load_lds_dwordx4 v[166:167], off
	v_lshl_add_u64 v[166:167], s[0:1], 0, v[132:133]
	s_add_i32 m0, s24, 0x2000
	s_nop 0
	global_load_lds_dwordx4 v[166:167], off
	v_lshl_add_u64 v[166:167], v[242:243], 0, s[28:29]
	s_mov_b32 m0, s46
	s_nop 0
	global_load_lds_dwordx4 v[166:167], off
	v_lshl_add_u64 v[166:167], v[244:245], 0, s[28:29]
	s_mov_b32 m0, s47
	s_nop 0
	global_load_lds_dwordx4 v[166:167], off
	s_waitcnt vmcnt(8)
	s_waitcnt lgkmcnt(0)
	s_barrier
	v_mfma_f32_16x16x32_bf16 v[60:63], v[138:141], v[192:195], v[60:63]
	v_mfma_f32_16x16x32_bf16 v[52:55], v[150:153], v[192:195], v[52:55]
	v_mfma_f32_16x16x32_bf16 v[44:47], v[138:141], v[200:203], v[44:47]
	v_mfma_f32_16x16x32_bf16 v[36:39], v[150:153], v[200:203], v[36:39]
	v_mfma_f32_16x16x32_bf16 v[28:31], v[138:141], v[208:211], v[28:31]
	v_mfma_f32_16x16x32_bf16 v[20:23], v[150:153], v[208:211], v[20:23]
	v_mfma_f32_16x16x32_bf16 v[12:15], v[138:141], v[234:237], v[12:15]
	v_mfma_f32_16x16x32_bf16 v[4:7], v[150:153], v[234:237], v[4:7]
	v_mfma_f32_16x16x32_bf16 v[60:63], v[146:149], v[196:199], v[60:63]
	v_mfma_f32_16x16x32_bf16 v[52:55], v[154:157], v[196:199], v[52:55]
	v_mfma_f32_16x16x32_bf16 v[44:47], v[146:149], v[204:207], v[44:47]
	v_mfma_f32_16x16x32_bf16 v[36:39], v[154:157], v[204:207], v[36:39]
	v_mfma_f32_16x16x32_bf16 v[28:31], v[146:149], v[230:233], v[28:31]
	v_mfma_f32_16x16x32_bf16 v[20:23], v[154:157], v[230:233], v[20:23]
	v_mfma_f32_16x16x32_bf16 v[12:15], v[146:149], v[238:241], v[12:15]
	v_mfma_f32_16x16x32_bf16 v[4:7], v[154:157], v[238:241], v[4:7]
	v_mfma_f32_16x16x32_bf16 v[56:59], v[158:161], v[192:195], v[56:59]
	v_mfma_f32_16x16x32_bf16 v[48:51], v[184:187], v[192:195], v[48:51]
	v_mfma_f32_16x16x32_bf16 v[40:43], v[158:161], v[200:203], v[40:43]
	v_mfma_f32_16x16x32_bf16 v[32:35], v[184:187], v[200:203], v[32:35]
	v_mfma_f32_16x16x32_bf16 v[24:27], v[158:161], v[208:211], v[24:27]
	v_mfma_f32_16x16x32_bf16 v[16:19], v[184:187], v[208:211], v[16:19]
	v_mfma_f32_16x16x32_bf16 v[8:11], v[158:161], v[234:237], v[8:11]
	v_mfma_f32_16x16x32_bf16 v[0:3], v[184:187], v[234:237], v[0:3]
	v_mfma_f32_16x16x32_bf16 v[56:59], v[162:165], v[196:199], v[56:59]
	v_mfma_f32_16x16x32_bf16 v[48:51], v[188:191], v[196:199], v[48:51]
	v_mfma_f32_16x16x32_bf16 v[40:43], v[162:165], v[204:207], v[40:43]
	v_mfma_f32_16x16x32_bf16 v[32:35], v[188:191], v[204:207], v[32:35]
	v_mfma_f32_16x16x32_bf16 v[24:27], v[162:165], v[230:233], v[24:27]
	v_mfma_f32_16x16x32_bf16 v[16:19], v[188:191], v[230:233], v[16:19]
	v_mfma_f32_16x16x32_bf16 v[8:11], v[162:165], v[238:241], v[8:11]
	v_mfma_f32_16x16x32_bf16 v[0:3], v[188:191], v[238:241], v[0:3]
	s_barrier
	s_add_i32 s59, s59, 2
	s_add_u32 s34, s34, 0x100
	s_addc_u32 s35, s35, 0
	s_add_u32 s57, s57, 0x100
	s_addc_u32 s58, s58, 0
	s_cmp_gt_u32 s59, 29

; #define PG8_STAGE(bufoff, gbase, voff) do { _Pragma("unroll") for (int _i = 0; _i < 2; ++_i) \
;         __builtin_amdgcn_global_load_lds((const unsigned*)((const char*)(gbase) + (voff)[_i]), (LAS unsigned*)(lds + (bufoff) + ldsw + _i * 8192), 16, 0, 0); } while (0)
; #define PG8_LDA(dst, b, h) do { _Pragma("unroll") for (int m = 0; m < 4; ++m) _Pragma("unroll") for (int k = 0; k < 2; ++k) dst[m][k] = *(const LAS bf16x8*)(lds + PG8_SA(b, h) + aoff + m * 2048 + k * 1024); } while (0)
; #define PG8_LDB(dst, b, h) do { _Pragma("unroll") for (int n = 0; n < 2; ++n) _Pragma("unroll") for (int k = 0; k < 2; ++k) dst[n][k] = *(const LAS bf16x8*)(lds + PG8_SB(b, h) + boff + n * 2048 + k * 1024); } while (0)
; #define PG8_MMA(ai, bj, At, Bt) do { __builtin_amdgcn_s_setprio(1); _Pragma("unroll") for (int m = 0; m < 4; ++m) _Pragma("unroll") for (int n = 0; n < 2; ++n) _Pragma("unroll") for (int k = 0; k < 2; ++k) \
;         acc[ai][bj][m][n] = __builtin_amdgcn_mfma_f32_16x16x32_bf16(Bt[n][k], At[m][k], acc[ai][bj][m][n], 0, 0, 0); __builtin_amdgcn_s_setprio(0); } while (0)
; #define PG8_WAIT_V(n) asm volatile("s_waitcnt vmcnt(" #n ")" ::: "memory")
; #define PG8_BAR __builtin_amdgcn_s_barrier()
; template <class Epi>
; __device__ __forceinline__ void gemm_phase(LAS unsigned char* lds, const Gemm g, const StaticOrder& S, const Epi& E, const int tid) {
;     ...
;         const bool has_next = S.next(ui + 1, nxt);
;         const char* nA = has_next ? PG8_APTR(nxt) : cA; const char* nB = has_next ? PG8_BPTR(nxt) : cB;
;         for (int t = 0; t < nt; t += 2) {
;             const bool last = (t == nt - 2);
;             const char* a1 = cA + (size_t)(t + 1) * kstep;
;             const char* a2 = last ? nA : cA + (size_t)(t + 2) * kstep; const char* b2 = last ? nB : cB + (size_t)(t + 2) * kstep;
;             const char* a3 = a2 + kstep; const char* b3 = b2 + kstep;
;             PG8_LDB(B0, 0, 0); PG8_LDB(B1, 0, 1); PG8_SCHED; PG8_LDA(At, 0, 0); PG8_STAGE(PG8_SA(1, 1), a1 + hsA, voffA);
;             PG8_WAIT_V(8); PG8_WAIT_L(0); PG8_BAR; PG8_MMA(0, 0, At, B0); PG8_MMA(0, 1, At, B1); PG8_BAR; PG8_SCHED;
;             PG8_LDA(At, 0, 1); PG8_STAGE(PG8_SB(0, 0), b2, voffB); PG8_STAGE(PG8_SB(0, 1), b2 + hsB, voffB); PG8_STAGE(PG8_SA(0, 0), a2, voffA);
;             PG8_WAIT_V(8); PG8_WAIT_L(0); PG8_BAR; PG8_MMA(1, 0, At, B0); PG8_MMA(1, 1, At, B1); PG8_BAR; PG8_SCHED;
.LBB0_232:
	s_add_u32 s42, s0, 0x100
	s_addc_u32 s43, s1, 0
	s_mov_b32 s69, -2
	s_add_u32 s0, s18, 0x100
	s_addc_u32 s1, s19, 0
	s_add_i32 s24, 0, 0x10000
	s_cmpk_eq_i32 s69, 0x54
	s_cselect_b32 s37, s15, s1
	s_cselect_b32 s36, s14, s0
	s_cselect_b32 s35, s17, s43
	s_cselect_b32 s34, s16, s42
	s_add_i32 s25, 0, 0x14000
	v_add_u32_e32 v152, s24, v193
	v_add_u32_e32 v170, s25, v193
	ds_read_b128 v[128:131], v152
	ds_read_b128 v[132:135], v152 offset:1024
	ds_read_b128 v[136:139], v152 offset:2048
	ds_read_b128 v[152:155], v152 offset:3072
	ds_read_b128 v[156:159], v170
	ds_read_b128 v[160:163], v170 offset:1024
	ds_read_b128 v[164:167], v170 offset:2048
	ds_read_b128 v[184:187], v170 offset:3072
	v_lshl_add_u64 v[212:213], s[18:19], 0, v[148:149]
	s_add_i32 m0, s44, 0xc000
	ds_read_b128 v[188:191], v198
	ds_read_b128 v[200:203], v198 offset:1024
	ds_read_b128 v[204:207], v198 offset:2048
	ds_read_b128 v[208:211], v198 offset:3072
	ds_read_b128 v[230:233], v198 offset:4096
	ds_read_b128 v[234:237], v198 offset:5120
	ds_read_b128 v[238:241], v198 offset:6144
	ds_read_b128 v[242:245], v198 offset:7168
	global_load_lds_dwordx4 v[212:213], off
	v_lshl_add_u64 v[212:213], s[18:19], 0, v[150:151]
	s_add_i32 m0, s44, 0xe000
	s_nop 0
	global_load_lds_dwordx4 v[212:213], off
	s_waitcnt vmcnt(8)
	s_waitcnt lgkmcnt(0)
	s_barrier
	v_mfma_f32_16x16x32_bf16 v[124:127], v[128:131], v[188:191], 0
	v_mfma_f32_16x16x32_bf16 v[120:123], v[136:139], v[188:191], 0
	v_mfma_f32_16x16x32_bf16 v[116:119], v[128:131], v[204:207], 0
	v_mfma_f32_16x16x32_bf16 v[108:111], v[136:139], v[204:207], 0
	v_mfma_f32_16x16x32_bf16 v[92:95], v[128:131], v[230:233], 0
	v_mfma_f32_16x16x32_bf16 v[88:91], v[136:139], v[230:233], 0
	v_mfma_f32_16x16x32_bf16 v[80:83], v[128:131], v[238:241], 0
	v_mfma_f32_16x16x32_bf16 v[72:75], v[136:139], v[238:241], 0
	v_mfma_f32_16x16x32_bf16 v[124:127], v[132:135], v[200:203], v[124:127]
	v_mfma_f32_16x16x32_bf16 v[120:123], v[152:155], v[200:203], v[120:123]
	v_mfma_f32_16x16x32_bf16 v[116:119], v[132:135], v[208:211], v[116:119]
	v_mfma_f32_16x16x32_bf16 v[108:111], v[152:155], v[208:211], v[108:111]
	v_mfma_f32_16x16x32_bf16 v[92:95], v[132:135], v[234:237], v[92:95]
	v_mfma_f32_16x16x32_bf16 v[88:91], v[152:155], v[234:237], v[88:91]
	v_mfma_f32_16x16x32_bf16 v[80:83], v[132:135], v[242:245], v[80:83]
	v_mfma_f32_16x16x32_bf16 v[72:75], v[152:155], v[242:245], v[72:75]
	v_mfma_f32_16x16x32_bf16 v[112:115], v[156:159], v[188:191], 0
	v_mfma_f32_16x16x32_bf16 v[104:107], v[164:167], v[188:191], 0
	v_mfma_f32_16x16x32_bf16 v[100:103], v[156:159], v[204:207], 0
	v_mfma_f32_16x16x32_bf16 v[96:99], v[164:167], v[204:207], 0
	v_mfma_f32_16x16x32_bf16 v[84:87], v[156:159], v[230:233], 0
	v_mfma_f32_16x16x32_bf16 v[76:79], v[164:167], v[230:233], 0
	v_mfma_f32_16x16x32_bf16 v[68:71], v[156:159], v[238:241], 0
	v_mfma_f32_16x16x32_bf16 v[64:67], v[164:167], v[238:241], 0
	v_mfma_f32_16x16x32_bf16 v[112:115], v[160:163], v[200:203], v[112:115]
	v_mfma_f32_16x16x32_bf16 v[104:107], v[184:187], v[200:203], v[104:107]
	v_mfma_f32_16x16x32_bf16 v[100:103], v[160:163], v[208:211], v[100:103]
	v_mfma_f32_16x16x32_bf16 v[96:99], v[184:187], v[208:211], v[96:99]
	v_mfma_f32_16x16x32_bf16 v[84:87], v[160:163], v[234:237], v[84:87]
	v_mfma_f32_16x16x32_bf16 v[76:79], v[184:187], v[234:237], v[76:79]
	v_mfma_f32_16x16x32_bf16 v[68:71], v[160:163], v[242:245], v[68:71]
	v_mfma_f32_16x16x32_bf16 v[64:67], v[184:187], v[242:245], v[64:67]
	s_barrier
	s_add_i32 s18, s24, s39
	v_lshl_add_u64 v[212:213], s[34:35], 0, v[144:145]
	s_mov_b32 m0, s18
	ds_read_b128 v[188:191], v198 offset:16384
	ds_read_b128 v[200:203], v198 offset:17408
	ds_read_b128 v[204:207], v198 offset:18432
	ds_read_b128 v[208:211], v198 offset:19456
	ds_read_b128 v[230:233], v198 offset:20480
	ds_read_b128 v[234:237], v198 offset:21504
	ds_read_b128 v[238:241], v198 offset:22528
	ds_read_b128 v[242:245], v198 offset:23552
	global_load_lds_dwordx4 v[212:213], off
	s_add_i32 m0, s18, 0x2000
	s_add_u32 s18, s34, 0x160000
	v_lshl_add_u64 v[246:247], s[34:35], 0, v[140:141]
	s_addc_u32 s19, s35, 0
	s_add_i32 s24, s25, s39
	global_load_lds_dwordx4 v[246:247], off
	v_lshl_add_u64 v[248:249], s[18:19], 0, v[144:145]
	s_mov_b32 m0, s24
	v_lshl_add_u64 v[250:251], s[36:37], 0, v[142:143]
	global_load_lds_dwordx4 v[248:249], off
	v_lshl_add_u64 v[248:249], s[18:19], 0, v[140:141]
	s_add_i32 m0, s24, 0x2000
	s_nop 0
	global_load_lds_dwordx4 v[248:249], off
	v_lshl_add_u64 v[248:249], s[36:37], 0, v[146:147]
	s_mov_b32 m0, s44
	s_nop 0
	global_load_lds_dwordx4 v[248:249], off
	s_mov_b32 m0, s45
	s_nop 0
	global_load_lds_dwordx4 v[250:251], off
	s_waitcnt vmcnt(8)
	s_waitcnt lgkmcnt(0)
	s_barrier
; #define PG8_STAGE(bufoff, gbase, voff) do { _Pragma("unroll") for (int _i = 0; _i < 2; ++_i) \
;         __builtin_amdgcn_global_load_lds((const unsigned*)((const char*)(gbase) + (voff)[_i]), (LAS unsigned*)(lds + (bufoff) + ldsw + _i * 8192), 16, 0, 0); } while (0)
; #define PG8_LDA(dst, b, h) do { _Pragma("unroll") for (int m = 0; m < 4; ++m) _Pragma("unroll") for (int k = 0; k < 2; ++k) dst[m][k] = *(const LAS bf16x8*)(lds + PG8_SA(b, h) + aoff + m * 2048 + k * 1024); } while (0)
; #define PG8_LDB(dst, b, h) do { _Pragma("unroll") for (int n = 0; n < 2; ++n) _Pragma("unroll") for (int k = 0; k < 2; ++k) dst[n][k] = *(const LAS bf16x8*)(lds + PG8_SB(b, h) + boff + n * 2048 + k * 1024); } while (0)
; #define PG8_MMA(ai, bj, At, Bt) do { __builtin_amdgcn_s_setprio(1); _Pragma("unroll") for (int m = 0; m < 4; ++m) _Pragma("unroll") for (int n = 0; n < 2; ++n) _Pragma("unroll") for (int k = 0; k < 2; ++k) \
;         acc[ai][bj][m][n] = __builtin_amdgcn_mfma_f32_16x16x32_bf16(Bt[n][k], At[m][k], acc[ai][bj][m][n], 0, 0, 0); __builtin_amdgcn_s_setprio(0); } while (0)
; #define PG8_WAIT_V(n) asm volatile("s_waitcnt vmcnt(" #n ")" ::: "memory")
; #define PG8_WAIT_L(n) asm volatile("s_waitcnt lgkmcnt(" #n ")" ::: "memory")
; #define PG8_BAR __builtin_amdgcn_s_barrier()
; #define PG8_SCHED __builtin_amdgcn_sched_barrier(0)
; template <class Epi>
; __device__ __forceinline__ void gemm_phase(LAS unsigned char* lds, const Gemm g, const StaticOrder& S, const Epi& E, const int tid) {
;     ...
;             PG8_WAIT_V(8); PG8_WAIT_L(0); PG8_BAR; PG8_MMA(1, 0, At, B0); PG8_MMA(1, 1, At, B1); PG8_BAR; PG8_SCHED;
;             PG8_LDB(B0, 1, 0); PG8_LDB(B1, 1, 1); PG8_SCHED; PG8_LDA(At, 1, 0); PG8_STAGE(PG8_SA(0, 1), a2 + hsA, voffA);
;             PG8_WAIT_V(8); PG8_WAIT_L(0); PG8_BAR; PG8_MMA(0, 0, At, B0); PG8_MMA(0, 1, At, B1); PG8_BAR; PG8_SCHED;
	v_mfma_f32_16x16x32_bf16 v[60:63], v[128:131], v[188:191], 0
	v_mfma_f32_16x16x32_bf16 v[56:59], v[136:139], v[188:191], 0
	v_mfma_f32_16x16x32_bf16 v[44:47], v[128:131], v[204:207], 0
	v_mfma_f32_16x16x32_bf16 v[40:43], v[136:139], v[204:207], 0
	v_mfma_f32_16x16x32_bf16 v[28:31], v[128:131], v[230:233], 0
	v_mfma_f32_16x16x32_bf16 v[24:27], v[136:139], v[230:233], 0
	v_mfma_f32_16x16x32_bf16 v[12:15], v[128:131], v[238:241], 0
	v_mfma_f32_16x16x32_bf16 v[8:11], v[136:139], v[238:241], 0
	v_mfma_f32_16x16x32_bf16 v[60:63], v[132:135], v[200:203], v[60:63]
	v_mfma_f32_16x16x32_bf16 v[56:59], v[152:155], v[200:203], v[56:59]
	v_mfma_f32_16x16x32_bf16 v[44:47], v[132:135], v[208:211], v[44:47]
	v_mfma_f32_16x16x32_bf16 v[40:43], v[152:155], v[208:211], v[40:43]
	v_mfma_f32_16x16x32_bf16 v[28:31], v[132:135], v[234:237], v[28:31]
	v_mfma_f32_16x16x32_bf16 v[24:27], v[152:155], v[234:237], v[24:27]
	v_mfma_f32_16x16x32_bf16 v[12:15], v[132:135], v[242:245], v[12:15]
	v_mfma_f32_16x16x32_bf16 v[8:11], v[152:155], v[242:245], v[8:11]
	v_mfma_f32_16x16x32_bf16 v[52:55], v[156:159], v[188:191], 0
	v_mfma_f32_16x16x32_bf16 v[48:51], v[164:167], v[188:191], 0
	v_mfma_f32_16x16x32_bf16 v[36:39], v[156:159], v[204:207], 0
	v_mfma_f32_16x16x32_bf16 v[32:35], v[164:167], v[204:207], 0
	v_mfma_f32_16x16x32_bf16 v[20:23], v[156:159], v[230:233], 0
	v_mfma_f32_16x16x32_bf16 v[16:19], v[164:167], v[230:233], 0
	v_mfma_f32_16x16x32_bf16 v[4:7], v[156:159], v[238:241], 0
	v_mfma_f32_16x16x32_bf16 v[0:3], v[164:167], v[238:241], 0
	v_mfma_f32_16x16x32_bf16 v[52:55], v[160:163], v[200:203], v[52:55]
	v_mfma_f32_16x16x32_bf16 v[48:51], v[184:187], v[200:203], v[48:51]
	v_mfma_f32_16x16x32_bf16 v[36:39], v[160:163], v[208:211], v[36:39]
	v_mfma_f32_16x16x32_bf16 v[32:35], v[184:187], v[208:211], v[32:35]
	v_mfma_f32_16x16x32_bf16 v[20:23], v[160:163], v[234:237], v[20:23]
	v_mfma_f32_16x16x32_bf16 v[16:19], v[184:187], v[234:237], v[16:19]
	v_mfma_f32_16x16x32_bf16 v[4:7], v[160:163], v[242:245], v[4:7]
	v_mfma_f32_16x16x32_bf16 v[0:3], v[184:187], v[242:245], v[0:3]
	s_barrier
	s_add_i32 s24, 0, 0x18000
	s_add_i32 s25, 0, 0x1c000
	v_add_u32_e32 v152, s24, v193
	v_add_u32_e32 v170, s25, v193
	ds_read_b128 v[128:131], v152
	ds_read_b128 v[132:135], v152 offset:1024
	ds_read_b128 v[136:139], v152 offset:2048
	ds_read_b128 v[152:155], v152 offset:3072
	ds_read_b128 v[156:159], v170
	ds_read_b128 v[160:163], v170 offset:1024
	ds_read_b128 v[164:167], v170 offset:2048
	ds_read_b128 v[184:187], v170 offset:3072
	s_add_u32 s18, s36, 0x160000
	s_addc_u32 s19, s37, 0
	s_mov_b32 m0, s46
	v_lshl_add_u64 v[170:171], s[18:19], 0, v[146:147]
	ds_read_b128 v[188:191], v198 offset:32768
	ds_read_b128 v[200:203], v198 offset:33792
	ds_read_b128 v[204:207], v198 offset:34816
	ds_read_b128 v[208:211], v198 offset:35840
	ds_read_b128 v[230:233], v198 offset:36864
	ds_read_b128 v[234:237], v198 offset:37888
	ds_read_b128 v[238:241], v198 offset:38912
	ds_read_b128 v[242:245], v198 offset:39936
	global_load_lds_dwordx4 v[170:171], off
	v_lshl_add_u64 v[170:171], s[18:19], 0, v[142:143]
	s_mov_b32 m0, s47
	s_nop 0
	global_load_lds_dwordx4 v[170:171], off
	s_waitcnt vmcnt(8)
	s_waitcnt lgkmcnt(0)
	s_barrier
	v_mfma_f32_16x16x32_bf16 v[124:127], v[128:131], v[188:191], v[124:127]
	v_mfma_f32_16x16x32_bf16 v[120:123], v[136:139], v[188:191], v[120:123]
	v_mfma_f32_16x16x32_bf16 v[116:119], v[128:131], v[204:207], v[116:119]
	v_mfma_f32_16x16x32_bf16 v[108:111], v[136:139], v[204:207], v[108:111]
	v_mfma_f32_16x16x32_bf16 v[92:95], v[128:131], v[230:233], v[92:95]
	v_mfma_f32_16x16x32_bf16 v[88:91], v[136:139], v[230:233], v[88:91]
	v_mfma_f32_16x16x32_bf16 v[80:83], v[128:131], v[238:241], v[80:83]
	v_mfma_f32_16x16x32_bf16 v[72:75], v[136:139], v[238:241], v[72:75]
	v_mfma_f32_16x16x32_bf16 v[124:127], v[132:135], v[200:203], v[124:127]
	v_mfma_f32_16x16x32_bf16 v[120:123], v[152:155], v[200:203], v[120:123]
	v_mfma_f32_16x16x32_bf16 v[116:119], v[132:135], v[208:211], v[116:119]
	v_mfma_f32_16x16x32_bf16 v[108:111], v[152:155], v[208:211], v[108:111]
	v_mfma_f32_16x16x32_bf16 v[92:95], v[132:135], v[234:237], v[92:95]
	v_mfma_f32_16x16x32_bf16 v[88:91], v[152:155], v[234:237], v[88:91]
	v_mfma_f32_16x16x32_bf16 v[80:83], v[132:135], v[242:245], v[80:83]
	v_mfma_f32_16x16x32_bf16 v[72:75], v[152:155], v[242:245], v[72:75]
	v_mfma_f32_16x16x32_bf16 v[112:115], v[156:159], v[188:191], v[112:115]
	v_mfma_f32_16x16x32_bf16 v[104:107], v[164:167], v[188:191], v[104:107]
	v_mfma_f32_16x16x32_bf16 v[100:103], v[156:159], v[204:207], v[100:103]
	v_mfma_f32_16x16x32_bf16 v[96:99], v[164:167], v[204:207], v[96:99]
	v_mfma_f32_16x16x32_bf16 v[84:87], v[156:159], v[230:233], v[84:87]
	v_mfma_f32_16x16x32_bf16 v[76:79], v[164:167], v[230:233], v[76:79]
	v_mfma_f32_16x16x32_bf16 v[68:71], v[156:159], v[238:241], v[68:71]
	v_mfma_f32_16x16x32_bf16 v[64:67], v[164:167], v[238:241], v[64:67]
	v_mfma_f32_16x16x32_bf16 v[112:115], v[160:163], v[200:203], v[112:115]
	v_mfma_f32_16x16x32_bf16 v[104:107], v[184:187], v[200:203], v[104:107]
	v_mfma_f32_16x16x32_bf16 v[100:103], v[160:163], v[208:211], v[100:103]
	v_mfma_f32_16x16x32_bf16 v[96:99], v[184:187], v[208:211], v[96:99]
	v_mfma_f32_16x16x32_bf16 v[84:87], v[160:163], v[234:237], v[84:87]
	v_mfma_f32_16x16x32_bf16 v[76:79], v[184:187], v[234:237], v[76:79]
	v_mfma_f32_16x16x32_bf16 v[68:71], v[160:163], v[242:245], v[68:71]
	v_mfma_f32_16x16x32_bf16 v[64:67], v[184:187], v[242:245], v[64:67]
	s_barrier
; #define PG8_STAGE(bufoff, gbase, voff) do { _Pragma("unroll") for (int _i = 0; _i < 2; ++_i) \
;         __builtin_amdgcn_global_load_lds((const unsigned*)((const char*)(gbase) + (voff)[_i]), (LAS unsigned*)(lds + (bufoff) + ldsw + _i * 8192), 16, 0, 0); } while (0)
; #define PG8_LDA(dst, b, h) do { _Pragma("unroll") for (int m = 0; m < 4; ++m) _Pragma("unroll") for (int k = 0; k < 2; ++k) dst[m][k] = *(const LAS bf16x8*)(lds + PG8_SA(b, h) + aoff + m * 2048 + k * 1024); } while (0)
; #define PG8_MMA(ai, bj, At, Bt) do { __builtin_amdgcn_s_setprio(1); _Pragma("unroll") for (int m = 0; m < 4; ++m) _Pragma("unroll") for (int n = 0; n < 2; ++n) _Pragma("unroll") for (int k = 0; k < 2; ++k) \
;         acc[ai][bj][m][n] = __builtin_amdgcn_mfma_f32_16x16x32_bf16(Bt[n][k], At[m][k], acc[ai][bj][m][n], 0, 0, 0); __builtin_amdgcn_s_setprio(0); } while (0)
; #define PG8_WAIT_V(n) asm volatile("s_waitcnt vmcnt(" #n ")" ::: "memory")
; #define PG8_WAIT_L(n) asm volatile("s_waitcnt lgkmcnt(" #n ")" ::: "memory")
; #define PG8_BAR __builtin_amdgcn_s_barrier()
; #define PG8_SCHED __builtin_amdgcn_sched_barrier(0)
; template <class Epi>
; __device__ __forceinline__ void gemm_phase(LAS unsigned char* lds, const Gemm g, const StaticOrder& S, const Epi& E, const int tid) {
;     ...
;             PG8_WAIT_V(8); PG8_WAIT_L(0); PG8_BAR; PG8_MMA(0, 0, At, B0); PG8_MMA(0, 1, At, B1); PG8_BAR; PG8_SCHED;
;             PG8_LDA(At, 1, 1); PG8_STAGE(PG8_SB(1, 0), b3, voffB); PG8_STAGE(PG8_SB(1, 1), b3 + hsB, voffB); PG8_STAGE(PG8_SA(1, 0), a3, voffA);
;             PG8_WAIT_V(8); PG8_WAIT_L(0); PG8_BAR; PG8_MMA(1, 0, At, B0); PG8_MMA(1, 1, At, B1); PG8_BAR; PG8_SCHED;
	s_add_i32 s18, s24, s39
	v_lshl_add_u64 v[170:171], v[212:213], 0, s[28:29]
	s_mov_b32 m0, s18
	ds_read_b128 v[188:191], v198 offset:49152
	ds_read_b128 v[200:203], v198 offset:50176
	ds_read_b128 v[204:207], v198 offset:51200
	ds_read_b128 v[208:211], v198 offset:52224
	ds_read_b128 v[230:233], v198 offset:53248
	ds_read_b128 v[234:237], v198 offset:54272
	ds_read_b128 v[238:241], v198 offset:55296
	ds_read_b128 v[242:245], v198 offset:56320
	global_load_lds_dwordx4 v[170:171], off
	s_add_i32 m0, s18, 0x2000
	s_add_u32 s18, s34, 0x160080
	v_lshl_add_u64 v[170:171], v[246:247], 0, s[28:29]
	s_addc_u32 s19, s35, 0
	s_add_i32 s24, s25, s39
	global_load_lds_dwordx4 v[170:171], off
	v_lshl_add_u64 v[170:171], s[18:19], 0, v[144:145]
	s_mov_b32 m0, s24
	s_nop 0
	global_load_lds_dwordx4 v[170:171], off
	v_lshl_add_u64 v[170:171], s[18:19], 0, v[140:141]
	s_add_i32 m0, s24, 0x2000
	s_nop 0
	global_load_lds_dwordx4 v[170:171], off
	v_lshl_add_u64 v[170:171], v[248:249], 0, s[28:29]
	s_mov_b32 m0, s56
	s_nop 0
	global_load_lds_dwordx4 v[170:171], off
	v_lshl_add_u64 v[170:171], v[250:251], 0, s[28:29]
	s_mov_b32 m0, s57
	s_nop 0
	global_load_lds_dwordx4 v[170:171], off
	s_waitcnt vmcnt(8)
	s_waitcnt lgkmcnt(0)
	s_barrier
	v_mfma_f32_16x16x32_bf16 v[60:63], v[128:131], v[188:191], v[60:63]
	v_mfma_f32_16x16x32_bf16 v[56:59], v[136:139], v[188:191], v[56:59]
	v_mfma_f32_16x16x32_bf16 v[44:47], v[128:131], v[204:207], v[44:47]
	v_mfma_f32_16x16x32_bf16 v[40:43], v[136:139], v[204:207], v[40:43]
	v_mfma_f32_16x16x32_bf16 v[28:31], v[128:131], v[230:233], v[28:31]
	v_mfma_f32_16x16x32_bf16 v[24:27], v[136:139], v[230:233], v[24:27]
	v_mfma_f32_16x16x32_bf16 v[12:15], v[128:131], v[238:241], v[12:15]
	v_mfma_f32_16x16x32_bf16 v[8:11], v[136:139], v[238:241], v[8:11]
	v_mfma_f32_16x16x32_bf16 v[60:63], v[132:135], v[200:203], v[60:63]
	v_mfma_f32_16x16x32_bf16 v[56:59], v[152:155], v[200:203], v[56:59]
	v_mfma_f32_16x16x32_bf16 v[44:47], v[132:135], v[208:211], v[44:47]
	v_mfma_f32_16x16x32_bf16 v[40:43], v[152:155], v[208:211], v[40:43]
	v_mfma_f32_16x16x32_bf16 v[28:31], v[132:135], v[234:237], v[28:31]
	v_mfma_f32_16x16x32_bf16 v[24:27], v[152:155], v[234:237], v[24:27]
	v_mfma_f32_16x16x32_bf16 v[12:15], v[132:135], v[242:245], v[12:15]
	v_mfma_f32_16x16x32_bf16 v[8:11], v[152:155], v[242:245], v[8:11]
	v_mfma_f32_16x16x32_bf16 v[52:55], v[156:159], v[188:191], v[52:55]
	v_mfma_f32_16x16x32_bf16 v[48:51], v[164:167], v[188:191], v[48:51]
	v_mfma_f32_16x16x32_bf16 v[36:39], v[156:159], v[204:207], v[36:39]
	v_mfma_f32_16x16x32_bf16 v[32:35], v[164:167], v[204:207], v[32:35]
	v_mfma_f32_16x16x32_bf16 v[20:23], v[156:159], v[230:233], v[20:23]
	v_mfma_f32_16x16x32_bf16 v[16:19], v[164:167], v[230:233], v[16:19]
	v_mfma_f32_16x16x32_bf16 v[4:7], v[156:159], v[238:241], v[4:7]
	v_mfma_f32_16x16x32_bf16 v[0:3], v[164:167], v[238:241], v[0:3]
	v_mfma_f32_16x16x32_bf16 v[52:55], v[160:163], v[200:203], v[52:55]
	v_mfma_f32_16x16x32_bf16 v[48:51], v[184:187], v[200:203], v[48:51]
	v_mfma_f32_16x16x32_bf16 v[36:39], v[160:163], v[208:211], v[36:39]
	v_mfma_f32_16x16x32_bf16 v[32:35], v[184:187], v[208:211], v[32:35]
	v_mfma_f32_16x16x32_bf16 v[20:23], v[160:163], v[234:237], v[20:23]
	v_mfma_f32_16x16x32_bf16 v[16:19], v[184:187], v[234:237], v[16:19]
	v_mfma_f32_16x16x32_bf16 v[4:7], v[160:163], v[242:245], v[4:7]
	v_mfma_f32_16x16x32_bf16 v[0:3], v[184:187], v[242:245], v[0:3]
	s_barrier
	s_add_i32 s69, s69, 2
	s_add_u32 s42, s42, 0x100
	s_addc_u32 s43, s43, 0
	s_cmpk_gt_u32 s69, 0x55
	s_mov_b64 s[18:19], s[0:1]

; #define PG8_STAGE(bufoff, gbase, voff) do { _Pragma("unroll") for (int _i = 0; _i < 2; ++_i) \
;         __builtin_amdgcn_global_load_lds((const unsigned*)((const char*)(gbase) + (voff)[_i]), (LAS unsigned*)(lds + (bufoff) + ldsw + _i * 8192), 16, 0, 0); } while (0)
; #define PG8_LDA(dst, b, h) do { _Pragma("unroll") for (int m = 0; m < 4; ++m) _Pragma("unroll") for (int k = 0; k < 2; ++k) dst[m][k] = *(const LAS bf16x8*)(lds + PG8_SA(b, h) + aoff + m * 2048 + k * 1024); } while (0)
; #define PG8_LDB(dst, b, h) do { _Pragma("unroll") for (int n = 0; n < 2; ++n) _Pragma("unroll") for (int k = 0; k < 2; ++k) dst[n][k] = *(const LAS bf16x8*)(lds + PG8_SB(b, h) + boff + n * 2048 + k * 1024); } while (0)
; #define PG8_MMA(ai, bj, At, Bt) do { __builtin_amdgcn_s_setprio(1); _Pragma("unroll") for (int m = 0; m < 4; ++m) _Pragma("unroll") for (int n = 0; n < 2; ++n) _Pragma("unroll") for (int k = 0; k < 2; ++k) \
;         acc[ai][bj][m][n] = __builtin_amdgcn_mfma_f32_16x16x32_bf16(Bt[n][k], At[m][k], acc[ai][bj][m][n], 0, 0, 0); __builtin_amdgcn_s_setprio(0); } while (0)
; #define PG8_WAIT_V(n) asm volatile("s_waitcnt vmcnt(" #n ")" ::: "memory")
; #define PG8_BAR __builtin_amdgcn_s_barrier()
; template <class Epi>
; __device__ __forceinline__ void gemm_phase(LAS unsigned char* lds, const Gemm g, const StaticOrder& S, const Epi& E, const int tid) {
;     ...
;         const bool has_next = S.next(ui + 1, nxt);
;         const char* nA = has_next ? PG8_APTR(nxt) : cA; const char* nB = has_next ? PG8_BPTR(nxt) : cB;
;         for (int t = 0; t < nt; t += 2) {
;             const bool last = (t == nt - 2);
;             const char* a1 = cA + (size_t)(t + 1) * kstep;
;             const char* a2 = last ? nA : cA + (size_t)(t + 2) * kstep; const char* b2 = last ? nB : cB + (size_t)(t + 2) * kstep;
;             const char* a3 = a2 + kstep; const char* b3 = b2 + kstep;
;             PG8_LDB(B0, 0, 0); PG8_LDB(B1, 0, 1); PG8_SCHED; PG8_LDA(At, 0, 0); PG8_STAGE(PG8_SA(1, 1), a1 + hsA, voffA);
;             PG8_WAIT_V(8); PG8_WAIT_L(0); PG8_BAR; PG8_MMA(0, 0, At, B0); PG8_MMA(0, 1, At, B1); PG8_BAR; PG8_SCHED;
;             PG8_LDA(At, 0, 1); PG8_STAGE(PG8_SB(0, 0), b2, voffB); PG8_STAGE(PG8_SB(0, 1), b2 + hsB, voffB); PG8_STAGE(PG8_SA(0, 0), a2, voffA);
;             PG8_WAIT_V(8); PG8_WAIT_L(0); PG8_BAR; PG8_MMA(1, 0, At, B0); PG8_MMA(1, 1, At, B1); PG8_BAR; PG8_SCHED;
.LBB0_353:
	s_ashr_i32 s49, s48, 31
	s_lshl_b64 s[10:11], s[48:49], 20
	s_add_u32 s52, s38, s10
	s_addc_u32 s53, s39, s11
	s_and_b64 s[10:11], s[40:41], exec
	s_cselect_b32 s10, s53, s1
	s_cselect_b32 s11, s52, s0
	s_ashr_i32 s47, s46, 31
	s_lshl_b64 s[12:13], s[46:47], 20
	v_readlane_b32 s16, v255, 32
	s_add_u32 s12, s16, s12
	v_readlane_b32 s16, v255, 33
	s_addc_u32 s13, s16, s13
	s_and_b64 s[36:37], s[40:41], exec
	s_cselect_b32 s47, s13, s43
	s_cselect_b32 s49, s12, s42
	s_add_u32 s36, s0, 0x80080
	s_addc_u32 s37, s1, 0
	s_add_u32 s69, s42, 0x100
	s_addc_u32 vcc_lo, s43, 0
	s_mov_b32 vcc_hi, -2
	s_add_u32 s0, s36, 0xfff80080
	s_addc_u32 s1, s37, -1
	s_add_i32 s24, 0, 0x10000
	s_cmp_eq_u32 vcc_hi, 28
	s_cselect_b32 s43, s10, s1
	s_cselect_b32 s42, s11, s0
	v_add_u32_e32 v143, s24, v163
	s_cselect_b32 s1, s47, vcc_lo
	s_cselect_b32 s0, s49, s69
	s_add_i32 s55, 0, 0x14000
	ds_read_b128 v[144:147], v143
	ds_read_b128 v[148:151], v143 offset:1024
	ds_read_b128 v[152:155], v143 offset:2048
	ds_read_b128 v[156:159], v143 offset:3072
	v_add_u32_e32 v143, s55, v163
	ds_read_b128 v[184:187], v143
	ds_read_b128 v[188:191], v143 offset:1024
	ds_read_b128 v[192:195], v143 offset:2048
	ds_read_b128 v[196:199], v143 offset:3072
	v_lshl_add_u64 v[160:161], s[36:37], 0, v[138:139]
	s_add_i32 m0, s58, 0xc000
	ds_read_b128 v[200:203], v165
	ds_read_b128 v[204:207], v165 offset:1024
	ds_read_b128 v[208:211], v165 offset:2048
	ds_read_b128 v[232:235], v165 offset:3072
	ds_read_b128 v[236:239], v165 offset:4096
	ds_read_b128 v[240:243], v165 offset:5120
	ds_read_b128 v[244:247], v165 offset:6144
	ds_read_b128 v[248:251], v165 offset:7168
	global_load_lds_dwordx4 v[160:161], off
	v_lshl_add_u64 v[160:161], s[36:37], 0, v[140:141]
	s_add_i32 m0, s58, 0xe000
	s_nop 0
	global_load_lds_dwordx4 v[160:161], off
	s_waitcnt vmcnt(8)
	s_waitcnt lgkmcnt(0)
	s_barrier
	v_mfma_f32_16x16x32_bf16 v[124:127], v[144:147], v[200:203], 0
	v_mfma_f32_16x16x32_bf16 v[120:123], v[152:155], v[200:203], 0
	v_mfma_f32_16x16x32_bf16 v[108:111], v[144:147], v[208:211], 0
	v_mfma_f32_16x16x32_bf16 v[104:107], v[152:155], v[208:211], 0
	v_mfma_f32_16x16x32_bf16 v[92:95], v[144:147], v[236:239], 0
	v_mfma_f32_16x16x32_bf16 v[88:91], v[152:155], v[236:239], 0
	v_mfma_f32_16x16x32_bf16 v[76:79], v[144:147], v[244:247], 0
	v_mfma_f32_16x16x32_bf16 v[72:75], v[152:155], v[244:247], 0
	v_mfma_f32_16x16x32_bf16 v[124:127], v[148:151], v[204:207], v[124:127]
	v_mfma_f32_16x16x32_bf16 v[120:123], v[156:159], v[204:207], v[120:123]
	v_mfma_f32_16x16x32_bf16 v[108:111], v[148:151], v[232:235], v[108:111]
	v_mfma_f32_16x16x32_bf16 v[104:107], v[156:159], v[232:235], v[104:107]
	v_mfma_f32_16x16x32_bf16 v[92:95], v[148:151], v[240:243], v[92:95]
	v_mfma_f32_16x16x32_bf16 v[88:91], v[156:159], v[240:243], v[88:91]
	v_mfma_f32_16x16x32_bf16 v[76:79], v[148:151], v[248:251], v[76:79]
	v_mfma_f32_16x16x32_bf16 v[72:75], v[156:159], v[248:251], v[72:75]
	v_mfma_f32_16x16x32_bf16 v[116:119], v[184:187], v[200:203], 0
	v_mfma_f32_16x16x32_bf16 v[112:115], v[192:195], v[200:203], 0
	v_mfma_f32_16x16x32_bf16 v[100:103], v[184:187], v[208:211], 0
	v_mfma_f32_16x16x32_bf16 v[96:99], v[192:195], v[208:211], 0
	v_mfma_f32_16x16x32_bf16 v[84:87], v[184:187], v[236:239], 0
	v_mfma_f32_16x16x32_bf16 v[80:83], v[192:195], v[236:239], 0
	v_mfma_f32_16x16x32_bf16 v[68:71], v[184:187], v[244:247], 0
	v_mfma_f32_16x16x32_bf16 v[64:67], v[192:195], v[244:247], 0
	v_mfma_f32_16x16x32_bf16 v[116:119], v[188:191], v[204:207], v[116:119]
	v_mfma_f32_16x16x32_bf16 v[112:115], v[196:199], v[204:207], v[112:115]
	v_mfma_f32_16x16x32_bf16 v[100:103], v[188:191], v[232:235], v[100:103]
	v_mfma_f32_16x16x32_bf16 v[96:99], v[196:199], v[232:235], v[96:99]
	v_mfma_f32_16x16x32_bf16 v[84:87], v[188:191], v[240:243], v[84:87]
	v_mfma_f32_16x16x32_bf16 v[80:83], v[196:199], v[240:243], v[80:83]
	v_mfma_f32_16x16x32_bf16 v[68:71], v[188:191], v[248:251], v[68:71]
	v_mfma_f32_16x16x32_bf16 v[64:67], v[196:199], v[248:251], v[64:67]
	s_barrier
	s_add_i32 s24, s24, s57
	v_lshl_add_u64 v[160:161], s[0:1], 0, v[132:133]
	s_mov_b32 m0, s24
	ds_read_b128 v[200:203], v165 offset:16384
	ds_read_b128 v[204:207], v165 offset:17408
	ds_read_b128 v[208:211], v165 offset:18432
	ds_read_b128 v[232:235], v165 offset:19456
	ds_read_b128 v[236:239], v165 offset:20480
	ds_read_b128 v[240:243], v165 offset:21504
	ds_read_b128 v[244:247], v165 offset:22528
	ds_read_b128 v[248:251], v165 offset:23552
	global_load_lds_dwordx4 v[160:161], off
	s_add_i32 m0, s24, 0x2000
	s_add_u32 s24, s0, 0x80000
	v_lshl_add_u64 v[166:167], s[0:1], 0, v[128:129]
	s_addc_u32 s25, s1, 0
	s_add_i32 s55, s55, s57
	global_load_lds_dwordx4 v[166:167], off
	v_lshl_add_u64 v[170:171], s[24:25], 0, v[132:133]
	s_mov_b32 m0, s55
	v_lshl_add_u64 v[212:213], s[42:43], 0, v[130:131]
	global_load_lds_dwordx4 v[170:171], off
	v_lshl_add_u64 v[170:171], s[24:25], 0, v[128:129]
	s_add_i32 m0, s55, 0x2000
	s_nop 0
	global_load_lds_dwordx4 v[170:171], off
	v_lshl_add_u64 v[170:171], s[42:43], 0, v[134:135]
	s_mov_b32 m0, s58
	s_nop 0
	global_load_lds_dwordx4 v[170:171], off
	s_mov_b32 m0, s59
	s_nop 0
	global_load_lds_dwordx4 v[212:213], off
	s_waitcnt vmcnt(8)
	s_waitcnt lgkmcnt(0)
	s_barrier
; #define PG8_STAGE(bufoff, gbase, voff) do { _Pragma("unroll") for (int _i = 0; _i < 2; ++_i) \
;         __builtin_amdgcn_global_load_lds((const unsigned*)((const char*)(gbase) + (voff)[_i]), (LAS unsigned*)(lds + (bufoff) + ldsw + _i * 8192), 16, 0, 0); } while (0)
; #define PG8_LDA(dst, b, h) do { _Pragma("unroll") for (int m = 0; m < 4; ++m) _Pragma("unroll") for (int k = 0; k < 2; ++k) dst[m][k] = *(const LAS bf16x8*)(lds + PG8_SA(b, h) + aoff + m * 2048 + k * 1024); } while (0)
; #define PG8_LDB(dst, b, h) do { _Pragma("unroll") for (int n = 0; n < 2; ++n) _Pragma("unroll") for (int k = 0; k < 2; ++k) dst[n][k] = *(const LAS bf16x8*)(lds + PG8_SB(b, h) + boff + n * 2048 + k * 1024); } while (0)
; #define PG8_MMA(ai, bj, At, Bt) do { __builtin_amdgcn_s_setprio(1); _Pragma("unroll") for (int m = 0; m < 4; ++m) _Pragma("unroll") for (int n = 0; n < 2; ++n) _Pragma("unroll") for (int k = 0; k < 2; ++k) \
;         acc[ai][bj][m][n] = __builtin_amdgcn_mfma_f32_16x16x32_bf16(Bt[n][k], At[m][k], acc[ai][bj][m][n], 0, 0, 0); __builtin_amdgcn_s_setprio(0); } while (0)
; #define PG8_WAIT_V(n) asm volatile("s_waitcnt vmcnt(" #n ")" ::: "memory")
; #define PG8_WAIT_L(n) asm volatile("s_waitcnt lgkmcnt(" #n ")" ::: "memory")
; #define PG8_BAR __builtin_amdgcn_s_barrier()
; #define PG8_SCHED __builtin_amdgcn_sched_barrier(0)
; template <class Epi>
; __device__ __forceinline__ void gemm_phase(LAS unsigned char* lds, const Gemm g, const StaticOrder& S, const Epi& E, const int tid) {
;     ...
;             PG8_WAIT_V(8); PG8_WAIT_L(0); PG8_BAR; PG8_MMA(1, 0, At, B0); PG8_MMA(1, 1, At, B1); PG8_BAR; PG8_SCHED;
;             PG8_LDB(B0, 1, 0); PG8_LDB(B1, 1, 1); PG8_SCHED; PG8_LDA(At, 1, 0); PG8_STAGE(PG8_SA(0, 1), a2 + hsA, voffA);
;             PG8_WAIT_V(8); PG8_WAIT_L(0); PG8_BAR; PG8_MMA(0, 0, At, B0); PG8_MMA(0, 1, At, B1); PG8_BAR; PG8_SCHED;
	v_mfma_f32_16x16x32_bf16 v[60:63], v[144:147], v[200:203], 0
	v_mfma_f32_16x16x32_bf16 v[56:59], v[152:155], v[200:203], 0
	v_mfma_f32_16x16x32_bf16 v[44:47], v[144:147], v[208:211], 0
	v_mfma_f32_16x16x32_bf16 v[40:43], v[152:155], v[208:211], 0
	v_mfma_f32_16x16x32_bf16 v[28:31], v[144:147], v[236:239], 0
	v_mfma_f32_16x16x32_bf16 v[24:27], v[152:155], v[236:239], 0
	v_mfma_f32_16x16x32_bf16 v[12:15], v[144:147], v[244:247], 0
	v_mfma_f32_16x16x32_bf16 v[8:11], v[152:155], v[244:247], 0
	v_mfma_f32_16x16x32_bf16 v[60:63], v[148:151], v[204:207], v[60:63]
	v_mfma_f32_16x16x32_bf16 v[56:59], v[156:159], v[204:207], v[56:59]
	v_mfma_f32_16x16x32_bf16 v[44:47], v[148:151], v[232:235], v[44:47]
	v_mfma_f32_16x16x32_bf16 v[40:43], v[156:159], v[232:235], v[40:43]
	v_mfma_f32_16x16x32_bf16 v[28:31], v[148:151], v[240:243], v[28:31]
	v_mfma_f32_16x16x32_bf16 v[24:27], v[156:159], v[240:243], v[24:27]
	v_mfma_f32_16x16x32_bf16 v[12:15], v[148:151], v[248:251], v[12:15]
	v_mfma_f32_16x16x32_bf16 v[8:11], v[156:159], v[248:251], v[8:11]
	v_mfma_f32_16x16x32_bf16 v[52:55], v[184:187], v[200:203], 0
	v_mfma_f32_16x16x32_bf16 v[48:51], v[192:195], v[200:203], 0
	v_mfma_f32_16x16x32_bf16 v[36:39], v[184:187], v[208:211], 0
	v_mfma_f32_16x16x32_bf16 v[32:35], v[192:195], v[208:211], 0
	v_mfma_f32_16x16x32_bf16 v[20:23], v[184:187], v[236:239], 0
	v_mfma_f32_16x16x32_bf16 v[16:19], v[192:195], v[236:239], 0
	v_mfma_f32_16x16x32_bf16 v[4:7], v[184:187], v[244:247], 0
	v_mfma_f32_16x16x32_bf16 v[0:3], v[192:195], v[244:247], 0
	v_mfma_f32_16x16x32_bf16 v[52:55], v[188:191], v[204:207], v[52:55]
	v_mfma_f32_16x16x32_bf16 v[48:51], v[196:199], v[204:207], v[48:51]
	v_mfma_f32_16x16x32_bf16 v[36:39], v[188:191], v[232:235], v[36:39]
	v_mfma_f32_16x16x32_bf16 v[32:35], v[196:199], v[232:235], v[32:35]
	v_mfma_f32_16x16x32_bf16 v[20:23], v[188:191], v[240:243], v[20:23]
	v_mfma_f32_16x16x32_bf16 v[16:19], v[196:199], v[240:243], v[16:19]
	v_mfma_f32_16x16x32_bf16 v[4:7], v[188:191], v[248:251], v[4:7]
	v_mfma_f32_16x16x32_bf16 v[0:3], v[196:199], v[248:251], v[0:3]
	s_barrier
	s_add_i32 s55, 0, 0x18000
	v_add_u32_e32 v143, s55, v163
	s_add_i32 s67, 0, 0x1c000
	ds_read_b128 v[144:147], v143
	ds_read_b128 v[148:151], v143 offset:1024
	ds_read_b128 v[152:155], v143 offset:2048
	ds_read_b128 v[156:159], v143 offset:3072
	v_add_u32_e32 v143, s67, v163
	ds_read_b128 v[184:187], v143
	ds_read_b128 v[188:191], v143 offset:1024
	ds_read_b128 v[192:195], v143 offset:2048
	ds_read_b128 v[196:199], v143 offset:3072
	s_add_u32 s24, s42, 0x80000
	s_addc_u32 s25, s43, 0
	s_mov_b32 m0, s27
	v_lshl_add_u64 v[172:173], s[24:25], 0, v[134:135]
	ds_read_b128 v[200:203], v165 offset:32768
	ds_read_b128 v[204:207], v165 offset:33792
	ds_read_b128 v[208:211], v165 offset:34816
	ds_read_b128 v[232:235], v165 offset:35840
	ds_read_b128 v[236:239], v165 offset:36864
	ds_read_b128 v[240:243], v165 offset:37888
	ds_read_b128 v[244:247], v165 offset:38912
	ds_read_b128 v[248:251], v165 offset:39936
	global_load_lds_dwordx4 v[172:173], off
	v_lshl_add_u64 v[172:173], s[24:25], 0, v[130:131]
	s_mov_b32 m0, s96
	s_nop 0
	global_load_lds_dwordx4 v[172:173], off
	s_waitcnt vmcnt(8)
	s_waitcnt lgkmcnt(0)
	s_barrier
	v_mfma_f32_16x16x32_bf16 v[124:127], v[144:147], v[200:203], v[124:127]
	v_mfma_f32_16x16x32_bf16 v[120:123], v[152:155], v[200:203], v[120:123]
	v_mfma_f32_16x16x32_bf16 v[108:111], v[144:147], v[208:211], v[108:111]
	v_mfma_f32_16x16x32_bf16 v[104:107], v[152:155], v[208:211], v[104:107]
	v_mfma_f32_16x16x32_bf16 v[92:95], v[144:147], v[236:239], v[92:95]
	v_mfma_f32_16x16x32_bf16 v[88:91], v[152:155], v[236:239], v[88:91]
	v_mfma_f32_16x16x32_bf16 v[76:79], v[144:147], v[244:247], v[76:79]
	v_mfma_f32_16x16x32_bf16 v[72:75], v[152:155], v[244:247], v[72:75]
	v_mfma_f32_16x16x32_bf16 v[124:127], v[148:151], v[204:207], v[124:127]
	v_mfma_f32_16x16x32_bf16 v[120:123], v[156:159], v[204:207], v[120:123]
	v_mfma_f32_16x16x32_bf16 v[108:111], v[148:151], v[232:235], v[108:111]
	v_mfma_f32_16x16x32_bf16 v[104:107], v[156:159], v[232:235], v[104:107]
	v_mfma_f32_16x16x32_bf16 v[92:95], v[148:151], v[240:243], v[92:95]
	v_mfma_f32_16x16x32_bf16 v[88:91], v[156:159], v[240:243], v[88:91]
	v_mfma_f32_16x16x32_bf16 v[76:79], v[148:151], v[248:251], v[76:79]
	v_mfma_f32_16x16x32_bf16 v[72:75], v[156:159], v[248:251], v[72:75]
	v_mfma_f32_16x16x32_bf16 v[116:119], v[184:187], v[200:203], v[116:119]
	v_mfma_f32_16x16x32_bf16 v[112:115], v[192:195], v[200:203], v[112:115]
	v_mfma_f32_16x16x32_bf16 v[100:103], v[184:187], v[208:211], v[100:103]
	v_mfma_f32_16x16x32_bf16 v[96:99], v[192:195], v[208:211], v[96:99]
	v_mfma_f32_16x16x32_bf16 v[84:87], v[184:187], v[236:239], v[84:87]
	v_mfma_f32_16x16x32_bf16 v[80:83], v[192:195], v[236:239], v[80:83]
	v_mfma_f32_16x16x32_bf16 v[68:71], v[184:187], v[244:247], v[68:71]
	v_mfma_f32_16x16x32_bf16 v[64:67], v[192:195], v[244:247], v[64:67]
	v_mfma_f32_16x16x32_bf16 v[116:119], v[188:191], v[204:207], v[116:119]
	v_mfma_f32_16x16x32_bf16 v[112:115], v[196:199], v[204:207], v[112:115]
	v_mfma_f32_16x16x32_bf16 v[100:103], v[188:191], v[232:235], v[100:103]
	v_mfma_f32_16x16x32_bf16 v[96:99], v[196:199], v[232:235], v[96:99]
	v_mfma_f32_16x16x32_bf16 v[84:87], v[188:191], v[240:243], v[84:87]
	v_mfma_f32_16x16x32_bf16 v[80:83], v[196:199], v[240:243], v[80:83]
	v_mfma_f32_16x16x32_bf16 v[68:71], v[188:191], v[248:251], v[68:71]
	v_mfma_f32_16x16x32_bf16 v[64:67], v[196:199], v[248:251], v[64:67]
	s_barrier
; #define PG8_STAGE(bufoff, gbase, voff) do { _Pragma("unroll") for (int _i = 0; _i < 2; ++_i) \
;         __builtin_amdgcn_global_load_lds((const unsigned*)((const char*)(gbase) + (voff)[_i]), (LAS unsigned*)(lds + (bufoff) + ldsw + _i * 8192), 16, 0, 0); } while (0)
; #define PG8_LDA(dst, b, h) do { _Pragma("unroll") for (int m = 0; m < 4; ++m) _Pragma("unroll") for (int k = 0; k < 2; ++k) dst[m][k] = *(const LAS bf16x8*)(lds + PG8_SA(b, h) + aoff + m * 2048 + k * 1024); } while (0)
; #define PG8_MMA(ai, bj, At, Bt) do { __builtin_amdgcn_s_setprio(1); _Pragma("unroll") for (int m = 0; m < 4; ++m) _Pragma("unroll") for (int n = 0; n < 2; ++n) _Pragma("unroll") for (int k = 0; k < 2; ++k) \
;         acc[ai][bj][m][n] = __builtin_amdgcn_mfma_f32_16x16x32_bf16(Bt[n][k], At[m][k], acc[ai][bj][m][n], 0, 0, 0); __builtin_amdgcn_s_setprio(0); } while (0)
; #define PG8_WAIT_V(n) asm volatile("s_waitcnt vmcnt(" #n ")" ::: "memory")
; #define PG8_WAIT_L(n) asm volatile("s_waitcnt lgkmcnt(" #n ")" ::: "memory")
; #define PG8_BAR __builtin_amdgcn_s_barrier()
; #define PG8_SCHED __builtin_amdgcn_sched_barrier(0)
; template <class Epi>
; __device__ __forceinline__ void gemm_phase(LAS unsigned char* lds, const Gemm g, const StaticOrder& S, const Epi& E, const int tid) {
;     ...
;             PG8_WAIT_V(8); PG8_WAIT_L(0); PG8_BAR; PG8_MMA(0, 0, At, B0); PG8_MMA(0, 1, At, B1); PG8_BAR; PG8_SCHED;
;             PG8_LDA(At, 1, 1); PG8_STAGE(PG8_SB(1, 0), b3, voffB); PG8_STAGE(PG8_SB(1, 1), b3 + hsB, voffB); PG8_STAGE(PG8_SA(1, 0), a3, voffA);
;             PG8_WAIT_V(8); PG8_WAIT_L(0); PG8_BAR; PG8_MMA(1, 0, At, B0); PG8_MMA(1, 1, At, B1); PG8_BAR; PG8_SCHED;
	s_add_i32 s24, s55, s57
	v_lshl_add_u64 v[160:161], v[160:161], 0, s[28:29]
	s_mov_b32 m0, s24
	ds_read_b128 v[200:203], v165 offset:49152
	ds_read_b128 v[204:207], v165 offset:50176
	ds_read_b128 v[208:211], v165 offset:51200
	ds_read_b128 v[232:235], v165 offset:52224
	ds_read_b128 v[236:239], v165 offset:53248
	ds_read_b128 v[240:243], v165 offset:54272
	ds_read_b128 v[244:247], v165 offset:55296
	ds_read_b128 v[248:251], v165 offset:56320
	global_load_lds_dwordx4 v[160:161], off
	s_add_i32 m0, s24, 0x2000
	s_add_u32 s0, s0, 0x80080
	v_lshl_add_u64 v[160:161], v[166:167], 0, s[28:29]
	s_addc_u32 s1, s1, 0
	s_add_i32 s24, s67, s57
	global_load_lds_dwordx4 v[160:161], off
	v_lshl_add_u64 v[160:161], s[0:1], 0, v[132:133]
	s_mov_b32 m0, s24
	s_nop 0
	global_load_lds_dwordx4 v[160:161], off
	v_lshl_add_u64 v[160:161], s[0:1], 0, v[128:129]
	s_add_i32 m0, s24, 0x2000
	s_nop 0
	global_load_lds_dwordx4 v[160:161], off
	v_lshl_add_u64 v[160:161], v[170:171], 0, s[28:29]
	s_mov_b32 m0, s6
	s_nop 0
	global_load_lds_dwordx4 v[160:161], off
	v_lshl_add_u64 v[160:161], v[212:213], 0, s[28:29]
	s_mov_b32 m0, s7
	s_nop 0
	global_load_lds_dwordx4 v[160:161], off
	s_waitcnt vmcnt(8)
	s_waitcnt lgkmcnt(0)
	s_barrier
	v_mfma_f32_16x16x32_bf16 v[60:63], v[144:147], v[200:203], v[60:63]
	v_mfma_f32_16x16x32_bf16 v[56:59], v[152:155], v[200:203], v[56:59]
	v_mfma_f32_16x16x32_bf16 v[44:47], v[144:147], v[208:211], v[44:47]
	v_mfma_f32_16x16x32_bf16 v[40:43], v[152:155], v[208:211], v[40:43]
	v_mfma_f32_16x16x32_bf16 v[28:31], v[144:147], v[236:239], v[28:31]
	v_mfma_f32_16x16x32_bf16 v[24:27], v[152:155], v[236:239], v[24:27]
	v_mfma_f32_16x16x32_bf16 v[12:15], v[144:147], v[244:247], v[12:15]
	v_mfma_f32_16x16x32_bf16 v[8:11], v[152:155], v[244:247], v[8:11]
	v_mfma_f32_16x16x32_bf16 v[60:63], v[148:151], v[204:207], v[60:63]
	v_mfma_f32_16x16x32_bf16 v[56:59], v[156:159], v[204:207], v[56:59]
	v_mfma_f32_16x16x32_bf16 v[44:47], v[148:151], v[232:235], v[44:47]
	v_mfma_f32_16x16x32_bf16 v[40:43], v[156:159], v[232:235], v[40:43]
	v_mfma_f32_16x16x32_bf16 v[28:31], v[148:151], v[240:243], v[28:31]
	v_mfma_f32_16x16x32_bf16 v[24:27], v[156:159], v[240:243], v[24:27]
	v_mfma_f32_16x16x32_bf16 v[12:15], v[148:151], v[248:251], v[12:15]
	v_mfma_f32_16x16x32_bf16 v[8:11], v[156:159], v[248:251], v[8:11]
	v_mfma_f32_16x16x32_bf16 v[52:55], v[184:187], v[200:203], v[52:55]
	v_mfma_f32_16x16x32_bf16 v[48:51], v[192:195], v[200:203], v[48:51]
	v_mfma_f32_16x16x32_bf16 v[36:39], v[184:187], v[208:211], v[36:39]
	v_mfma_f32_16x16x32_bf16 v[32:35], v[192:195], v[208:211], v[32:35]
	v_mfma_f32_16x16x32_bf16 v[20:23], v[184:187], v[236:239], v[20:23]
	v_mfma_f32_16x16x32_bf16 v[16:19], v[192:195], v[236:239], v[16:19]
	v_mfma_f32_16x16x32_bf16 v[4:7], v[184:187], v[244:247], v[4:7]
	v_mfma_f32_16x16x32_bf16 v[0:3], v[192:195], v[244:247], v[0:3]
	v_mfma_f32_16x16x32_bf16 v[52:55], v[188:191], v[204:207], v[52:55]
	v_mfma_f32_16x16x32_bf16 v[48:51], v[196:199], v[204:207], v[48:51]
	v_mfma_f32_16x16x32_bf16 v[36:39], v[188:191], v[232:235], v[36:39]
	v_mfma_f32_16x16x32_bf16 v[32:35], v[196:199], v[232:235], v[32:35]
	v_mfma_f32_16x16x32_bf16 v[20:23], v[188:191], v[240:243], v[20:23]
	v_mfma_f32_16x16x32_bf16 v[16:19], v[196:199], v[240:243], v[16:19]
	v_mfma_f32_16x16x32_bf16 v[4:7], v[188:191], v[248:251], v[4:7]
	v_mfma_f32_16x16x32_bf16 v[0:3], v[196:199], v[248:251], v[0:3]
	s_barrier
	s_add_i32 vcc_hi, vcc_hi, 2
	s_add_u32 s36, s36, 0x100
	s_addc_u32 s37, s37, 0
	s_add_u32 s69, s69, 0x100
	s_addc_u32 vcc_lo, vcc_lo, 0
	s_cmp_gt_u32 vcc_hi, 29

; #define PG8_STAGE(bufoff, gbase, voff) do { _Pragma("unroll") for (int _i = 0; _i < 2; ++_i) \
;         __builtin_amdgcn_global_load_lds((const unsigned*)((const char*)(gbase) + (voff)[_i]), (LAS unsigned*)(lds + (bufoff) + ldsw + _i * 8192), 16, 0, 0); } while (0)
; #define PG8_LDA(dst, b, h) do { _Pragma("unroll") for (int m = 0; m < 4; ++m) _Pragma("unroll") for (int k = 0; k < 2; ++k) dst[m][k] = *(const LAS bf16x8*)(lds + PG8_SA(b, h) + aoff + m * 2048 + k * 1024); } while (0)
; #define PG8_LDB(dst, b, h) do { _Pragma("unroll") for (int n = 0; n < 2; ++n) _Pragma("unroll") for (int k = 0; k < 2; ++k) dst[n][k] = *(const LAS bf16x8*)(lds + PG8_SB(b, h) + boff + n * 2048 + k * 1024); } while (0)
; #define PG8_MMA(ai, bj, At, Bt) do { __builtin_amdgcn_s_setprio(1); _Pragma("unroll") for (int m = 0; m < 4; ++m) _Pragma("unroll") for (int n = 0; n < 2; ++n) _Pragma("unroll") for (int k = 0; k < 2; ++k) \
;         acc[ai][bj][m][n] = __builtin_amdgcn_mfma_f32_16x16x32_bf16(Bt[n][k], At[m][k], acc[ai][bj][m][n], 0, 0, 0); __builtin_amdgcn_s_setprio(0); } while (0)
; #define PG8_WAIT_V(n) asm volatile("s_waitcnt vmcnt(" #n ")" ::: "memory")
; #define PG8_BAR __builtin_amdgcn_s_barrier()
; template <class Epi>
; __device__ __forceinline__ void gemm_phase(LAS unsigned char* lds, const Gemm g, const StaticOrder& S, const Epi& E, const int tid) {
;     ...
;         const bool has_next = S.next(ui + 1, nxt);
;         const char* nA = has_next ? PG8_APTR(nxt) : cA; const char* nB = has_next ? PG8_BPTR(nxt) : cB;
;         for (int t = 0; t < nt; t += 2) {
;             const bool last = (t == nt - 2);
;             const char* a1 = cA + (size_t)(t + 1) * kstep;
;             const char* a2 = last ? nA : cA + (size_t)(t + 2) * kstep; const char* b2 = last ? nB : cB + (size_t)(t + 2) * kstep;
;             const char* a3 = a2 + kstep; const char* b3 = b2 + kstep;
;             PG8_LDB(B0, 0, 0); PG8_LDB(B1, 0, 1); PG8_SCHED; PG8_LDA(At, 0, 0); PG8_STAGE(PG8_SA(1, 1), a1 + hsA, voffA);
;             PG8_WAIT_V(8); PG8_WAIT_L(0); PG8_BAR; PG8_MMA(0, 0, At, B0); PG8_MMA(0, 1, At, B1); PG8_BAR; PG8_SCHED;
;             PG8_LDA(At, 0, 1); PG8_STAGE(PG8_SB(0, 0), b2, voffB); PG8_STAGE(PG8_SB(0, 1), b2 + hsB, voffB); PG8_STAGE(PG8_SA(0, 0), a2, voffA);
;             PG8_WAIT_V(8); PG8_WAIT_L(0); PG8_BAR; PG8_MMA(1, 0, At, B0); PG8_MMA(1, 1, At, B1); PG8_BAR; PG8_SCHED;
.LBB0_822:
	s_lshl_b64 s[0:1], s[44:45], 22
	v_readlane_b32 s14, v255, 24
	s_add_u32 s24, s14, s0
	v_readlane_b32 s0, v255, 25
	s_addc_u32 s25, s0, s1
	s_ashr_i32 s35, s34, 31
	s_lshl_b64 s[0:1], s[34:35], 19
	s_add_u32 s0, s24, s0
	s_addc_u32 s1, s25, s1
	s_and_b64 s[24:25], s[42:43], exec
	s_cselect_b32 s35, s1, s49
	s_cselect_b32 s45, s0, s48
	s_add_u32 s68, s48, 0x100
	s_addc_u32 s69, s49, 0
	s_mov_b32 s96, -2
.LBB0_823:
	s_add_u32 s42, s36, 0x100
	s_addc_u32 s43, s37, 0
	s_add_i32 s24, 0, 0x10000
	s_cmp_eq_u32 s96, 12
	s_cselect_b32 vcc_hi, s47, s43
	s_cselect_b32 vcc_lo, s46, s42
	s_cselect_b32 s49, s35, s69
	s_cselect_b32 s48, s45, s68
	s_add_i32 s55, 0, 0x14000
	v_add_u32_e32 v150, s24, v232
	v_add_u32_e32 v166, s55, v232
	ds_read_b128 v[138:141], v150
	ds_read_b128 v[142:145], v150 offset:1024
	ds_read_b128 v[146:149], v150 offset:2048
	ds_read_b128 v[150:153], v150 offset:3072
	ds_read_b128 v[154:157], v166
	ds_read_b128 v[158:161], v166 offset:1024
	ds_read_b128 v[162:165], v166 offset:2048
	ds_read_b128 v[184:187], v166 offset:3072
	v_lshl_add_u64 v[166:167], s[36:37], 0, v[134:135]
	s_add_i32 m0, s7, 0xc000
	ds_read_b128 v[188:191], v234
	ds_read_b128 v[192:195], v234 offset:1024
	ds_read_b128 v[196:199], v234 offset:2048
	ds_read_b128 v[200:203], v234 offset:3072
	ds_read_b128 v[204:207], v234 offset:4096
	ds_read_b128 v[208:211], v234 offset:5120
	ds_read_b128 v[236:239], v234 offset:6144
	ds_read_b128 v[240:243], v234 offset:7168
	global_load_lds_dwordx4 v[166:167], off
	v_lshl_add_u64 v[166:167], s[36:37], 0, v[136:137]
	s_add_i32 m0, s7, 0xe000
	s_nop 0
	global_load_lds_dwordx4 v[166:167], off
	s_waitcnt vmcnt(8)
	s_waitcnt lgkmcnt(0)
	s_barrier
	v_mfma_f32_16x16x32_bf16 v[124:127], v[138:141], v[188:191], v[124:127]
	v_mfma_f32_16x16x32_bf16 v[120:123], v[146:149], v[188:191], v[120:123]
	v_mfma_f32_16x16x32_bf16 v[116:119], v[138:141], v[196:199], v[116:119]
	v_mfma_f32_16x16x32_bf16 v[112:115], v[146:149], v[196:199], v[112:115]
	v_mfma_f32_16x16x32_bf16 v[108:111], v[138:141], v[204:207], v[108:111]
	v_mfma_f32_16x16x32_bf16 v[104:107], v[146:149], v[204:207], v[104:107]
	v_mfma_f32_16x16x32_bf16 v[100:103], v[138:141], v[236:239], v[100:103]
	v_mfma_f32_16x16x32_bf16 v[96:99], v[146:149], v[236:239], v[96:99]
	v_mfma_f32_16x16x32_bf16 v[124:127], v[142:145], v[192:195], v[124:127]
	v_mfma_f32_16x16x32_bf16 v[120:123], v[150:153], v[192:195], v[120:123]
	v_mfma_f32_16x16x32_bf16 v[116:119], v[142:145], v[200:203], v[116:119]
	v_mfma_f32_16x16x32_bf16 v[112:115], v[150:153], v[200:203], v[112:115]
	v_mfma_f32_16x16x32_bf16 v[108:111], v[142:145], v[208:211], v[108:111]
	v_mfma_f32_16x16x32_bf16 v[104:107], v[150:153], v[208:211], v[104:107]
	v_mfma_f32_16x16x32_bf16 v[100:103], v[142:145], v[240:243], v[100:103]
	v_mfma_f32_16x16x32_bf16 v[96:99], v[150:153], v[240:243], v[96:99]
	v_mfma_f32_16x16x32_bf16 v[92:95], v[154:157], v[188:191], v[92:95]
	v_mfma_f32_16x16x32_bf16 v[88:91], v[162:165], v[188:191], v[88:91]
	v_mfma_f32_16x16x32_bf16 v[84:87], v[154:157], v[196:199], v[84:87]
	v_mfma_f32_16x16x32_bf16 v[80:83], v[162:165], v[196:199], v[80:83]
	v_mfma_f32_16x16x32_bf16 v[76:79], v[154:157], v[204:207], v[76:79]
	v_mfma_f32_16x16x32_bf16 v[72:75], v[162:165], v[204:207], v[72:75]
	v_mfma_f32_16x16x32_bf16 v[68:71], v[154:157], v[236:239], v[68:71]
	v_mfma_f32_16x16x32_bf16 v[64:67], v[162:165], v[236:239], v[64:67]
	v_mfma_f32_16x16x32_bf16 v[92:95], v[158:161], v[192:195], v[92:95]
	v_mfma_f32_16x16x32_bf16 v[88:91], v[184:187], v[192:195], v[88:91]
	v_mfma_f32_16x16x32_bf16 v[84:87], v[158:161], v[200:203], v[84:87]
	v_mfma_f32_16x16x32_bf16 v[80:83], v[184:187], v[200:203], v[80:83]
	v_mfma_f32_16x16x32_bf16 v[76:79], v[158:161], v[208:211], v[76:79]
	v_mfma_f32_16x16x32_bf16 v[72:75], v[184:187], v[208:211], v[72:75]
	v_mfma_f32_16x16x32_bf16 v[68:71], v[158:161], v[240:243], v[68:71]
	v_mfma_f32_16x16x32_bf16 v[64:67], v[184:187], v[240:243], v[64:67]
	s_barrier
	s_add_i32 s24, s24, s6
	v_lshl_add_u64 v[166:167], s[48:49], 0, v[168:169]
	s_mov_b32 m0, s24
	ds_read_b128 v[188:191], v234 offset:16384
	ds_read_b128 v[192:195], v234 offset:17408
	ds_read_b128 v[196:199], v234 offset:18432
	ds_read_b128 v[200:203], v234 offset:19456
	ds_read_b128 v[204:207], v234 offset:20480
	ds_read_b128 v[208:211], v234 offset:21504
	ds_read_b128 v[236:239], v234 offset:22528
	ds_read_b128 v[240:243], v234 offset:23552
	global_load_lds_dwordx4 v[166:167], off
	s_add_i32 m0, s24, 0x2000
	s_add_u32 s24, s48, 0x40000
	v_lshl_add_u64 v[170:171], s[48:49], 0, v[128:129]
	s_addc_u32 s25, s49, 0
	s_add_i32 s36, s55, s6
	global_load_lds_dwordx4 v[170:171], off
	v_lshl_add_u64 v[172:173], s[24:25], 0, v[168:169]
	s_mov_b32 m0, s36
	v_lshl_add_u64 v[212:213], vcc, 0, v[130:131]
	global_load_lds_dwordx4 v[172:173], off
	v_lshl_add_u64 v[172:173], s[24:25], 0, v[128:129]
	s_add_i32 m0, s36, 0x2000
	s_nop 0
	global_load_lds_dwordx4 v[172:173], off
	v_lshl_add_u64 v[172:173], vcc, 0, v[132:133]
	s_mov_b32 m0, s7
	s_nop 0
	global_load_lds_dwordx4 v[172:173], off
	s_mov_b32 m0, s10
	s_nop 0
	global_load_lds_dwordx4 v[212:213], off
	s_waitcnt vmcnt(8)
	s_waitcnt lgkmcnt(0)
	s_barrier
; #define PG8_STAGE(bufoff, gbase, voff) do { _Pragma("unroll") for (int _i = 0; _i < 2; ++_i) \
;         __builtin_amdgcn_global_load_lds((const unsigned*)((const char*)(gbase) + (voff)[_i]), (LAS unsigned*)(lds + (bufoff) + ldsw + _i * 8192), 16, 0, 0); } while (0)
; #define PG8_LDA(dst, b, h) do { _Pragma("unroll") for (int m = 0; m < 4; ++m) _Pragma("unroll") for (int k = 0; k < 2; ++k) dst[m][k] = *(const LAS bf16x8*)(lds + PG8_SA(b, h) + aoff + m * 2048 + k * 1024); } while (0)
; #define PG8_LDB(dst, b, h) do { _Pragma("unroll") for (int n = 0; n < 2; ++n) _Pragma("unroll") for (int k = 0; k < 2; ++k) dst[n][k] = *(const LAS bf16x8*)(lds + PG8_SB(b, h) + boff + n * 2048 + k * 1024); } while (0)
; #define PG8_MMA(ai, bj, At, Bt) do { __builtin_amdgcn_s_setprio(1); _Pragma("unroll") for (int m = 0; m < 4; ++m) _Pragma("unroll") for (int n = 0; n < 2; ++n) _Pragma("unroll") for (int k = 0; k < 2; ++k) \
;         acc[ai][bj][m][n] = __builtin_amdgcn_mfma_f32_16x16x32_bf16(Bt[n][k], At[m][k], acc[ai][bj][m][n], 0, 0, 0); __builtin_amdgcn_s_setprio(0); } while (0)
; #define PG8_WAIT_V(n) asm volatile("s_waitcnt vmcnt(" #n ")" ::: "memory")
; #define PG8_WAIT_L(n) asm volatile("s_waitcnt lgkmcnt(" #n ")" ::: "memory")
; #define PG8_BAR __builtin_amdgcn_s_barrier()
; #define PG8_SCHED __builtin_amdgcn_sched_barrier(0)
; template <class Epi>
; __device__ __forceinline__ void gemm_phase(LAS unsigned char* lds, const Gemm g, const StaticOrder& S, const Epi& E, const int tid) {
;     ...
;             PG8_WAIT_V(8); PG8_WAIT_L(0); PG8_BAR; PG8_MMA(1, 0, At, B0); PG8_MMA(1, 1, At, B1); PG8_BAR; PG8_SCHED;
;             PG8_LDB(B0, 1, 0); PG8_LDB(B1, 1, 1); PG8_SCHED; PG8_LDA(At, 1, 0); PG8_STAGE(PG8_SA(0, 1), a2 + hsA, voffA);
;             PG8_WAIT_V(8); PG8_WAIT_L(0); PG8_BAR; PG8_MMA(0, 0, At, B0); PG8_MMA(0, 1, At, B1); PG8_BAR; PG8_SCHED;
	v_mfma_f32_16x16x32_bf16 v[60:63], v[138:141], v[188:191], v[60:63]
	v_mfma_f32_16x16x32_bf16 v[56:59], v[146:149], v[188:191], v[56:59]
	v_mfma_f32_16x16x32_bf16 v[52:55], v[138:141], v[196:199], v[52:55]
	v_mfma_f32_16x16x32_bf16 v[48:51], v[146:149], v[196:199], v[48:51]
	v_mfma_f32_16x16x32_bf16 v[44:47], v[138:141], v[204:207], v[44:47]
	v_mfma_f32_16x16x32_bf16 v[40:43], v[146:149], v[204:207], v[40:43]
	v_mfma_f32_16x16x32_bf16 v[36:39], v[138:141], v[236:239], v[36:39]
	v_mfma_f32_16x16x32_bf16 v[32:35], v[146:149], v[236:239], v[32:35]
	v_mfma_f32_16x16x32_bf16 v[60:63], v[142:145], v[192:195], v[60:63]
	v_mfma_f32_16x16x32_bf16 v[56:59], v[150:153], v[192:195], v[56:59]
	v_mfma_f32_16x16x32_bf16 v[52:55], v[142:145], v[200:203], v[52:55]
	v_mfma_f32_16x16x32_bf16 v[48:51], v[150:153], v[200:203], v[48:51]
	v_mfma_f32_16x16x32_bf16 v[44:47], v[142:145], v[208:211], v[44:47]
	v_mfma_f32_16x16x32_bf16 v[40:43], v[150:153], v[208:211], v[40:43]
	v_mfma_f32_16x16x32_bf16 v[36:39], v[142:145], v[240:243], v[36:39]
	v_mfma_f32_16x16x32_bf16 v[32:35], v[150:153], v[240:243], v[32:35]
	v_mfma_f32_16x16x32_bf16 v[28:31], v[154:157], v[188:191], v[28:31]
	v_mfma_f32_16x16x32_bf16 v[24:27], v[162:165], v[188:191], v[24:27]
	v_mfma_f32_16x16x32_bf16 v[20:23], v[154:157], v[196:199], v[20:23]
	v_mfma_f32_16x16x32_bf16 v[16:19], v[162:165], v[196:199], v[16:19]
	v_mfma_f32_16x16x32_bf16 v[12:15], v[154:157], v[204:207], v[12:15]
	v_mfma_f32_16x16x32_bf16 v[8:11], v[162:165], v[204:207], v[8:11]
	v_mfma_f32_16x16x32_bf16 v[4:7], v[154:157], v[236:239], v[4:7]
	v_mfma_f32_16x16x32_bf16 v[0:3], v[162:165], v[236:239], v[0:3]
	v_mfma_f32_16x16x32_bf16 v[28:31], v[158:161], v[192:195], v[28:31]
	v_mfma_f32_16x16x32_bf16 v[24:27], v[184:187], v[192:195], v[24:27]
	v_mfma_f32_16x16x32_bf16 v[20:23], v[158:161], v[200:203], v[20:23]
	v_mfma_f32_16x16x32_bf16 v[16:19], v[184:187], v[200:203], v[16:19]
	v_mfma_f32_16x16x32_bf16 v[12:15], v[158:161], v[208:211], v[12:15]
	v_mfma_f32_16x16x32_bf16 v[8:11], v[184:187], v[208:211], v[8:11]
	v_mfma_f32_16x16x32_bf16 v[4:7], v[158:161], v[240:243], v[4:7]
	v_mfma_f32_16x16x32_bf16 v[0:3], v[184:187], v[240:243], v[0:3]
	s_barrier
	s_add_i32 s36, 0, 0x18000
	s_add_i32 s37, 0, 0x1c000
	v_add_u32_e32 v150, s36, v232
	v_add_u32_e32 v184, s37, v232
	ds_read_b128 v[138:141], v150
	ds_read_b128 v[142:145], v150 offset:1024
	ds_read_b128 v[146:149], v150 offset:2048
	ds_read_b128 v[150:153], v150 offset:3072
	ds_read_b128 v[154:157], v184
	ds_read_b128 v[158:161], v184 offset:1024
	ds_read_b128 v[162:165], v184 offset:2048
	ds_read_b128 v[184:187], v184 offset:3072
	s_add_u32 s24, vcc_lo, 0xc0000
	s_addc_u32 s25, vcc_hi, 0
	s_mov_b32 m0, s11
	v_lshl_add_u64 v[244:245], s[24:25], 0, v[132:133]
	ds_read_b128 v[188:191], v234 offset:32768
	ds_read_b128 v[192:195], v234 offset:33792
	ds_read_b128 v[196:199], v234 offset:34816
	ds_read_b128 v[200:203], v234 offset:35840
	ds_read_b128 v[204:207], v234 offset:36864
	ds_read_b128 v[208:211], v234 offset:37888
	ds_read_b128 v[236:239], v234 offset:38912
	ds_read_b128 v[240:243], v234 offset:39936
	global_load_lds_dwordx4 v[244:245], off
	v_lshl_add_u64 v[244:245], s[24:25], 0, v[130:131]
	s_mov_b32 m0, s27
	s_nop 0
	global_load_lds_dwordx4 v[244:245], off
	s_waitcnt vmcnt(8)
	s_waitcnt lgkmcnt(0)
	s_barrier
	v_mfma_f32_16x16x32_bf16 v[124:127], v[138:141], v[188:191], v[124:127]
	v_mfma_f32_16x16x32_bf16 v[120:123], v[146:149], v[188:191], v[120:123]
	v_mfma_f32_16x16x32_bf16 v[116:119], v[138:141], v[196:199], v[116:119]
	v_mfma_f32_16x16x32_bf16 v[112:115], v[146:149], v[196:199], v[112:115]
	v_mfma_f32_16x16x32_bf16 v[108:111], v[138:141], v[204:207], v[108:111]
	v_mfma_f32_16x16x32_bf16 v[104:107], v[146:149], v[204:207], v[104:107]
	v_mfma_f32_16x16x32_bf16 v[100:103], v[138:141], v[236:239], v[100:103]
	v_mfma_f32_16x16x32_bf16 v[96:99], v[146:149], v[236:239], v[96:99]
	v_mfma_f32_16x16x32_bf16 v[124:127], v[142:145], v[192:195], v[124:127]
	v_mfma_f32_16x16x32_bf16 v[120:123], v[150:153], v[192:195], v[120:123]
	v_mfma_f32_16x16x32_bf16 v[116:119], v[142:145], v[200:203], v[116:119]
	v_mfma_f32_16x16x32_bf16 v[112:115], v[150:153], v[200:203], v[112:115]
	v_mfma_f32_16x16x32_bf16 v[108:111], v[142:145], v[208:211], v[108:111]
	v_mfma_f32_16x16x32_bf16 v[104:107], v[150:153], v[208:211], v[104:107]
	v_mfma_f32_16x16x32_bf16 v[100:103], v[142:145], v[240:243], v[100:103]
	v_mfma_f32_16x16x32_bf16 v[96:99], v[150:153], v[240:243], v[96:99]
	v_mfma_f32_16x16x32_bf16 v[92:95], v[154:157], v[188:191], v[92:95]
	v_mfma_f32_16x16x32_bf16 v[88:91], v[162:165], v[188:191], v[88:91]
	v_mfma_f32_16x16x32_bf16 v[84:87], v[154:157], v[196:199], v[84:87]
	v_mfma_f32_16x16x32_bf16 v[80:83], v[162:165], v[196:199], v[80:83]
	v_mfma_f32_16x16x32_bf16 v[76:79], v[154:157], v[204:207], v[76:79]
	v_mfma_f32_16x16x32_bf16 v[72:75], v[162:165], v[204:207], v[72:75]
	v_mfma_f32_16x16x32_bf16 v[68:71], v[154:157], v[236:239], v[68:71]
	v_mfma_f32_16x16x32_bf16 v[64:67], v[162:165], v[236:239], v[64:67]
	v_mfma_f32_16x16x32_bf16 v[92:95], v[158:161], v[192:195], v[92:95]
	v_mfma_f32_16x16x32_bf16 v[88:91], v[184:187], v[192:195], v[88:91]
	v_mfma_f32_16x16x32_bf16 v[84:87], v[158:161], v[200:203], v[84:87]
	v_mfma_f32_16x16x32_bf16 v[80:83], v[184:187], v[200:203], v[80:83]
	v_mfma_f32_16x16x32_bf16 v[76:79], v[158:161], v[208:211], v[76:79]
	v_mfma_f32_16x16x32_bf16 v[72:75], v[184:187], v[208:211], v[72:75]
	v_mfma_f32_16x16x32_bf16 v[68:71], v[158:161], v[240:243], v[68:71]
	v_mfma_f32_16x16x32_bf16 v[64:67], v[184:187], v[240:243], v[64:67]
	s_barrier
; #define PG8_STAGE(bufoff, gbase, voff) do { _Pragma("unroll") for (int _i = 0; _i < 2; ++_i) \
;         __builtin_amdgcn_global_load_lds((const unsigned*)((const char*)(gbase) + (voff)[_i]), (LAS unsigned*)(lds + (bufoff) + ldsw + _i * 8192), 16, 0, 0); } while (0)
; #define PG8_LDA(dst, b, h) do { _Pragma("unroll") for (int m = 0; m < 4; ++m) _Pragma("unroll") for (int k = 0; k < 2; ++k) dst[m][k] = *(const LAS bf16x8*)(lds + PG8_SA(b, h) + aoff + m * 2048 + k * 1024); } while (0)
; #define PG8_MMA(ai, bj, At, Bt) do { __builtin_amdgcn_s_setprio(1); _Pragma("unroll") for (int m = 0; m < 4; ++m) _Pragma("unroll") for (int n = 0; n < 2; ++n) _Pragma("unroll") for (int k = 0; k < 2; ++k) \
;         acc[ai][bj][m][n] = __builtin_amdgcn_mfma_f32_16x16x32_bf16(Bt[n][k], At[m][k], acc[ai][bj][m][n], 0, 0, 0); __builtin_amdgcn_s_setprio(0); } while (0)
; #define PG8_WAIT_V(n) asm volatile("s_waitcnt vmcnt(" #n ")" ::: "memory")
; #define PG8_WAIT_L(n) asm volatile("s_waitcnt lgkmcnt(" #n ")" ::: "memory")
; #define PG8_BAR __builtin_amdgcn_s_barrier()
; #define PG8_SCHED __builtin_amdgcn_sched_barrier(0)
; template <class Epi>
; __device__ __forceinline__ void gemm_phase(LAS unsigned char* lds, const Gemm g, const StaticOrder& S, const Epi& E, const int tid) {
;     ...
;             PG8_LDA(At, 1, 1); PG8_STAGE(PG8_SB(1, 0), b3, voffB); PG8_STAGE(PG8_SB(1, 1), b3 + hsB, voffB); PG8_STAGE(PG8_SA(1, 0), a3, voffA);
;             PG8_WAIT_V(8); PG8_WAIT_L(0); PG8_BAR; PG8_MMA(1, 0, At, B0); PG8_MMA(1, 1, At, B1); PG8_BAR; PG8_SCHED;
;         }
;         if (wr == 0) PG8_BAR;
	s_add_i32 s24, s36, s6
	v_lshl_add_u64 v[166:167], v[166:167], 0, s[28:29]
	s_mov_b32 m0, s24
	ds_read_b128 v[188:191], v234 offset:49152
	ds_read_b128 v[192:195], v234 offset:50176
	ds_read_b128 v[196:199], v234 offset:51200
	ds_read_b128 v[200:203], v234 offset:52224
	ds_read_b128 v[204:207], v234 offset:53248
	ds_read_b128 v[208:211], v234 offset:54272
	ds_read_b128 v[236:239], v234 offset:55296
	ds_read_b128 v[240:243], v234 offset:56320
	global_load_lds_dwordx4 v[166:167], off
	s_add_i32 m0, s24, 0x2000
	s_add_u32 s24, s48, 0x40080
	v_lshl_add_u64 v[166:167], v[170:171], 0, s[28:29]
	s_addc_u32 s25, s49, 0
	s_add_i32 s36, s37, s6
	global_load_lds_dwordx4 v[166:167], off
	v_lshl_add_u64 v[166:167], s[24:25], 0, v[168:169]
	s_mov_b32 m0, s36
	s_nop 0
	global_load_lds_dwordx4 v[166:167], off
	v_lshl_add_u64 v[166:167], s[24:25], 0, v[128:129]
	s_add_i32 m0, s36, 0x2000
	s_nop 0
	global_load_lds_dwordx4 v[166:167], off
	v_lshl_add_u64 v[166:167], v[172:173], 0, s[28:29]
	s_mov_b32 m0, s56
	s_nop 0
	global_load_lds_dwordx4 v[166:167], off
	v_lshl_add_u64 v[166:167], v[212:213], 0, s[28:29]
	s_mov_b32 m0, s57
	s_nop 0
	global_load_lds_dwordx4 v[166:167], off
	s_waitcnt vmcnt(8)
	s_waitcnt lgkmcnt(0)
	s_barrier
	v_mfma_f32_16x16x32_bf16 v[60:63], v[138:141], v[188:191], v[60:63]
	v_mfma_f32_16x16x32_bf16 v[56:59], v[146:149], v[188:191], v[56:59]
	v_mfma_f32_16x16x32_bf16 v[52:55], v[138:141], v[196:199], v[52:55]
	v_mfma_f32_16x16x32_bf16 v[48:51], v[146:149], v[196:199], v[48:51]
	v_mfma_f32_16x16x32_bf16 v[44:47], v[138:141], v[204:207], v[44:47]
	v_mfma_f32_16x16x32_bf16 v[40:43], v[146:149], v[204:207], v[40:43]
	v_mfma_f32_16x16x32_bf16 v[36:39], v[138:141], v[236:239], v[36:39]
	v_mfma_f32_16x16x32_bf16 v[32:35], v[146:149], v[236:239], v[32:35]
	v_mfma_f32_16x16x32_bf16 v[60:63], v[142:145], v[192:195], v[60:63]
	v_mfma_f32_16x16x32_bf16 v[56:59], v[150:153], v[192:195], v[56:59]
	v_mfma_f32_16x16x32_bf16 v[52:55], v[142:145], v[200:203], v[52:55]
	v_mfma_f32_16x16x32_bf16 v[48:51], v[150:153], v[200:203], v[48:51]
	v_mfma_f32_16x16x32_bf16 v[44:47], v[142:145], v[208:211], v[44:47]
	v_mfma_f32_16x16x32_bf16 v[40:43], v[150:153], v[208:211], v[40:43]
	v_mfma_f32_16x16x32_bf16 v[36:39], v[142:145], v[240:243], v[36:39]
	v_mfma_f32_16x16x32_bf16 v[32:35], v[150:153], v[240:243], v[32:35]
	v_mfma_f32_16x16x32_bf16 v[28:31], v[154:157], v[188:191], v[28:31]
	v_mfma_f32_16x16x32_bf16 v[24:27], v[162:165], v[188:191], v[24:27]
	v_mfma_f32_16x16x32_bf16 v[20:23], v[154:157], v[196:199], v[20:23]
	v_mfma_f32_16x16x32_bf16 v[16:19], v[162:165], v[196:199], v[16:19]
	v_mfma_f32_16x16x32_bf16 v[12:15], v[154:157], v[204:207], v[12:15]
	v_mfma_f32_16x16x32_bf16 v[8:11], v[162:165], v[204:207], v[8:11]
	v_mfma_f32_16x16x32_bf16 v[4:7], v[154:157], v[236:239], v[4:7]
	v_mfma_f32_16x16x32_bf16 v[0:3], v[162:165], v[236:239], v[0:3]
	v_mfma_f32_16x16x32_bf16 v[28:31], v[158:161], v[192:195], v[28:31]
	v_mfma_f32_16x16x32_bf16 v[24:27], v[184:187], v[192:195], v[24:27]
	v_mfma_f32_16x16x32_bf16 v[20:23], v[158:161], v[200:203], v[20:23]
	v_mfma_f32_16x16x32_bf16 v[16:19], v[184:187], v[200:203], v[16:19]
	v_mfma_f32_16x16x32_bf16 v[12:15], v[158:161], v[208:211], v[12:15]
	v_mfma_f32_16x16x32_bf16 v[8:11], v[184:187], v[208:211], v[8:11]
	v_mfma_f32_16x16x32_bf16 v[4:7], v[158:161], v[240:243], v[4:7]
	v_mfma_f32_16x16x32_bf16 v[0:3], v[184:187], v[240:243], v[0:3]
	s_barrier
	s_add_i32 s96, s96, 2
	s_add_u32 s68, s68, 0x100
	s_addc_u32 s69, s69, 0
	s_cmp_gt_u32 s96, 13
	s_mov_b64 s[36:37], s[42:43]
	s_cbranch_scc0 .LBB0_823
	s_and_b64 vcc, exec, s[12:13]
	s_cbranch_vccz .LBB0_826
	s_barrier

; #define PG8_STAGE(bufoff, gbase, voff) do { _Pragma("unroll") for (int _i = 0; _i < 2; ++_i) \
;         __builtin_amdgcn_global_load_lds((const unsigned*)((const char*)(gbase) + (voff)[_i]), (LAS unsigned*)(lds + (bufoff) + ldsw + _i * 8192), 16, 0, 0); } while (0)
; #define PG8_LDA(dst, b, h) do { _Pragma("unroll") for (int m = 0; m < 4; ++m) _Pragma("unroll") for (int k = 0; k < 2; ++k) dst[m][k] = *(const LAS bf16x8*)(lds + PG8_SA(b, h) + aoff + m * 2048 + k * 1024); } while (0)
; #define PG8_LDB(dst, b, h) do { _Pragma("unroll") for (int n = 0; n < 2; ++n) _Pragma("unroll") for (int k = 0; k < 2; ++k) dst[n][k] = *(const LAS bf16x8*)(lds + PG8_SB(b, h) + boff + n * 2048 + k * 1024); } while (0)
; #define PG8_MMA(ai, bj, At, Bt) do { __builtin_amdgcn_s_setprio(1); _Pragma("unroll") for (int m = 0; m < 4; ++m) _Pragma("unroll") for (int n = 0; n < 2; ++n) _Pragma("unroll") for (int k = 0; k < 2; ++k) \
;         acc[ai][bj][m][n] = __builtin_amdgcn_mfma_f32_16x16x32_bf16(Bt[n][k], At[m][k], acc[ai][bj][m][n], 0, 0, 0); __builtin_amdgcn_s_setprio(0); } while (0)
; #define PG8_WAIT_V(n) asm volatile("s_waitcnt vmcnt(" #n ")" ::: "memory")
; #define PG8_WAIT_L(n) asm volatile("s_waitcnt lgkmcnt(" #n ")" ::: "memory")
; #define PG8_BAR __builtin_amdgcn_s_barrier()
; template <class Epi>
; __device__ __forceinline__ void gemm_phase(LAS unsigned char* lds, const Gemm g, const StaticOrder& S, const Epi& E, const int tid) {
;     ...
;         for (int t = 0; t < nt; t += 2) {
;             const bool last = (t == nt - 2);
;             const char* a1 = cA + (size_t)(t + 1) * kstep;
;             const char* a2 = last ? nA : cA + (size_t)(t + 2) * kstep; const char* b2 = last ? nB : cB + (size_t)(t + 2) * kstep;
;             const char* a3 = a2 + kstep; const char* b3 = b2 + kstep;
;             PG8_LDB(B0, 0, 0); PG8_LDB(B1, 0, 1); PG8_SCHED; PG8_LDA(At, 0, 0); PG8_STAGE(PG8_SA(1, 1), a1 + hsA, voffA);
;             PG8_WAIT_V(8); PG8_WAIT_L(0); PG8_BAR; PG8_MMA(0, 0, At, B0); PG8_MMA(0, 1, At, B1); PG8_BAR; PG8_SCHED;
;     ...
;         if (!(Epi::CHAIN && cur.n + 1 < S.NS)) {
; #pragma unroll
;         for (int a = 0; a < 2; ++a)
; #pragma unroll
;             for (int b = 0; b < 2; ++b)
; #pragma unroll
;                 for (int m = 0; m < 4; ++m)
; #pragma unroll
;                     for (int n = 0; n < 2; ++n) acc[a][b][m][n] = (f32x4){0.f, 0.f, 0.f, 0.f};
;         }
.LBB0_892:
	s_ashr_i32 s11, s10, 31
	s_lshl_b64 s[12:13], s[10:11], 20
	s_add_u32 s12, s58, s12
	s_addc_u32 s13, s59, s13
	s_and_b64 s[14:15], s[40:41], exec
	s_cselect_b32 s11, s13, s17
	s_cselect_b32 s49, s12, s16
	s_ashr_i32 s9, s8, 31
	s_lshl_b64 s[14:15], s[8:9], 20
	s_add_u32 s14, s27, s14
	s_addc_u32 s15, s34, s15
	s_and_b64 s[18:19], s[40:41], exec
	s_cselect_b32 s9, s15, s1
	s_cselect_b32 s52, s14, s0
	s_add_u32 s16, s16, 0x80080
	s_addc_u32 s17, s17, 0
	s_add_u32 s53, s0, 0x100
	v_mov_b32_e32 v0, 0
	s_addc_u32 s56, s1, 0
	s_mov_b32 s57, -2
	v_mov_b32_e32 v1, v0
	v_mov_b32_e32 v2, v0
	v_mov_b32_e32 v3, v0
	v_mov_b32_e32 v4, v0
	v_mov_b32_e32 v5, v0
	v_mov_b32_e32 v6, v0
	v_mov_b32_e32 v7, v0
	v_mov_b32_e32 v16, v0
	v_mov_b32_e32 v17, v0
	v_mov_b32_e32 v18, v0
	v_mov_b32_e32 v19, v0
	v_mov_b32_e32 v20, v0
	v_mov_b32_e32 v21, v0
	v_mov_b32_e32 v22, v0
	v_mov_b32_e32 v23, v0
	v_mov_b32_e32 v32, v0
	v_mov_b32_e32 v33, v0
	v_mov_b32_e32 v34, v0
	v_mov_b32_e32 v35, v0
	v_mov_b32_e32 v36, v0
	v_mov_b32_e32 v37, v0
	v_mov_b32_e32 v38, v0
	v_mov_b32_e32 v39, v0
	v_mov_b32_e32 v48, v0
	v_mov_b32_e32 v49, v0
	v_mov_b32_e32 v50, v0
	v_mov_b32_e32 v51, v0
	v_mov_b32_e32 v52, v0
	v_mov_b32_e32 v53, v0
	v_mov_b32_e32 v54, v0
	v_mov_b32_e32 v55, v0
	v_mov_b32_e32 v8, v0
	v_mov_b32_e32 v9, v0
	v_mov_b32_e32 v10, v0
	v_mov_b32_e32 v11, v0
	v_mov_b32_e32 v12, v0
	v_mov_b32_e32 v13, v0
	v_mov_b32_e32 v14, v0
	v_mov_b32_e32 v15, v0
	v_mov_b32_e32 v24, v0
	v_mov_b32_e32 v25, v0
	v_mov_b32_e32 v26, v0
	v_mov_b32_e32 v27, v0
	v_mov_b32_e32 v28, v0
	v_mov_b32_e32 v29, v0
	v_mov_b32_e32 v30, v0
	v_mov_b32_e32 v31, v0
	v_mov_b32_e32 v40, v0
	v_mov_b32_e32 v41, v0
	v_mov_b32_e32 v42, v0
	v_mov_b32_e32 v43, v0
	v_mov_b32_e32 v44, v0
	v_mov_b32_e32 v45, v0
	v_mov_b32_e32 v46, v0
	v_mov_b32_e32 v47, v0
	v_mov_b32_e32 v56, v0
	v_mov_b32_e32 v57, v0
	v_mov_b32_e32 v58, v0
	v_mov_b32_e32 v59, v0
	v_mov_b32_e32 v60, v0
	v_mov_b32_e32 v61, v0
	v_mov_b32_e32 v62, v0
	v_mov_b32_e32 v63, v0
	v_mov_b32_e32 v80, v0
	v_mov_b32_e32 v81, v0
	v_mov_b32_e32 v82, v0
	v_mov_b32_e32 v83, v0
	v_mov_b32_e32 v84, v0
	v_mov_b32_e32 v85, v0
	v_mov_b32_e32 v86, v0
	v_mov_b32_e32 v87, v0
	v_mov_b32_e32 v92, v0
	v_mov_b32_e32 v93, v0
	v_mov_b32_e32 v94, v0
	v_mov_b32_e32 v95, v0
	v_mov_b32_e32 v100, v0
	v_mov_b32_e32 v101, v0
	v_mov_b32_e32 v102, v0
	v_mov_b32_e32 v103, v0
	v_mov_b32_e32 v112, v0
	v_mov_b32_e32 v113, v0
	v_mov_b32_e32 v114, v0
	v_mov_b32_e32 v115, v0
	v_mov_b32_e32 v116, v0
	v_mov_b32_e32 v117, v0
	v_mov_b32_e32 v118, v0
	v_mov_b32_e32 v119, v0
	v_mov_b32_e32 v128, v0
	v_mov_b32_e32 v129, v0
	v_mov_b32_e32 v130, v0
	v_mov_b32_e32 v131, v0
	v_mov_b32_e32 v132, v0
	v_mov_b32_e32 v133, v0
	v_mov_b32_e32 v134, v0
	v_mov_b32_e32 v135, v0
	v_mov_b32_e32 v88, v0
	v_mov_b32_e32 v89, v0
	v_mov_b32_e32 v90, v0
	v_mov_b32_e32 v91, v0
	v_mov_b32_e32 v96, v0
	v_mov_b32_e32 v97, v0
	v_mov_b32_e32 v98, v0
	v_mov_b32_e32 v99, v0
	v_mov_b32_e32 v104, v0
	v_mov_b32_e32 v105, v0
	v_mov_b32_e32 v106, v0
	v_mov_b32_e32 v107, v0
	v_mov_b32_e32 v108, v0
	v_mov_b32_e32 v109, v0
	v_mov_b32_e32 v110, v0
	v_mov_b32_e32 v111, v0
	v_mov_b32_e32 v120, v0
	v_mov_b32_e32 v121, v0
	v_mov_b32_e32 v122, v0
	v_mov_b32_e32 v123, v0
	v_mov_b32_e32 v124, v0
	v_mov_b32_e32 v125, v0
	v_mov_b32_e32 v126, v0
	v_mov_b32_e32 v127, v0
	v_mov_b32_e32 v136, v0
	v_mov_b32_e32 v137, v0
	v_mov_b32_e32 v138, v0
	v_mov_b32_e32 v139, v0
	v_mov_b32_e32 v140, v0
	v_mov_b32_e32 v141, v0
	v_mov_b32_e32 v142, v0
	v_mov_b32_e32 v143, v0
.LBB0_893:
	s_add_u32 s0, s16, 0xfff80080
	s_addc_u32 s1, s17, -1
	s_add_i32 s2, 0, 0x10000
	s_cmp_eq_u32 s57, 28
	s_cselect_b32 s19, s11, s1
	s_cselect_b32 s18, s49, s0
	s_cselect_b32 s1, s9, s56
	s_cselect_b32 s0, s52, s53
	s_add_i32 s55, 0, 0x14000
	v_add_u32_e32 v76, s2, v204
	v_add_u32_e32 v156, s55, v204
	ds_read_b128 v[64:67], v76
	ds_read_b128 v[68:71], v76 offset:1024
	ds_read_b128 v[72:75], v76 offset:2048
	ds_read_b128 v[76:79], v76 offset:3072
	ds_read_b128 v[144:147], v156
	ds_read_b128 v[148:151], v156 offset:1024
	ds_read_b128 v[152:155], v156 offset:2048
	ds_read_b128 v[156:159], v156 offset:3072
	v_lshl_add_u64 v[170:171], s[16:17], 0, v[192:193]
	s_add_i32 m0, s36, 0xc000
	ds_read_b128 v[160:163], v209
	ds_read_b128 v[164:167], v209 offset:1024
	ds_read_b128 v[196:199], v209 offset:2048
	ds_read_b128 v[200:203], v209 offset:3072
	ds_read_b128 v[210:213], v209 offset:4096
	ds_read_b128 v[230:233], v209 offset:5120
	ds_read_b128 v[234:237], v209 offset:6144
	ds_read_b128 v[238:241], v209 offset:7168
	global_load_lds_dwordx4 v[170:171], off
	v_lshl_add_u64 v[170:171], s[16:17], 0, v[194:195]
	s_add_i32 m0, s36, 0xe000
	s_nop 0
	global_load_lds_dwordx4 v[170:171], off
	s_waitcnt vmcnt(8)
	s_waitcnt lgkmcnt(0)
	s_barrier
; #define PG8_STAGE(bufoff, gbase, voff) do { _Pragma("unroll") for (int _i = 0; _i < 2; ++_i) \
;         __builtin_amdgcn_global_load_lds((const unsigned*)((const char*)(gbase) + (voff)[_i]), (LAS unsigned*)(lds + (bufoff) + ldsw + _i * 8192), 16, 0, 0); } while (0)
; #define PG8_LDA(dst, b, h) do { _Pragma("unroll") for (int m = 0; m < 4; ++m) _Pragma("unroll") for (int k = 0; k < 2; ++k) dst[m][k] = *(const LAS bf16x8*)(lds + PG8_SA(b, h) + aoff + m * 2048 + k * 1024); } while (0)
; #define PG8_MMA(ai, bj, At, Bt) do { __builtin_amdgcn_s_setprio(1); _Pragma("unroll") for (int m = 0; m < 4; ++m) _Pragma("unroll") for (int n = 0; n < 2; ++n) _Pragma("unroll") for (int k = 0; k < 2; ++k) \
;         acc[ai][bj][m][n] = __builtin_amdgcn_mfma_f32_16x16x32_bf16(Bt[n][k], At[m][k], acc[ai][bj][m][n], 0, 0, 0); __builtin_amdgcn_s_setprio(0); } while (0)
; #define PG8_WAIT_V(n) asm volatile("s_waitcnt vmcnt(" #n ")" ::: "memory")
; #define PG8_WAIT_L(n) asm volatile("s_waitcnt lgkmcnt(" #n ")" ::: "memory")
; #define PG8_BAR __builtin_amdgcn_s_barrier()
; #define PG8_SCHED __builtin_amdgcn_sched_barrier(0)
; template <class Epi>
; __device__ __forceinline__ void gemm_phase(LAS unsigned char* lds, const Gemm g, const StaticOrder& S, const Epi& E, const int tid) {
;     ...
;             PG8_WAIT_V(8); PG8_WAIT_L(0); PG8_BAR; PG8_MMA(0, 0, At, B0); PG8_MMA(0, 1, At, B1); PG8_BAR; PG8_SCHED;
;             PG8_LDA(At, 0, 1); PG8_STAGE(PG8_SB(0, 0), b2, voffB); PG8_STAGE(PG8_SB(0, 1), b2 + hsB, voffB); PG8_STAGE(PG8_SA(0, 0), a2, voffA);
;             PG8_WAIT_V(8); PG8_WAIT_L(0); PG8_BAR; PG8_MMA(1, 0, At, B0); PG8_MMA(1, 1, At, B1); PG8_BAR; PG8_SCHED;
	v_mfma_f32_16x16x32_bf16 v[140:143], v[64:67], v[160:163], v[140:143]
	v_mfma_f32_16x16x32_bf16 v[136:139], v[72:75], v[160:163], v[136:139]
	v_mfma_f32_16x16x32_bf16 v[124:127], v[64:67], v[196:199], v[124:127]
	v_mfma_f32_16x16x32_bf16 v[120:123], v[72:75], v[196:199], v[120:123]
	v_mfma_f32_16x16x32_bf16 v[108:111], v[64:67], v[210:213], v[108:111]
	v_mfma_f32_16x16x32_bf16 v[104:107], v[72:75], v[210:213], v[104:107]
	v_mfma_f32_16x16x32_bf16 v[96:99], v[64:67], v[234:237], v[96:99]
	v_mfma_f32_16x16x32_bf16 v[88:91], v[72:75], v[234:237], v[88:91]
	v_mfma_f32_16x16x32_bf16 v[140:143], v[68:71], v[164:167], v[140:143]
	v_mfma_f32_16x16x32_bf16 v[136:139], v[76:79], v[164:167], v[136:139]
	v_mfma_f32_16x16x32_bf16 v[124:127], v[68:71], v[200:203], v[124:127]
	v_mfma_f32_16x16x32_bf16 v[120:123], v[76:79], v[200:203], v[120:123]
	v_mfma_f32_16x16x32_bf16 v[108:111], v[68:71], v[230:233], v[108:111]
	v_mfma_f32_16x16x32_bf16 v[104:107], v[76:79], v[230:233], v[104:107]
	v_mfma_f32_16x16x32_bf16 v[96:99], v[68:71], v[238:241], v[96:99]
	v_mfma_f32_16x16x32_bf16 v[88:91], v[76:79], v[238:241], v[88:91]
	v_mfma_f32_16x16x32_bf16 v[132:135], v[144:147], v[160:163], v[132:135]
	v_mfma_f32_16x16x32_bf16 v[128:131], v[152:155], v[160:163], v[128:131]
	v_mfma_f32_16x16x32_bf16 v[116:119], v[144:147], v[196:199], v[116:119]
	v_mfma_f32_16x16x32_bf16 v[112:115], v[152:155], v[196:199], v[112:115]
	v_mfma_f32_16x16x32_bf16 v[100:103], v[144:147], v[210:213], v[100:103]
	v_mfma_f32_16x16x32_bf16 v[92:95], v[152:155], v[210:213], v[92:95]
	v_mfma_f32_16x16x32_bf16 v[84:87], v[144:147], v[234:237], v[84:87]
	v_mfma_f32_16x16x32_bf16 v[80:83], v[152:155], v[234:237], v[80:83]
	v_mfma_f32_16x16x32_bf16 v[132:135], v[148:151], v[164:167], v[132:135]
	v_mfma_f32_16x16x32_bf16 v[128:131], v[156:159], v[164:167], v[128:131]
	v_mfma_f32_16x16x32_bf16 v[116:119], v[148:151], v[200:203], v[116:119]
	v_mfma_f32_16x16x32_bf16 v[112:115], v[156:159], v[200:203], v[112:115]
	v_mfma_f32_16x16x32_bf16 v[100:103], v[148:151], v[230:233], v[100:103]
	v_mfma_f32_16x16x32_bf16 v[92:95], v[156:159], v[230:233], v[92:95]
	v_mfma_f32_16x16x32_bf16 v[84:87], v[148:151], v[238:241], v[84:87]
	v_mfma_f32_16x16x32_bf16 v[80:83], v[156:159], v[238:241], v[80:83]
	s_barrier
	s_add_i32 s2, s2, s35
	v_lshl_add_u64 v[170:171], s[0:1], 0, v[188:189]
	s_mov_b32 m0, s2
	ds_read_b128 v[160:163], v209 offset:16384
	ds_read_b128 v[164:167], v209 offset:17408
	ds_read_b128 v[196:199], v209 offset:18432
	ds_read_b128 v[200:203], v209 offset:19456
	ds_read_b128 v[210:213], v209 offset:20480
	ds_read_b128 v[230:233], v209 offset:21504
	ds_read_b128 v[234:237], v209 offset:22528
	ds_read_b128 v[238:241], v209 offset:23552
	global_load_lds_dwordx4 v[170:171], off
	s_add_i32 m0, s2, 0x2000
	s_add_u32 s24, s0, 0x80000
	v_lshl_add_u64 v[172:173], s[0:1], 0, v[184:185]
	s_addc_u32 s25, s1, 0
	s_add_i32 s2, s55, s35
	global_load_lds_dwordx4 v[172:173], off
	v_lshl_add_u64 v[242:243], s[24:25], 0, v[188:189]
	s_mov_b32 m0, s2
	v_lshl_add_u64 v[244:245], s[18:19], 0, v[186:187]
	global_load_lds_dwordx4 v[242:243], off
	v_lshl_add_u64 v[242:243], s[24:25], 0, v[184:185]
	s_add_i32 m0, s2, 0x2000
	s_nop 0
	global_load_lds_dwordx4 v[242:243], off
	v_lshl_add_u64 v[242:243], s[18:19], 0, v[190:191]
	s_mov_b32 m0, s36
	s_nop 0
	global_load_lds_dwordx4 v[242:243], off
	s_mov_b32 m0, s37
	s_nop 0
	global_load_lds_dwordx4 v[244:245], off
	s_waitcnt vmcnt(8)
	s_waitcnt lgkmcnt(0)
	s_barrier
	v_mfma_f32_16x16x32_bf16 v[60:63], v[64:67], v[160:163], v[60:63]
	v_mfma_f32_16x16x32_bf16 v[56:59], v[72:75], v[160:163], v[56:59]
	v_mfma_f32_16x16x32_bf16 v[44:47], v[64:67], v[196:199], v[44:47]
	v_mfma_f32_16x16x32_bf16 v[40:43], v[72:75], v[196:199], v[40:43]
	v_mfma_f32_16x16x32_bf16 v[28:31], v[64:67], v[210:213], v[28:31]
	v_mfma_f32_16x16x32_bf16 v[24:27], v[72:75], v[210:213], v[24:27]
	v_mfma_f32_16x16x32_bf16 v[12:15], v[64:67], v[234:237], v[12:15]
	v_mfma_f32_16x16x32_bf16 v[8:11], v[72:75], v[234:237], v[8:11]
	v_mfma_f32_16x16x32_bf16 v[60:63], v[68:71], v[164:167], v[60:63]
	v_mfma_f32_16x16x32_bf16 v[56:59], v[76:79], v[164:167], v[56:59]
	v_mfma_f32_16x16x32_bf16 v[44:47], v[68:71], v[200:203], v[44:47]
	v_mfma_f32_16x16x32_bf16 v[40:43], v[76:79], v[200:203], v[40:43]
	v_mfma_f32_16x16x32_bf16 v[28:31], v[68:71], v[230:233], v[28:31]
	v_mfma_f32_16x16x32_bf16 v[24:27], v[76:79], v[230:233], v[24:27]
	v_mfma_f32_16x16x32_bf16 v[12:15], v[68:71], v[238:241], v[12:15]
	v_mfma_f32_16x16x32_bf16 v[8:11], v[76:79], v[238:241], v[8:11]
	v_mfma_f32_16x16x32_bf16 v[52:55], v[144:147], v[160:163], v[52:55]
	v_mfma_f32_16x16x32_bf16 v[48:51], v[152:155], v[160:163], v[48:51]
	v_mfma_f32_16x16x32_bf16 v[36:39], v[144:147], v[196:199], v[36:39]
	v_mfma_f32_16x16x32_bf16 v[32:35], v[152:155], v[196:199], v[32:35]
	v_mfma_f32_16x16x32_bf16 v[20:23], v[144:147], v[210:213], v[20:23]
	v_mfma_f32_16x16x32_bf16 v[16:19], v[152:155], v[210:213], v[16:19]
	v_mfma_f32_16x16x32_bf16 v[4:7], v[144:147], v[234:237], v[4:7]
	v_mfma_f32_16x16x32_bf16 v[0:3], v[152:155], v[234:237], v[0:3]
	v_mfma_f32_16x16x32_bf16 v[52:55], v[148:151], v[164:167], v[52:55]
	v_mfma_f32_16x16x32_bf16 v[48:51], v[156:159], v[164:167], v[48:51]
	v_mfma_f32_16x16x32_bf16 v[36:39], v[148:151], v[200:203], v[36:39]
	v_mfma_f32_16x16x32_bf16 v[32:35], v[156:159], v[200:203], v[32:35]
	v_mfma_f32_16x16x32_bf16 v[20:23], v[148:151], v[230:233], v[20:23]
	v_mfma_f32_16x16x32_bf16 v[16:19], v[156:159], v[230:233], v[16:19]
	v_mfma_f32_16x16x32_bf16 v[4:7], v[148:151], v[238:241], v[4:7]
	v_mfma_f32_16x16x32_bf16 v[0:3], v[156:159], v[238:241], v[0:3]
	s_barrier
; #define PG8_STAGE(bufoff, gbase, voff) do { _Pragma("unroll") for (int _i = 0; _i < 2; ++_i) \
;         __builtin_amdgcn_global_load_lds((const unsigned*)((const char*)(gbase) + (voff)[_i]), (LAS unsigned*)(lds + (bufoff) + ldsw + _i * 8192), 16, 0, 0); } while (0)
; #define PG8_LDA(dst, b, h) do { _Pragma("unroll") for (int m = 0; m < 4; ++m) _Pragma("unroll") for (int k = 0; k < 2; ++k) dst[m][k] = *(const LAS bf16x8*)(lds + PG8_SA(b, h) + aoff + m * 2048 + k * 1024); } while (0)
; #define PG8_LDB(dst, b, h) do { _Pragma("unroll") for (int n = 0; n < 2; ++n) _Pragma("unroll") for (int k = 0; k < 2; ++k) dst[n][k] = *(const LAS bf16x8*)(lds + PG8_SB(b, h) + boff + n * 2048 + k * 1024); } while (0)
; #define PG8_MMA(ai, bj, At, Bt) do { __builtin_amdgcn_s_setprio(1); _Pragma("unroll") for (int m = 0; m < 4; ++m) _Pragma("unroll") for (int n = 0; n < 2; ++n) _Pragma("unroll") for (int k = 0; k < 2; ++k) \
;         acc[ai][bj][m][n] = __builtin_amdgcn_mfma_f32_16x16x32_bf16(Bt[n][k], At[m][k], acc[ai][bj][m][n], 0, 0, 0); __builtin_amdgcn_s_setprio(0); } while (0)
; #define PG8_WAIT_V(n) asm volatile("s_waitcnt vmcnt(" #n ")" ::: "memory")
; #define PG8_WAIT_L(n) asm volatile("s_waitcnt lgkmcnt(" #n ")" ::: "memory")
; #define PG8_BAR __builtin_amdgcn_s_barrier()
; #define PG8_SCHED __builtin_amdgcn_sched_barrier(0)
; template <class Epi>
; __device__ __forceinline__ void gemm_phase(LAS unsigned char* lds, const Gemm g, const StaticOrder& S, const Epi& E, const int tid) {
;     ...
;             PG8_LDB(B0, 1, 0); PG8_LDB(B1, 1, 1); PG8_SCHED; PG8_LDA(At, 1, 0); PG8_STAGE(PG8_SA(0, 1), a2 + hsA, voffA);
;             PG8_WAIT_V(8); PG8_WAIT_L(0); PG8_BAR; PG8_MMA(0, 0, At, B0); PG8_MMA(0, 1, At, B1); PG8_BAR; PG8_SCHED;
	s_add_i32 s2, 0, 0x18000
	s_add_i32 s24, 0, 0x1c000
	v_add_u32_e32 v76, s2, v204
	v_add_u32_e32 v156, s24, v204
	ds_read_b128 v[64:67], v76
	ds_read_b128 v[68:71], v76 offset:1024
	ds_read_b128 v[72:75], v76 offset:2048
	ds_read_b128 v[76:79], v76 offset:3072
	ds_read_b128 v[144:147], v156
	ds_read_b128 v[148:151], v156 offset:1024
	ds_read_b128 v[152:155], v156 offset:2048
	ds_read_b128 v[156:159], v156 offset:3072
	s_add_u32 s18, s18, 0x80000
	s_addc_u32 s19, s19, 0
	s_mov_b32 m0, s38
	v_lshl_add_u64 v[246:247], s[18:19], 0, v[190:191]
	ds_read_b128 v[160:163], v209 offset:32768
	ds_read_b128 v[164:167], v209 offset:33792
	ds_read_b128 v[196:199], v209 offset:34816
	ds_read_b128 v[200:203], v209 offset:35840
	ds_read_b128 v[210:213], v209 offset:36864
	ds_read_b128 v[230:233], v209 offset:37888
	ds_read_b128 v[234:237], v209 offset:38912
	ds_read_b128 v[238:241], v209 offset:39936
	global_load_lds_dwordx4 v[246:247], off
	v_lshl_add_u64 v[246:247], s[18:19], 0, v[186:187]
	s_mov_b32 m0, s39
	s_nop 0
	global_load_lds_dwordx4 v[246:247], off
	s_waitcnt vmcnt(8)
	s_waitcnt lgkmcnt(0)
	s_barrier
	v_mfma_f32_16x16x32_bf16 v[140:143], v[64:67], v[160:163], v[140:143]
	v_mfma_f32_16x16x32_bf16 v[136:139], v[72:75], v[160:163], v[136:139]
	v_mfma_f32_16x16x32_bf16 v[124:127], v[64:67], v[196:199], v[124:127]
	v_mfma_f32_16x16x32_bf16 v[120:123], v[72:75], v[196:199], v[120:123]
	v_mfma_f32_16x16x32_bf16 v[108:111], v[64:67], v[210:213], v[108:111]
	v_mfma_f32_16x16x32_bf16 v[104:107], v[72:75], v[210:213], v[104:107]
	v_mfma_f32_16x16x32_bf16 v[96:99], v[64:67], v[234:237], v[96:99]
	v_mfma_f32_16x16x32_bf16 v[88:91], v[72:75], v[234:237], v[88:91]
	v_mfma_f32_16x16x32_bf16 v[140:143], v[68:71], v[164:167], v[140:143]
	v_mfma_f32_16x16x32_bf16 v[136:139], v[76:79], v[164:167], v[136:139]
	v_mfma_f32_16x16x32_bf16 v[124:127], v[68:71], v[200:203], v[124:127]
	v_mfma_f32_16x16x32_bf16 v[120:123], v[76:79], v[200:203], v[120:123]
	v_mfma_f32_16x16x32_bf16 v[108:111], v[68:71], v[230:233], v[108:111]
	v_mfma_f32_16x16x32_bf16 v[104:107], v[76:79], v[230:233], v[104:107]
	v_mfma_f32_16x16x32_bf16 v[96:99], v[68:71], v[238:241], v[96:99]
	v_mfma_f32_16x16x32_bf16 v[88:91], v[76:79], v[238:241], v[88:91]
	v_mfma_f32_16x16x32_bf16 v[132:135], v[144:147], v[160:163], v[132:135]
	v_mfma_f32_16x16x32_bf16 v[128:131], v[152:155], v[160:163], v[128:131]
	v_mfma_f32_16x16x32_bf16 v[116:119], v[144:147], v[196:199], v[116:119]
	v_mfma_f32_16x16x32_bf16 v[112:115], v[152:155], v[196:199], v[112:115]
	v_mfma_f32_16x16x32_bf16 v[100:103], v[144:147], v[210:213], v[100:103]
	v_mfma_f32_16x16x32_bf16 v[92:95], v[152:155], v[210:213], v[92:95]
	v_mfma_f32_16x16x32_bf16 v[84:87], v[144:147], v[234:237], v[84:87]
	v_mfma_f32_16x16x32_bf16 v[80:83], v[152:155], v[234:237], v[80:83]
	v_mfma_f32_16x16x32_bf16 v[132:135], v[148:151], v[164:167], v[132:135]
	v_mfma_f32_16x16x32_bf16 v[128:131], v[156:159], v[164:167], v[128:131]
	v_mfma_f32_16x16x32_bf16 v[116:119], v[148:151], v[200:203], v[116:119]
	v_mfma_f32_16x16x32_bf16 v[112:115], v[156:159], v[200:203], v[112:115]
	v_mfma_f32_16x16x32_bf16 v[100:103], v[148:151], v[230:233], v[100:103]
	v_mfma_f32_16x16x32_bf16 v[92:95], v[156:159], v[230:233], v[92:95]
	v_mfma_f32_16x16x32_bf16 v[84:87], v[148:151], v[238:241], v[84:87]
	v_mfma_f32_16x16x32_bf16 v[80:83], v[156:159], v[238:241], v[80:83]
	s_barrier
; #define PG8_STAGE(bufoff, gbase, voff) do { _Pragma("unroll") for (int _i = 0; _i < 2; ++_i) \
;         __builtin_amdgcn_global_load_lds((const unsigned*)((const char*)(gbase) + (voff)[_i]), (LAS unsigned*)(lds + (bufoff) + ldsw + _i * 8192), 16, 0, 0); } while (0)
; #define PG8_LDA(dst, b, h) do { _Pragma("unroll") for (int m = 0; m < 4; ++m) _Pragma("unroll") for (int k = 0; k < 2; ++k) dst[m][k] = *(const LAS bf16x8*)(lds + PG8_SA(b, h) + aoff + m * 2048 + k * 1024); } while (0)
; #define PG8_MMA(ai, bj, At, Bt) do { __builtin_amdgcn_s_setprio(1); _Pragma("unroll") for (int m = 0; m < 4; ++m) _Pragma("unroll") for (int n = 0; n < 2; ++n) _Pragma("unroll") for (int k = 0; k < 2; ++k) \
;         acc[ai][bj][m][n] = __builtin_amdgcn_mfma_f32_16x16x32_bf16(Bt[n][k], At[m][k], acc[ai][bj][m][n], 0, 0, 0); __builtin_amdgcn_s_setprio(0); } while (0)
; #define PG8_WAIT_V(n) asm volatile("s_waitcnt vmcnt(" #n ")" ::: "memory")
; #define PG8_WAIT_L(n) asm volatile("s_waitcnt lgkmcnt(" #n ")" ::: "memory")
; #define PG8_BAR __builtin_amdgcn_s_barrier()
; #define PG8_SCHED __builtin_amdgcn_sched_barrier(0)
; template <class Epi>
; __device__ __forceinline__ void gemm_phase(LAS unsigned char* lds, const Gemm g, const StaticOrder& S, const Epi& E, const int tid) {
;     ...
;             PG8_LDA(At, 1, 1); PG8_STAGE(PG8_SB(1, 0), b3, voffB); PG8_STAGE(PG8_SB(1, 1), b3 + hsB, voffB); PG8_STAGE(PG8_SA(1, 0), a3, voffA);
;             PG8_WAIT_V(8); PG8_WAIT_L(0); PG8_BAR; PG8_MMA(1, 0, At, B0); PG8_MMA(1, 1, At, B1); PG8_BAR; PG8_SCHED;
;         }
;         if (wr == 0) PG8_BAR;
	s_add_i32 s2, s2, s35
	v_lshl_add_u64 v[170:171], v[170:171], 0, s[28:29]
	s_mov_b32 m0, s2
	ds_read_b128 v[160:163], v209 offset:49152
	ds_read_b128 v[164:167], v209 offset:50176
	ds_read_b128 v[196:199], v209 offset:51200
	ds_read_b128 v[200:203], v209 offset:52224
	ds_read_b128 v[210:213], v209 offset:53248
	ds_read_b128 v[230:233], v209 offset:54272
	ds_read_b128 v[234:237], v209 offset:55296
	ds_read_b128 v[238:241], v209 offset:56320
	global_load_lds_dwordx4 v[170:171], off
	s_add_i32 m0, s2, 0x2000
	s_add_u32 s0, s0, 0x80080
	v_lshl_add_u64 v[170:171], v[172:173], 0, s[28:29]
	s_addc_u32 s1, s1, 0
	s_add_i32 s2, s24, s35
	global_load_lds_dwordx4 v[170:171], off
	v_lshl_add_u64 v[170:171], s[0:1], 0, v[188:189]
	s_mov_b32 m0, s2
	s_nop 0
	global_load_lds_dwordx4 v[170:171], off
	v_lshl_add_u64 v[170:171], s[0:1], 0, v[184:185]
	s_add_i32 m0, s2, 0x2000
	s_nop 0
	global_load_lds_dwordx4 v[170:171], off
	v_lshl_add_u64 v[170:171], v[242:243], 0, s[28:29]
	s_mov_b32 m0, s44
	s_nop 0
	global_load_lds_dwordx4 v[170:171], off
	v_lshl_add_u64 v[170:171], v[244:245], 0, s[28:29]
	s_mov_b32 m0, s45
	s_nop 0
	global_load_lds_dwordx4 v[170:171], off
	s_waitcnt vmcnt(8)
	s_waitcnt lgkmcnt(0)
	s_barrier
	v_mfma_f32_16x16x32_bf16 v[60:63], v[64:67], v[160:163], v[60:63]
	v_mfma_f32_16x16x32_bf16 v[56:59], v[72:75], v[160:163], v[56:59]
	v_mfma_f32_16x16x32_bf16 v[44:47], v[64:67], v[196:199], v[44:47]
	v_mfma_f32_16x16x32_bf16 v[40:43], v[72:75], v[196:199], v[40:43]
	v_mfma_f32_16x16x32_bf16 v[28:31], v[64:67], v[210:213], v[28:31]
	v_mfma_f32_16x16x32_bf16 v[24:27], v[72:75], v[210:213], v[24:27]
	v_mfma_f32_16x16x32_bf16 v[12:15], v[64:67], v[234:237], v[12:15]
	v_mfma_f32_16x16x32_bf16 v[8:11], v[72:75], v[234:237], v[8:11]
	v_mfma_f32_16x16x32_bf16 v[60:63], v[68:71], v[164:167], v[60:63]
	v_mfma_f32_16x16x32_bf16 v[56:59], v[76:79], v[164:167], v[56:59]
	v_mfma_f32_16x16x32_bf16 v[44:47], v[68:71], v[200:203], v[44:47]
	v_mfma_f32_16x16x32_bf16 v[40:43], v[76:79], v[200:203], v[40:43]
	v_mfma_f32_16x16x32_bf16 v[28:31], v[68:71], v[230:233], v[28:31]
	v_mfma_f32_16x16x32_bf16 v[24:27], v[76:79], v[230:233], v[24:27]
	v_mfma_f32_16x16x32_bf16 v[12:15], v[68:71], v[238:241], v[12:15]
	v_mfma_f32_16x16x32_bf16 v[8:11], v[76:79], v[238:241], v[8:11]
	v_mfma_f32_16x16x32_bf16 v[52:55], v[144:147], v[160:163], v[52:55]
	v_mfma_f32_16x16x32_bf16 v[48:51], v[152:155], v[160:163], v[48:51]
	v_mfma_f32_16x16x32_bf16 v[36:39], v[144:147], v[196:199], v[36:39]
	v_mfma_f32_16x16x32_bf16 v[32:35], v[152:155], v[196:199], v[32:35]
	v_mfma_f32_16x16x32_bf16 v[20:23], v[144:147], v[210:213], v[20:23]
	v_mfma_f32_16x16x32_bf16 v[16:19], v[152:155], v[210:213], v[16:19]
	v_mfma_f32_16x16x32_bf16 v[4:7], v[144:147], v[234:237], v[4:7]
	v_mfma_f32_16x16x32_bf16 v[0:3], v[152:155], v[234:237], v[0:3]
	v_mfma_f32_16x16x32_bf16 v[52:55], v[148:151], v[164:167], v[52:55]
	v_mfma_f32_16x16x32_bf16 v[48:51], v[156:159], v[164:167], v[48:51]
	v_mfma_f32_16x16x32_bf16 v[36:39], v[148:151], v[200:203], v[36:39]
	v_mfma_f32_16x16x32_bf16 v[32:35], v[156:159], v[200:203], v[32:35]
	v_mfma_f32_16x16x32_bf16 v[20:23], v[148:151], v[230:233], v[20:23]
	v_mfma_f32_16x16x32_bf16 v[16:19], v[156:159], v[230:233], v[16:19]
	v_mfma_f32_16x16x32_bf16 v[4:7], v[148:151], v[238:241], v[4:7]
	v_mfma_f32_16x16x32_bf16 v[0:3], v[156:159], v[238:241], v[0:3]
	s_barrier
	s_add_i32 s57, s57, 2
	s_add_u32 s16, s16, 0x100
	s_addc_u32 s17, s17, 0
	s_add_u32 s53, s53, 0x100
	s_addc_u32 s56, s56, 0
	s_cmp_gt_u32 s57, 29
	s_cbranch_scc0 .LBB0_893
	s_and_b64 vcc, exec, s[6:7]
	s_movk_i32 s49, 0x300
	s_mov_b64 s[52:53], 0x60000
	s_cbranch_vccz .LBB0_896
	s_barrier

; #define PG8_STAGE(bufoff, gbase, voff) do { _Pragma("unroll") for (int _i = 0; _i < 2; ++_i) \
;         __builtin_amdgcn_global_load_lds((const unsigned*)((const char*)(gbase) + (voff)[_i]), (LAS unsigned*)(lds + (bufoff) + ldsw + _i * 8192), 16, 0, 0); } while (0)
; #define PG8_LDA(dst, b, h) do { _Pragma("unroll") for (int m = 0; m < 4; ++m) _Pragma("unroll") for (int k = 0; k < 2; ++k) dst[m][k] = *(const LAS bf16x8*)(lds + PG8_SA(b, h) + aoff + m * 2048 + k * 1024); } while (0)
; #define PG8_LDB(dst, b, h) do { _Pragma("unroll") for (int n = 0; n < 2; ++n) _Pragma("unroll") for (int k = 0; k < 2; ++k) dst[n][k] = *(const LAS bf16x8*)(lds + PG8_SB(b, h) + boff + n * 2048 + k * 1024); } while (0)
; #define PG8_MMA(ai, bj, At, Bt) do { __builtin_amdgcn_s_setprio(1); _Pragma("unroll") for (int m = 0; m < 4; ++m) _Pragma("unroll") for (int n = 0; n < 2; ++n) _Pragma("unroll") for (int k = 0; k < 2; ++k) \
;         acc[ai][bj][m][n] = __builtin_amdgcn_mfma_f32_16x16x32_bf16(Bt[n][k], At[m][k], acc[ai][bj][m][n], 0, 0, 0); __builtin_amdgcn_s_setprio(0); } while (0)
; #define PG8_WAIT_V(n) asm volatile("s_waitcnt vmcnt(" #n ")" ::: "memory")
; #define PG8_BAR __builtin_amdgcn_s_barrier()
; template <class Epi>
; __device__ __forceinline__ void gemm_phase(LAS unsigned char* lds, const Gemm g, const StaticOrder& S, const Epi& E, const int tid) {
;     ...
;         const bool has_next = S.next(ui + 1, nxt);
;         const char* nA = has_next ? PG8_APTR(nxt) : cA; const char* nB = has_next ? PG8_BPTR(nxt) : cB;
;         for (int t = 0; t < nt; t += 2) {
;             const bool last = (t == nt - 2);
;             const char* a1 = cA + (size_t)(t + 1) * kstep;
;             const char* a2 = last ? nA : cA + (size_t)(t + 2) * kstep; const char* b2 = last ? nB : cB + (size_t)(t + 2) * kstep;
;             const char* a3 = a2 + kstep; const char* b3 = b2 + kstep;
;             PG8_LDB(B0, 0, 0); PG8_LDB(B1, 0, 1); PG8_SCHED; PG8_LDA(At, 0, 0); PG8_STAGE(PG8_SA(1, 1), a1 + hsA, voffA);
;             PG8_WAIT_V(8); PG8_WAIT_L(0); PG8_BAR; PG8_MMA(0, 0, At, B0); PG8_MMA(0, 1, At, B1); PG8_BAR; PG8_SCHED;
;             PG8_LDA(At, 0, 1); PG8_STAGE(PG8_SB(0, 0), b2, voffB); PG8_STAGE(PG8_SB(0, 1), b2 + hsB, voffB); PG8_STAGE(PG8_SA(0, 0), a2, voffA);
;             PG8_WAIT_V(8); PG8_WAIT_L(0); PG8_BAR; PG8_MMA(1, 0, At, B0); PG8_MMA(1, 1, At, B1); PG8_BAR; PG8_SCHED;
.LBB0_1003:
	s_ashr_i32 s13, s12, 31
	s_lshl_b64 s[14:15], s[12:13], 20
	s_add_u32 s14, s58, s14
	s_addc_u32 s15, s59, s15
	s_and_b64 s[16:17], s[38:39], exec
	s_cselect_b32 s13, s15, s19
	s_cselect_b32 s49, s14, s18
	s_ashr_i32 s11, s10, 31
	s_lshl_b64 s[16:17], s[10:11], 20
	s_add_u32 s16, s36, s16
	s_addc_u32 s17, s37, s17
	s_and_b64 s[24:25], s[38:39], exec
	s_cselect_b32 s11, s17, s1
	s_cselect_b32 s52, s16, s0
	s_add_u32 s18, s18, 0x80080
	s_addc_u32 s19, s19, 0
	s_add_u32 s53, s0, 0x100
	s_addc_u32 s56, s1, 0
	s_mov_b32 s57, -2
	s_add_u32 s0, s18, 0xfff80080
	s_addc_u32 s1, s19, -1
	s_add_i32 s2, 0, 0x10000
	s_cmp_eq_u32 s57, 28
	s_cselect_b32 s35, s13, s1
	s_cselect_b32 s34, s49, s0
	s_cselect_b32 s1, s11, s56
	s_cselect_b32 s0, s52, s53
	s_add_i32 s55, 0, 0x14000
	v_add_u32_e32 v154, s2, v143
	v_add_u32_e32 v166, s55, v143
	ds_read_b128 v[138:141], v154
	ds_read_b128 v[146:149], v154 offset:1024
	ds_read_b128 v[150:153], v154 offset:2048
	ds_read_b128 v[154:157], v154 offset:3072
	ds_read_b128 v[158:161], v166
	ds_read_b128 v[162:165], v166 offset:1024
	ds_read_b128 v[184:187], v166 offset:2048
	ds_read_b128 v[188:191], v166 offset:3072
	v_lshl_add_u64 v[166:167], s[18:19], 0, v[134:135]
	s_add_i32 m0, s40, 0xc000
	ds_read_b128 v[192:195], v145
	ds_read_b128 v[196:199], v145 offset:1024
	ds_read_b128 v[200:203], v145 offset:2048
	ds_read_b128 v[204:207], v145 offset:3072
	ds_read_b128 v[208:211], v145 offset:4096
	ds_read_b128 v[230:233], v145 offset:5120
	ds_read_b128 v[234:237], v145 offset:6144
	ds_read_b128 v[238:241], v145 offset:7168
	global_load_lds_dwordx4 v[166:167], off
	v_lshl_add_u64 v[166:167], s[18:19], 0, v[136:137]
	s_add_i32 m0, s40, 0xe000
	s_nop 0
	global_load_lds_dwordx4 v[166:167], off
	s_waitcnt vmcnt(8)
	s_waitcnt lgkmcnt(0)
	s_barrier
	v_mfma_f32_16x16x32_bf16 v[124:127], v[138:141], v[192:195], 0
	v_mfma_f32_16x16x32_bf16 v[116:119], v[150:153], v[192:195], 0
	v_mfma_f32_16x16x32_bf16 v[108:111], v[138:141], v[200:203], 0
	v_mfma_f32_16x16x32_bf16 v[100:103], v[150:153], v[200:203], 0
	v_mfma_f32_16x16x32_bf16 v[92:95], v[138:141], v[208:211], 0
	v_mfma_f32_16x16x32_bf16 v[84:87], v[150:153], v[208:211], 0
	v_mfma_f32_16x16x32_bf16 v[76:79], v[138:141], v[234:237], 0
	v_mfma_f32_16x16x32_bf16 v[68:71], v[150:153], v[234:237], 0
	v_mfma_f32_16x16x32_bf16 v[124:127], v[146:149], v[196:199], v[124:127]
	v_mfma_f32_16x16x32_bf16 v[116:119], v[154:157], v[196:199], v[116:119]
	v_mfma_f32_16x16x32_bf16 v[108:111], v[146:149], v[204:207], v[108:111]
	v_mfma_f32_16x16x32_bf16 v[100:103], v[154:157], v[204:207], v[100:103]
	v_mfma_f32_16x16x32_bf16 v[92:95], v[146:149], v[230:233], v[92:95]
	v_mfma_f32_16x16x32_bf16 v[84:87], v[154:157], v[230:233], v[84:87]
	v_mfma_f32_16x16x32_bf16 v[76:79], v[146:149], v[238:241], v[76:79]
	v_mfma_f32_16x16x32_bf16 v[68:71], v[154:157], v[238:241], v[68:71]
	v_mfma_f32_16x16x32_bf16 v[120:123], v[158:161], v[192:195], 0
	v_mfma_f32_16x16x32_bf16 v[112:115], v[184:187], v[192:195], 0
	v_mfma_f32_16x16x32_bf16 v[104:107], v[158:161], v[200:203], 0
	v_mfma_f32_16x16x32_bf16 v[96:99], v[184:187], v[200:203], 0
	v_mfma_f32_16x16x32_bf16 v[88:91], v[158:161], v[208:211], 0
	v_mfma_f32_16x16x32_bf16 v[80:83], v[184:187], v[208:211], 0
	v_mfma_f32_16x16x32_bf16 v[72:75], v[158:161], v[234:237], 0
	v_mfma_f32_16x16x32_bf16 v[64:67], v[184:187], v[234:237], 0
	v_mfma_f32_16x16x32_bf16 v[120:123], v[162:165], v[196:199], v[120:123]
	v_mfma_f32_16x16x32_bf16 v[112:115], v[188:191], v[196:199], v[112:115]
	v_mfma_f32_16x16x32_bf16 v[104:107], v[162:165], v[204:207], v[104:107]
	v_mfma_f32_16x16x32_bf16 v[96:99], v[188:191], v[204:207], v[96:99]
	v_mfma_f32_16x16x32_bf16 v[88:91], v[162:165], v[230:233], v[88:91]
	v_mfma_f32_16x16x32_bf16 v[80:83], v[188:191], v[230:233], v[80:83]
	v_mfma_f32_16x16x32_bf16 v[72:75], v[162:165], v[238:241], v[72:75]
	v_mfma_f32_16x16x32_bf16 v[64:67], v[188:191], v[238:241], v[64:67]
	s_barrier
	s_add_i32 s2, s2, s27
	v_lshl_add_u64 v[166:167], s[0:1], 0, v[168:169]
	s_mov_b32 m0, s2
	ds_read_b128 v[192:195], v145 offset:16384
	ds_read_b128 v[196:199], v145 offset:17408
	ds_read_b128 v[200:203], v145 offset:18432
	ds_read_b128 v[204:207], v145 offset:19456
	ds_read_b128 v[208:211], v145 offset:20480
	ds_read_b128 v[230:233], v145 offset:21504
	ds_read_b128 v[234:237], v145 offset:22528
	ds_read_b128 v[238:241], v145 offset:23552
	global_load_lds_dwordx4 v[166:167], off
	s_add_i32 m0, s2, 0x2000
	s_add_u32 s24, s0, 0x80000
	v_lshl_add_u64 v[170:171], s[0:1], 0, v[132:133]
	s_addc_u32 s25, s1, 0
	s_add_i32 s2, s55, s27
	global_load_lds_dwordx4 v[170:171], off
	v_lshl_add_u64 v[172:173], s[24:25], 0, v[168:169]
	s_mov_b32 m0, s2
	v_lshl_add_u64 v[212:213], s[34:35], 0, v[130:131]
	global_load_lds_dwordx4 v[172:173], off
	v_lshl_add_u64 v[172:173], s[24:25], 0, v[132:133]
	s_add_i32 m0, s2, 0x2000
	s_nop 0
	global_load_lds_dwordx4 v[172:173], off
	v_lshl_add_u64 v[172:173], s[34:35], 0, v[128:129]
	s_mov_b32 m0, s40
	s_nop 0
	global_load_lds_dwordx4 v[172:173], off
	s_mov_b32 m0, s41
	s_nop 0
	global_load_lds_dwordx4 v[212:213], off
	s_waitcnt vmcnt(8)
	s_waitcnt lgkmcnt(0)
	s_barrier
; #define PG8_STAGE(bufoff, gbase, voff) do { _Pragma("unroll") for (int _i = 0; _i < 2; ++_i) \
;         __builtin_amdgcn_global_load_lds((const unsigned*)((const char*)(gbase) + (voff)[_i]), (LAS unsigned*)(lds + (bufoff) + ldsw + _i * 8192), 16, 0, 0); } while (0)
; #define PG8_LDA(dst, b, h) do { _Pragma("unroll") for (int m = 0; m < 4; ++m) _Pragma("unroll") for (int k = 0; k < 2; ++k) dst[m][k] = *(const LAS bf16x8*)(lds + PG8_SA(b, h) + aoff + m * 2048 + k * 1024); } while (0)
; #define PG8_LDB(dst, b, h) do { _Pragma("unroll") for (int n = 0; n < 2; ++n) _Pragma("unroll") for (int k = 0; k < 2; ++k) dst[n][k] = *(const LAS bf16x8*)(lds + PG8_SB(b, h) + boff + n * 2048 + k * 1024); } while (0)
; #define PG8_MMA(ai, bj, At, Bt) do { __builtin_amdgcn_s_setprio(1); _Pragma("unroll") for (int m = 0; m < 4; ++m) _Pragma("unroll") for (int n = 0; n < 2; ++n) _Pragma("unroll") for (int k = 0; k < 2; ++k) \
;         acc[ai][bj][m][n] = __builtin_amdgcn_mfma_f32_16x16x32_bf16(Bt[n][k], At[m][k], acc[ai][bj][m][n], 0, 0, 0); __builtin_amdgcn_s_setprio(0); } while (0)
; #define PG8_WAIT_V(n) asm volatile("s_waitcnt vmcnt(" #n ")" ::: "memory")
; #define PG8_WAIT_L(n) asm volatile("s_waitcnt lgkmcnt(" #n ")" ::: "memory")
; #define PG8_BAR __builtin_amdgcn_s_barrier()
; #define PG8_SCHED __builtin_amdgcn_sched_barrier(0)
; template <class Epi>
; __device__ __forceinline__ void gemm_phase(LAS unsigned char* lds, const Gemm g, const StaticOrder& S, const Epi& E, const int tid) {
;     ...
;             PG8_WAIT_V(8); PG8_WAIT_L(0); PG8_BAR; PG8_MMA(1, 0, At, B0); PG8_MMA(1, 1, At, B1); PG8_BAR; PG8_SCHED;
;             PG8_LDB(B0, 1, 0); PG8_LDB(B1, 1, 1); PG8_SCHED; PG8_LDA(At, 1, 0); PG8_STAGE(PG8_SA(0, 1), a2 + hsA, voffA);
;             PG8_WAIT_V(8); PG8_WAIT_L(0); PG8_BAR; PG8_MMA(0, 0, At, B0); PG8_MMA(0, 1, At, B1); PG8_BAR; PG8_SCHED;
	v_mfma_f32_16x16x32_bf16 v[60:63], v[138:141], v[192:195], 0
	v_mfma_f32_16x16x32_bf16 v[52:55], v[150:153], v[192:195], 0
	v_mfma_f32_16x16x32_bf16 v[44:47], v[138:141], v[200:203], 0
	v_mfma_f32_16x16x32_bf16 v[36:39], v[150:153], v[200:203], 0
	v_mfma_f32_16x16x32_bf16 v[28:31], v[138:141], v[208:211], 0
	v_mfma_f32_16x16x32_bf16 v[20:23], v[150:153], v[208:211], 0
	v_mfma_f32_16x16x32_bf16 v[12:15], v[138:141], v[234:237], 0
	v_mfma_f32_16x16x32_bf16 v[4:7], v[150:153], v[234:237], 0
	v_mfma_f32_16x16x32_bf16 v[60:63], v[146:149], v[196:199], v[60:63]
	v_mfma_f32_16x16x32_bf16 v[52:55], v[154:157], v[196:199], v[52:55]
	v_mfma_f32_16x16x32_bf16 v[44:47], v[146:149], v[204:207], v[44:47]
	v_mfma_f32_16x16x32_bf16 v[36:39], v[154:157], v[204:207], v[36:39]
	v_mfma_f32_16x16x32_bf16 v[28:31], v[146:149], v[230:233], v[28:31]
	v_mfma_f32_16x16x32_bf16 v[20:23], v[154:157], v[230:233], v[20:23]
	v_mfma_f32_16x16x32_bf16 v[12:15], v[146:149], v[238:241], v[12:15]
	v_mfma_f32_16x16x32_bf16 v[4:7], v[154:157], v[238:241], v[4:7]
	v_mfma_f32_16x16x32_bf16 v[56:59], v[158:161], v[192:195], 0
	v_mfma_f32_16x16x32_bf16 v[48:51], v[184:187], v[192:195], 0
	v_mfma_f32_16x16x32_bf16 v[40:43], v[158:161], v[200:203], 0
	v_mfma_f32_16x16x32_bf16 v[32:35], v[184:187], v[200:203], 0
	v_mfma_f32_16x16x32_bf16 v[24:27], v[158:161], v[208:211], 0
	v_mfma_f32_16x16x32_bf16 v[16:19], v[184:187], v[208:211], 0
	v_mfma_f32_16x16x32_bf16 v[8:11], v[158:161], v[234:237], 0
	v_mfma_f32_16x16x32_bf16 v[0:3], v[184:187], v[234:237], 0
	v_mfma_f32_16x16x32_bf16 v[56:59], v[162:165], v[196:199], v[56:59]
	v_mfma_f32_16x16x32_bf16 v[48:51], v[188:191], v[196:199], v[48:51]
	v_mfma_f32_16x16x32_bf16 v[40:43], v[162:165], v[204:207], v[40:43]
	v_mfma_f32_16x16x32_bf16 v[32:35], v[188:191], v[204:207], v[32:35]
	v_mfma_f32_16x16x32_bf16 v[24:27], v[162:165], v[230:233], v[24:27]
	v_mfma_f32_16x16x32_bf16 v[16:19], v[188:191], v[230:233], v[16:19]
	v_mfma_f32_16x16x32_bf16 v[8:11], v[162:165], v[238:241], v[8:11]
	v_mfma_f32_16x16x32_bf16 v[0:3], v[188:191], v[238:241], v[0:3]
	s_barrier
	s_add_i32 s2, 0, 0x18000
	s_add_i32 s55, 0, 0x1c000
	v_add_u32_e32 v154, s2, v143
	v_add_u32_e32 v188, s55, v143
	ds_read_b128 v[138:141], v154
	ds_read_b128 v[146:149], v154 offset:1024
	ds_read_b128 v[150:153], v154 offset:2048
	ds_read_b128 v[154:157], v154 offset:3072
	ds_read_b128 v[158:161], v188
	ds_read_b128 v[162:165], v188 offset:1024
	ds_read_b128 v[184:187], v188 offset:2048
	ds_read_b128 v[188:191], v188 offset:3072
	s_add_u32 s24, s34, 0x80000
	s_addc_u32 s25, s35, 0
	s_mov_b32 m0, s42
	v_lshl_add_u64 v[242:243], s[24:25], 0, v[128:129]
	ds_read_b128 v[192:195], v145 offset:32768
	ds_read_b128 v[196:199], v145 offset:33792
	ds_read_b128 v[200:203], v145 offset:34816
	ds_read_b128 v[204:207], v145 offset:35840
	ds_read_b128 v[208:211], v145 offset:36864
	ds_read_b128 v[230:233], v145 offset:37888
	ds_read_b128 v[234:237], v145 offset:38912
	ds_read_b128 v[238:241], v145 offset:39936
	global_load_lds_dwordx4 v[242:243], off
	v_lshl_add_u64 v[242:243], s[24:25], 0, v[130:131]
	s_mov_b32 m0, s43
	s_nop 0
	global_load_lds_dwordx4 v[242:243], off
	s_waitcnt vmcnt(8)
	s_waitcnt lgkmcnt(0)
	s_barrier
	v_mfma_f32_16x16x32_bf16 v[124:127], v[138:141], v[192:195], v[124:127]
	v_mfma_f32_16x16x32_bf16 v[116:119], v[150:153], v[192:195], v[116:119]
	v_mfma_f32_16x16x32_bf16 v[108:111], v[138:141], v[200:203], v[108:111]
	v_mfma_f32_16x16x32_bf16 v[100:103], v[150:153], v[200:203], v[100:103]
	v_mfma_f32_16x16x32_bf16 v[92:95], v[138:141], v[208:211], v[92:95]
	v_mfma_f32_16x16x32_bf16 v[84:87], v[150:153], v[208:211], v[84:87]
	v_mfma_f32_16x16x32_bf16 v[76:79], v[138:141], v[234:237], v[76:79]
	v_mfma_f32_16x16x32_bf16 v[68:71], v[150:153], v[234:237], v[68:71]
	v_mfma_f32_16x16x32_bf16 v[124:127], v[146:149], v[196:199], v[124:127]
	v_mfma_f32_16x16x32_bf16 v[116:119], v[154:157], v[196:199], v[116:119]
	v_mfma_f32_16x16x32_bf16 v[108:111], v[146:149], v[204:207], v[108:111]
	v_mfma_f32_16x16x32_bf16 v[100:103], v[154:157], v[204:207], v[100:103]
	v_mfma_f32_16x16x32_bf16 v[92:95], v[146:149], v[230:233], v[92:95]
	v_mfma_f32_16x16x32_bf16 v[84:87], v[154:157], v[230:233], v[84:87]
	v_mfma_f32_16x16x32_bf16 v[76:79], v[146:149], v[238:241], v[76:79]
	v_mfma_f32_16x16x32_bf16 v[68:71], v[154:157], v[238:241], v[68:71]
	v_mfma_f32_16x16x32_bf16 v[120:123], v[158:161], v[192:195], v[120:123]
	v_mfma_f32_16x16x32_bf16 v[112:115], v[184:187], v[192:195], v[112:115]
	v_mfma_f32_16x16x32_bf16 v[104:107], v[158:161], v[200:203], v[104:107]
	v_mfma_f32_16x16x32_bf16 v[96:99], v[184:187], v[200:203], v[96:99]
	v_mfma_f32_16x16x32_bf16 v[88:91], v[158:161], v[208:211], v[88:91]
	v_mfma_f32_16x16x32_bf16 v[80:83], v[184:187], v[208:211], v[80:83]
	v_mfma_f32_16x16x32_bf16 v[72:75], v[158:161], v[234:237], v[72:75]
	v_mfma_f32_16x16x32_bf16 v[64:67], v[184:187], v[234:237], v[64:67]
	v_mfma_f32_16x16x32_bf16 v[120:123], v[162:165], v[196:199], v[120:123]
	v_mfma_f32_16x16x32_bf16 v[112:115], v[188:191], v[196:199], v[112:115]
	v_mfma_f32_16x16x32_bf16 v[104:107], v[162:165], v[204:207], v[104:107]
	v_mfma_f32_16x16x32_bf16 v[96:99], v[188:191], v[204:207], v[96:99]
	v_mfma_f32_16x16x32_bf16 v[88:91], v[162:165], v[230:233], v[88:91]
	v_mfma_f32_16x16x32_bf16 v[80:83], v[188:191], v[230:233], v[80:83]
	v_mfma_f32_16x16x32_bf16 v[72:75], v[162:165], v[238:241], v[72:75]
	v_mfma_f32_16x16x32_bf16 v[64:67], v[188:191], v[238:241], v[64:67]
	s_barrier
; #define PG8_STAGE(bufoff, gbase, voff) do { _Pragma("unroll") for (int _i = 0; _i < 2; ++_i) \
;         __builtin_amdgcn_global_load_lds((const unsigned*)((const char*)(gbase) + (voff)[_i]), (LAS unsigned*)(lds + (bufoff) + ldsw + _i * 8192), 16, 0, 0); } while (0)
; #define PG8_LDA(dst, b, h) do { _Pragma("unroll") for (int m = 0; m < 4; ++m) _Pragma("unroll") for (int k = 0; k < 2; ++k) dst[m][k] = *(const LAS bf16x8*)(lds + PG8_SA(b, h) + aoff + m * 2048 + k * 1024); } while (0)
; #define PG8_MMA(ai, bj, At, Bt) do { __builtin_amdgcn_s_setprio(1); _Pragma("unroll") for (int m = 0; m < 4; ++m) _Pragma("unroll") for (int n = 0; n < 2; ++n) _Pragma("unroll") for (int k = 0; k < 2; ++k) \
;         acc[ai][bj][m][n] = __builtin_amdgcn_mfma_f32_16x16x32_bf16(Bt[n][k], At[m][k], acc[ai][bj][m][n], 0, 0, 0); __builtin_amdgcn_s_setprio(0); } while (0)
; #define PG8_WAIT_V(n) asm volatile("s_waitcnt vmcnt(" #n ")" ::: "memory")
; #define PG8_WAIT_L(n) asm volatile("s_waitcnt lgkmcnt(" #n ")" ::: "memory")
; #define PG8_BAR __builtin_amdgcn_s_barrier()
; #define PG8_SCHED __builtin_amdgcn_sched_barrier(0)
; template <class Epi>
; __device__ __forceinline__ void gemm_phase(LAS unsigned char* lds, const Gemm g, const StaticOrder& S, const Epi& E, const int tid) {
;     ...
;             PG8_WAIT_V(8); PG8_WAIT_L(0); PG8_BAR; PG8_MMA(0, 0, At, B0); PG8_MMA(0, 1, At, B1); PG8_BAR; PG8_SCHED;
;             PG8_LDA(At, 1, 1); PG8_STAGE(PG8_SB(1, 0), b3, voffB); PG8_STAGE(PG8_SB(1, 1), b3 + hsB, voffB); PG8_STAGE(PG8_SA(1, 0), a3, voffA);
;             PG8_WAIT_V(8); PG8_WAIT_L(0); PG8_BAR; PG8_MMA(1, 0, At, B0); PG8_MMA(1, 1, At, B1); PG8_BAR; PG8_SCHED;
	s_add_i32 s2, s2, s27
	v_lshl_add_u64 v[166:167], v[166:167], 0, s[28:29]
	s_mov_b32 m0, s2
	ds_read_b128 v[192:195], v145 offset:49152
	ds_read_b128 v[196:199], v145 offset:50176
	ds_read_b128 v[200:203], v145 offset:51200
	ds_read_b128 v[204:207], v145 offset:52224
	ds_read_b128 v[208:211], v145 offset:53248
	ds_read_b128 v[230:233], v145 offset:54272
	ds_read_b128 v[234:237], v145 offset:55296
	ds_read_b128 v[238:241], v145 offset:56320
	global_load_lds_dwordx4 v[166:167], off
	s_add_i32 m0, s2, 0x2000
	s_add_u32 s0, s0, 0x80080
	v_lshl_add_u64 v[166:167], v[170:171], 0, s[28:29]
	s_addc_u32 s1, s1, 0
	s_add_i32 s2, s55, s27
	global_load_lds_dwordx4 v[166:167], off
	v_lshl_add_u64 v[166:167], s[0:1], 0, v[168:169]
	s_mov_b32 m0, s2
	s_nop 0
	global_load_lds_dwordx4 v[166:167], off
	v_lshl_add_u64 v[166:167], s[0:1], 0, v[132:133]
	s_add_i32 m0, s2, 0x2000
	s_nop 0
	global_load_lds_dwordx4 v[166:167], off
	v_lshl_add_u64 v[166:167], v[172:173], 0, s[28:29]
	s_mov_b32 m0, s44
	s_nop 0
	global_load_lds_dwordx4 v[166:167], off
	v_lshl_add_u64 v[166:167], v[212:213], 0, s[28:29]
	s_mov_b32 m0, s45
	s_nop 0
	global_load_lds_dwordx4 v[166:167], off
	s_waitcnt vmcnt(8)
	s_waitcnt lgkmcnt(0)
	s_barrier
	v_mfma_f32_16x16x32_bf16 v[60:63], v[138:141], v[192:195], v[60:63]
	v_mfma_f32_16x16x32_bf16 v[52:55], v[150:153], v[192:195], v[52:55]
	v_mfma_f32_16x16x32_bf16 v[44:47], v[138:141], v[200:203], v[44:47]
	v_mfma_f32_16x16x32_bf16 v[36:39], v[150:153], v[200:203], v[36:39]
	v_mfma_f32_16x16x32_bf16 v[28:31], v[138:141], v[208:211], v[28:31]
	v_mfma_f32_16x16x32_bf16 v[20:23], v[150:153], v[208:211], v[20:23]
	v_mfma_f32_16x16x32_bf16 v[12:15], v[138:141], v[234:237], v[12:15]
	v_mfma_f32_16x16x32_bf16 v[4:7], v[150:153], v[234:237], v[4:7]
	v_mfma_f32_16x16x32_bf16 v[60:63], v[146:149], v[196:199], v[60:63]
	v_mfma_f32_16x16x32_bf16 v[52:55], v[154:157], v[196:199], v[52:55]
	v_mfma_f32_16x16x32_bf16 v[44:47], v[146:149], v[204:207], v[44:47]
	v_mfma_f32_16x16x32_bf16 v[36:39], v[154:157], v[204:207], v[36:39]
	v_mfma_f32_16x16x32_bf16 v[28:31], v[146:149], v[230:233], v[28:31]
	v_mfma_f32_16x16x32_bf16 v[20:23], v[154:157], v[230:233], v[20:23]
	v_mfma_f32_16x16x32_bf16 v[12:15], v[146:149], v[238:241], v[12:15]
	v_mfma_f32_16x16x32_bf16 v[4:7], v[154:157], v[238:241], v[4:7]
	v_mfma_f32_16x16x32_bf16 v[56:59], v[158:161], v[192:195], v[56:59]
	v_mfma_f32_16x16x32_bf16 v[48:51], v[184:187], v[192:195], v[48:51]
	v_mfma_f32_16x16x32_bf16 v[40:43], v[158:161], v[200:203], v[40:43]
	v_mfma_f32_16x16x32_bf16 v[32:35], v[184:187], v[200:203], v[32:35]
	v_mfma_f32_16x16x32_bf16 v[24:27], v[158:161], v[208:211], v[24:27]
	v_mfma_f32_16x16x32_bf16 v[16:19], v[184:187], v[208:211], v[16:19]
	v_mfma_f32_16x16x32_bf16 v[8:11], v[158:161], v[234:237], v[8:11]
	v_mfma_f32_16x16x32_bf16 v[0:3], v[184:187], v[234:237], v[0:3]
	v_mfma_f32_16x16x32_bf16 v[56:59], v[162:165], v[196:199], v[56:59]
	v_mfma_f32_16x16x32_bf16 v[48:51], v[188:191], v[196:199], v[48:51]
	v_mfma_f32_16x16x32_bf16 v[40:43], v[162:165], v[204:207], v[40:43]
	v_mfma_f32_16x16x32_bf16 v[32:35], v[188:191], v[204:207], v[32:35]
	v_mfma_f32_16x16x32_bf16 v[24:27], v[162:165], v[230:233], v[24:27]
	v_mfma_f32_16x16x32_bf16 v[16:19], v[188:191], v[230:233], v[16:19]
	v_mfma_f32_16x16x32_bf16 v[8:11], v[162:165], v[238:241], v[8:11]
	v_mfma_f32_16x16x32_bf16 v[0:3], v[188:191], v[238:241], v[0:3]
	s_barrier
	s_add_i32 s57, s57, 2
	s_add_u32 s18, s18, 0x100
	s_addc_u32 s19, s19, 0
	s_add_u32 s53, s53, 0x100
	s_addc_u32 s56, s56, 0
	s_cmp_gt_u32 s57, 29

; #define PG8_STAGE(bufoff, gbase, voff) do { _Pragma("unroll") for (int _i = 0; _i < 2; ++_i) \
;         __builtin_amdgcn_global_load_lds((const unsigned*)((const char*)(gbase) + (voff)[_i]), (LAS unsigned*)(lds + (bufoff) + ldsw + _i * 8192), 16, 0, 0); } while (0)
; #define PG8_LDA(dst, b, h) do { _Pragma("unroll") for (int m = 0; m < 4; ++m) _Pragma("unroll") for (int k = 0; k < 2; ++k) dst[m][k] = *(const LAS bf16x8*)(lds + PG8_SA(b, h) + aoff + m * 2048 + k * 1024); } while (0)
; #define PG8_LDB(dst, b, h) do { _Pragma("unroll") for (int n = 0; n < 2; ++n) _Pragma("unroll") for (int k = 0; k < 2; ++k) dst[n][k] = *(const LAS bf16x8*)(lds + PG8_SB(b, h) + boff + n * 2048 + k * 1024); } while (0)
; #define PG8_MMA(ai, bj, At, Bt) do { __builtin_amdgcn_s_setprio(1); _Pragma("unroll") for (int m = 0; m < 4; ++m) _Pragma("unroll") for (int n = 0; n < 2; ++n) _Pragma("unroll") for (int k = 0; k < 2; ++k) \
;         acc[ai][bj][m][n] = __builtin_amdgcn_mfma_f32_16x16x32_bf16(Bt[n][k], At[m][k], acc[ai][bj][m][n], 0, 0, 0); __builtin_amdgcn_s_setprio(0); } while (0)
; #define PG8_WAIT_V(n) asm volatile("s_waitcnt vmcnt(" #n ")" ::: "memory")
; #define PG8_BAR __builtin_amdgcn_s_barrier()
; template <class Epi>
; __device__ __forceinline__ void gemm_phase(LAS unsigned char* lds, const Gemm g, const StaticOrder& S, const Epi& E, const int tid) {
;     ...
;         const bool has_next = S.next(ui + 1, nxt);
;         const char* nA = has_next ? PG8_APTR(nxt) : cA; const char* nB = has_next ? PG8_BPTR(nxt) : cB;
;         for (int t = 0; t < nt; t += 2) {
;             const bool last = (t == nt - 2);
;             const char* a1 = cA + (size_t)(t + 1) * kstep;
;             const char* a2 = last ? nA : cA + (size_t)(t + 2) * kstep; const char* b2 = last ? nB : cB + (size_t)(t + 2) * kstep;
;             const char* a3 = a2 + kstep; const char* b3 = b2 + kstep;
;             PG8_LDB(B0, 0, 0); PG8_LDB(B1, 0, 1); PG8_SCHED; PG8_LDA(At, 0, 0); PG8_STAGE(PG8_SA(1, 1), a1 + hsA, voffA);
;             PG8_WAIT_V(8); PG8_WAIT_L(0); PG8_BAR; PG8_MMA(0, 0, At, B0); PG8_MMA(0, 1, At, B1); PG8_BAR; PG8_SCHED;
;             PG8_LDA(At, 0, 1); PG8_STAGE(PG8_SB(0, 0), b2, voffB); PG8_STAGE(PG8_SB(0, 1), b2 + hsB, voffB); PG8_STAGE(PG8_SA(0, 0), a2, voffA);
;             PG8_WAIT_V(8); PG8_WAIT_L(0); PG8_BAR; PG8_MMA(1, 0, At, B0); PG8_MMA(1, 1, At, B1); PG8_BAR; PG8_SCHED;
.LBB0_1075:
	s_add_u32 s38, s0, 0x100
	s_addc_u32 s39, s1, 0
	s_mov_b32 s53, -2
	s_add_u32 s0, s12, 0x100
	s_addc_u32 s1, s13, 0
	s_add_i32 s2, 0, 0x10000
	s_cmpk_eq_i32 s53, 0x54
	s_cselect_b32 s17, s9, s1
	s_cselect_b32 s16, s8, s0
	s_cselect_b32 s15, s11, s39
	s_cselect_b32 s14, s10, s38
	s_add_i32 s24, 0, 0x14000
	v_add_u32_e32 v152, s2, v184
	v_add_u32_e32 v170, s24, v184
	ds_read_b128 v[128:131], v152
	ds_read_b128 v[144:147], v152 offset:1024
	ds_read_b128 v[148:151], v152 offset:2048
	ds_read_b128 v[152:155], v152 offset:3072
	ds_read_b128 v[156:159], v170
	ds_read_b128 v[160:163], v170 offset:1024
	ds_read_b128 v[164:167], v170 offset:2048
	ds_read_b128 v[190:193], v170 offset:3072
	v_lshl_add_u64 v[170:171], s[12:13], 0, v[140:141]
	s_add_i32 m0, s34, 0xc000
	ds_read_b128 v[194:197], v189
	ds_read_b128 v[198:201], v189 offset:1024
	ds_read_b128 v[202:205], v189 offset:2048
	ds_read_b128 v[206:209], v189 offset:3072
	ds_read_b128 v[210:213], v189 offset:4096
	ds_read_b128 v[230:233], v189 offset:5120
	ds_read_b128 v[234:237], v189 offset:6144
	ds_read_b128 v[238:241], v189 offset:7168
	global_load_lds_dwordx4 v[170:171], off
	v_lshl_add_u64 v[170:171], s[12:13], 0, v[142:143]
	s_add_i32 m0, s34, 0xe000
	s_nop 0
	global_load_lds_dwordx4 v[170:171], off
	s_waitcnt vmcnt(8)
	s_waitcnt lgkmcnt(0)
	s_barrier
	v_mfma_f32_16x16x32_bf16 v[124:127], v[128:131], v[194:197], 0
	v_mfma_f32_16x16x32_bf16 v[120:123], v[148:151], v[194:197], 0
	v_mfma_f32_16x16x32_bf16 v[108:111], v[128:131], v[202:205], 0
	v_mfma_f32_16x16x32_bf16 v[104:107], v[148:151], v[202:205], 0
	v_mfma_f32_16x16x32_bf16 v[92:95], v[128:131], v[210:213], 0
	v_mfma_f32_16x16x32_bf16 v[88:91], v[148:151], v[210:213], 0
	v_mfma_f32_16x16x32_bf16 v[80:83], v[128:131], v[234:237], 0
	v_mfma_f32_16x16x32_bf16 v[72:75], v[148:151], v[234:237], 0
	v_mfma_f32_16x16x32_bf16 v[124:127], v[144:147], v[198:201], v[124:127]
	v_mfma_f32_16x16x32_bf16 v[120:123], v[152:155], v[198:201], v[120:123]
	v_mfma_f32_16x16x32_bf16 v[108:111], v[144:147], v[206:209], v[108:111]
	v_mfma_f32_16x16x32_bf16 v[104:107], v[152:155], v[206:209], v[104:107]
	v_mfma_f32_16x16x32_bf16 v[92:95], v[144:147], v[230:233], v[92:95]
	v_mfma_f32_16x16x32_bf16 v[88:91], v[152:155], v[230:233], v[88:91]
	v_mfma_f32_16x16x32_bf16 v[80:83], v[144:147], v[238:241], v[80:83]
	v_mfma_f32_16x16x32_bf16 v[72:75], v[152:155], v[238:241], v[72:75]
	v_mfma_f32_16x16x32_bf16 v[116:119], v[156:159], v[194:197], 0
	v_mfma_f32_16x16x32_bf16 v[112:115], v[164:167], v[194:197], 0
	v_mfma_f32_16x16x32_bf16 v[100:103], v[156:159], v[202:205], 0
	v_mfma_f32_16x16x32_bf16 v[96:99], v[164:167], v[202:205], 0
	v_mfma_f32_16x16x32_bf16 v[84:87], v[156:159], v[210:213], 0
	v_mfma_f32_16x16x32_bf16 v[76:79], v[164:167], v[210:213], 0
	v_mfma_f32_16x16x32_bf16 v[68:71], v[156:159], v[234:237], 0
	v_mfma_f32_16x16x32_bf16 v[64:67], v[164:167], v[234:237], 0
	v_mfma_f32_16x16x32_bf16 v[116:119], v[160:163], v[198:201], v[116:119]
	v_mfma_f32_16x16x32_bf16 v[112:115], v[190:193], v[198:201], v[112:115]
	v_mfma_f32_16x16x32_bf16 v[100:103], v[160:163], v[206:209], v[100:103]
	v_mfma_f32_16x16x32_bf16 v[96:99], v[190:193], v[206:209], v[96:99]
	v_mfma_f32_16x16x32_bf16 v[84:87], v[160:163], v[230:233], v[84:87]
	v_mfma_f32_16x16x32_bf16 v[76:79], v[190:193], v[230:233], v[76:79]
	v_mfma_f32_16x16x32_bf16 v[68:71], v[160:163], v[238:241], v[68:71]
	v_mfma_f32_16x16x32_bf16 v[64:67], v[190:193], v[238:241], v[64:67]
	s_barrier
	s_add_i32 s2, s2, s27
	v_lshl_add_u64 v[170:171], s[14:15], 0, v[136:137]
	s_mov_b32 m0, s2
	ds_read_b128 v[194:197], v189 offset:16384
	ds_read_b128 v[198:201], v189 offset:17408
	ds_read_b128 v[202:205], v189 offset:18432
	ds_read_b128 v[206:209], v189 offset:19456
	ds_read_b128 v[210:213], v189 offset:20480
	ds_read_b128 v[230:233], v189 offset:21504
	ds_read_b128 v[234:237], v189 offset:22528
	ds_read_b128 v[238:241], v189 offset:23552
	global_load_lds_dwordx4 v[170:171], off
	s_add_i32 m0, s2, 0x2000
	s_add_u32 s12, s14, 0x160000
	v_lshl_add_u64 v[172:173], s[14:15], 0, v[132:133]
	s_addc_u32 s13, s15, 0
	s_add_i32 s2, s24, s27
	global_load_lds_dwordx4 v[172:173], off
	v_lshl_add_u64 v[242:243], s[12:13], 0, v[136:137]
	s_mov_b32 m0, s2
	v_lshl_add_u64 v[244:245], s[16:17], 0, v[134:135]
	global_load_lds_dwordx4 v[242:243], off
	v_lshl_add_u64 v[242:243], s[12:13], 0, v[132:133]
	s_add_i32 m0, s2, 0x2000
	s_nop 0
	global_load_lds_dwordx4 v[242:243], off
	v_lshl_add_u64 v[242:243], s[16:17], 0, v[138:139]
	s_mov_b32 m0, s34
	s_nop 0
	global_load_lds_dwordx4 v[242:243], off
	s_mov_b32 m0, s35
	s_nop 0
	global_load_lds_dwordx4 v[244:245], off
	s_waitcnt vmcnt(8)
	s_waitcnt lgkmcnt(0)
	s_barrier
; #define PG8_STAGE(bufoff, gbase, voff) do { _Pragma("unroll") for (int _i = 0; _i < 2; ++_i) \
;         __builtin_amdgcn_global_load_lds((const unsigned*)((const char*)(gbase) + (voff)[_i]), (LAS unsigned*)(lds + (bufoff) + ldsw + _i * 8192), 16, 0, 0); } while (0)
; #define PG8_LDA(dst, b, h) do { _Pragma("unroll") for (int m = 0; m < 4; ++m) _Pragma("unroll") for (int k = 0; k < 2; ++k) dst[m][k] = *(const LAS bf16x8*)(lds + PG8_SA(b, h) + aoff + m * 2048 + k * 1024); } while (0)
; #define PG8_LDB(dst, b, h) do { _Pragma("unroll") for (int n = 0; n < 2; ++n) _Pragma("unroll") for (int k = 0; k < 2; ++k) dst[n][k] = *(const LAS bf16x8*)(lds + PG8_SB(b, h) + boff + n * 2048 + k * 1024); } while (0)
; #define PG8_MMA(ai, bj, At, Bt) do { __builtin_amdgcn_s_setprio(1); _Pragma("unroll") for (int m = 0; m < 4; ++m) _Pragma("unroll") for (int n = 0; n < 2; ++n) _Pragma("unroll") for (int k = 0; k < 2; ++k) \
;         acc[ai][bj][m][n] = __builtin_amdgcn_mfma_f32_16x16x32_bf16(Bt[n][k], At[m][k], acc[ai][bj][m][n], 0, 0, 0); __builtin_amdgcn_s_setprio(0); } while (0)
; #define PG8_WAIT_V(n) asm volatile("s_waitcnt vmcnt(" #n ")" ::: "memory")
; #define PG8_WAIT_L(n) asm volatile("s_waitcnt lgkmcnt(" #n ")" ::: "memory")
; #define PG8_BAR __builtin_amdgcn_s_barrier()
; #define PG8_SCHED __builtin_amdgcn_sched_barrier(0)
; template <class Epi>
; __device__ __forceinline__ void gemm_phase(LAS unsigned char* lds, const Gemm g, const StaticOrder& S, const Epi& E, const int tid) {
;     ...
;             PG8_WAIT_V(8); PG8_WAIT_L(0); PG8_BAR; PG8_MMA(1, 0, At, B0); PG8_MMA(1, 1, At, B1); PG8_BAR; PG8_SCHED;
;             PG8_LDB(B0, 1, 0); PG8_LDB(B1, 1, 1); PG8_SCHED; PG8_LDA(At, 1, 0); PG8_STAGE(PG8_SA(0, 1), a2 + hsA, voffA);
;             PG8_WAIT_V(8); PG8_WAIT_L(0); PG8_BAR; PG8_MMA(0, 0, At, B0); PG8_MMA(0, 1, At, B1); PG8_BAR; PG8_SCHED;
	v_mfma_f32_16x16x32_bf16 v[60:63], v[128:131], v[194:197], 0
	v_mfma_f32_16x16x32_bf16 v[56:59], v[148:151], v[194:197], 0
	v_mfma_f32_16x16x32_bf16 v[44:47], v[128:131], v[202:205], 0
	v_mfma_f32_16x16x32_bf16 v[40:43], v[148:151], v[202:205], 0
	v_mfma_f32_16x16x32_bf16 v[28:31], v[128:131], v[210:213], 0
	v_mfma_f32_16x16x32_bf16 v[24:27], v[148:151], v[210:213], 0
	v_mfma_f32_16x16x32_bf16 v[12:15], v[128:131], v[234:237], 0
	v_mfma_f32_16x16x32_bf16 v[8:11], v[148:151], v[234:237], 0
	v_mfma_f32_16x16x32_bf16 v[60:63], v[144:147], v[198:201], v[60:63]
	v_mfma_f32_16x16x32_bf16 v[56:59], v[152:155], v[198:201], v[56:59]
	v_mfma_f32_16x16x32_bf16 v[44:47], v[144:147], v[206:209], v[44:47]
	v_mfma_f32_16x16x32_bf16 v[40:43], v[152:155], v[206:209], v[40:43]
	v_mfma_f32_16x16x32_bf16 v[28:31], v[144:147], v[230:233], v[28:31]
	v_mfma_f32_16x16x32_bf16 v[24:27], v[152:155], v[230:233], v[24:27]
	v_mfma_f32_16x16x32_bf16 v[12:15], v[144:147], v[238:241], v[12:15]
	v_mfma_f32_16x16x32_bf16 v[8:11], v[152:155], v[238:241], v[8:11]
	v_mfma_f32_16x16x32_bf16 v[52:55], v[156:159], v[194:197], 0
	v_mfma_f32_16x16x32_bf16 v[48:51], v[164:167], v[194:197], 0
	v_mfma_f32_16x16x32_bf16 v[36:39], v[156:159], v[202:205], 0
	v_mfma_f32_16x16x32_bf16 v[32:35], v[164:167], v[202:205], 0
	v_mfma_f32_16x16x32_bf16 v[20:23], v[156:159], v[210:213], 0
	v_mfma_f32_16x16x32_bf16 v[16:19], v[164:167], v[210:213], 0
	v_mfma_f32_16x16x32_bf16 v[4:7], v[156:159], v[234:237], 0
	v_mfma_f32_16x16x32_bf16 v[0:3], v[164:167], v[234:237], 0
	v_mfma_f32_16x16x32_bf16 v[52:55], v[160:163], v[198:201], v[52:55]
	v_mfma_f32_16x16x32_bf16 v[48:51], v[190:193], v[198:201], v[48:51]
	v_mfma_f32_16x16x32_bf16 v[36:39], v[160:163], v[206:209], v[36:39]
	v_mfma_f32_16x16x32_bf16 v[32:35], v[190:193], v[206:209], v[32:35]
	v_mfma_f32_16x16x32_bf16 v[20:23], v[160:163], v[230:233], v[20:23]
	v_mfma_f32_16x16x32_bf16 v[16:19], v[190:193], v[230:233], v[16:19]
	v_mfma_f32_16x16x32_bf16 v[4:7], v[160:163], v[238:241], v[4:7]
	v_mfma_f32_16x16x32_bf16 v[0:3], v[190:193], v[238:241], v[0:3]
	s_barrier
	s_add_i32 s2, 0, 0x18000
	s_add_i32 s24, 0, 0x1c000
	v_add_u32_e32 v152, s2, v184
	v_add_u32_e32 v190, s24, v184
	ds_read_b128 v[128:131], v152
	ds_read_b128 v[144:147], v152 offset:1024
	ds_read_b128 v[148:151], v152 offset:2048
	ds_read_b128 v[152:155], v152 offset:3072
	ds_read_b128 v[156:159], v190
	ds_read_b128 v[160:163], v190 offset:1024
	ds_read_b128 v[164:167], v190 offset:2048
	ds_read_b128 v[190:193], v190 offset:3072
	s_add_u32 s12, s16, 0x160000
	s_addc_u32 s13, s17, 0
	s_mov_b32 m0, s40
	v_lshl_add_u64 v[246:247], s[12:13], 0, v[138:139]
	ds_read_b128 v[194:197], v189 offset:32768
	ds_read_b128 v[198:201], v189 offset:33792
	ds_read_b128 v[202:205], v189 offset:34816
	ds_read_b128 v[206:209], v189 offset:35840
	ds_read_b128 v[210:213], v189 offset:36864
	ds_read_b128 v[230:233], v189 offset:37888
	ds_read_b128 v[234:237], v189 offset:38912
	ds_read_b128 v[238:241], v189 offset:39936
	global_load_lds_dwordx4 v[246:247], off
	v_lshl_add_u64 v[246:247], s[12:13], 0, v[134:135]
	s_mov_b32 m0, s41
	s_nop 0
	global_load_lds_dwordx4 v[246:247], off
	s_waitcnt vmcnt(8)
	s_waitcnt lgkmcnt(0)
	s_barrier
	v_mfma_f32_16x16x32_bf16 v[124:127], v[128:131], v[194:197], v[124:127]
	v_mfma_f32_16x16x32_bf16 v[120:123], v[148:151], v[194:197], v[120:123]
	v_mfma_f32_16x16x32_bf16 v[108:111], v[128:131], v[202:205], v[108:111]
	v_mfma_f32_16x16x32_bf16 v[104:107], v[148:151], v[202:205], v[104:107]
	v_mfma_f32_16x16x32_bf16 v[92:95], v[128:131], v[210:213], v[92:95]
	v_mfma_f32_16x16x32_bf16 v[88:91], v[148:151], v[210:213], v[88:91]
	v_mfma_f32_16x16x32_bf16 v[80:83], v[128:131], v[234:237], v[80:83]
	v_mfma_f32_16x16x32_bf16 v[72:75], v[148:151], v[234:237], v[72:75]
	v_mfma_f32_16x16x32_bf16 v[124:127], v[144:147], v[198:201], v[124:127]
	v_mfma_f32_16x16x32_bf16 v[120:123], v[152:155], v[198:201], v[120:123]
	v_mfma_f32_16x16x32_bf16 v[108:111], v[144:147], v[206:209], v[108:111]
	v_mfma_f32_16x16x32_bf16 v[104:107], v[152:155], v[206:209], v[104:107]
	v_mfma_f32_16x16x32_bf16 v[92:95], v[144:147], v[230:233], v[92:95]
	v_mfma_f32_16x16x32_bf16 v[88:91], v[152:155], v[230:233], v[88:91]
	v_mfma_f32_16x16x32_bf16 v[80:83], v[144:147], v[238:241], v[80:83]
	v_mfma_f32_16x16x32_bf16 v[72:75], v[152:155], v[238:241], v[72:75]
	v_mfma_f32_16x16x32_bf16 v[116:119], v[156:159], v[194:197], v[116:119]
	v_mfma_f32_16x16x32_bf16 v[112:115], v[164:167], v[194:197], v[112:115]
	v_mfma_f32_16x16x32_bf16 v[100:103], v[156:159], v[202:205], v[100:103]
	v_mfma_f32_16x16x32_bf16 v[96:99], v[164:167], v[202:205], v[96:99]
	v_mfma_f32_16x16x32_bf16 v[84:87], v[156:159], v[210:213], v[84:87]
	v_mfma_f32_16x16x32_bf16 v[76:79], v[164:167], v[210:213], v[76:79]
	v_mfma_f32_16x16x32_bf16 v[68:71], v[156:159], v[234:237], v[68:71]
	v_mfma_f32_16x16x32_bf16 v[64:67], v[164:167], v[234:237], v[64:67]
	v_mfma_f32_16x16x32_bf16 v[116:119], v[160:163], v[198:201], v[116:119]
	v_mfma_f32_16x16x32_bf16 v[112:115], v[190:193], v[198:201], v[112:115]
	v_mfma_f32_16x16x32_bf16 v[100:103], v[160:163], v[206:209], v[100:103]
	v_mfma_f32_16x16x32_bf16 v[96:99], v[190:193], v[206:209], v[96:99]
	v_mfma_f32_16x16x32_bf16 v[84:87], v[160:163], v[230:233], v[84:87]
	v_mfma_f32_16x16x32_bf16 v[76:79], v[190:193], v[230:233], v[76:79]
	v_mfma_f32_16x16x32_bf16 v[68:71], v[160:163], v[238:241], v[68:71]
	v_mfma_f32_16x16x32_bf16 v[64:67], v[190:193], v[238:241], v[64:67]
	s_barrier
; #define PG8_STAGE(bufoff, gbase, voff) do { _Pragma("unroll") for (int _i = 0; _i < 2; ++_i) \
;         __builtin_amdgcn_global_load_lds((const unsigned*)((const char*)(gbase) + (voff)[_i]), (LAS unsigned*)(lds + (bufoff) + ldsw + _i * 8192), 16, 0, 0); } while (0)
; #define PG8_LDA(dst, b, h) do { _Pragma("unroll") for (int m = 0; m < 4; ++m) _Pragma("unroll") for (int k = 0; k < 2; ++k) dst[m][k] = *(const LAS bf16x8*)(lds + PG8_SA(b, h) + aoff + m * 2048 + k * 1024); } while (0)
; #define PG8_MMA(ai, bj, At, Bt) do { __builtin_amdgcn_s_setprio(1); _Pragma("unroll") for (int m = 0; m < 4; ++m) _Pragma("unroll") for (int n = 0; n < 2; ++n) _Pragma("unroll") for (int k = 0; k < 2; ++k) \
;         acc[ai][bj][m][n] = __builtin_amdgcn_mfma_f32_16x16x32_bf16(Bt[n][k], At[m][k], acc[ai][bj][m][n], 0, 0, 0); __builtin_amdgcn_s_setprio(0); } while (0)
; #define PG8_WAIT_V(n) asm volatile("s_waitcnt vmcnt(" #n ")" ::: "memory")
; #define PG8_WAIT_L(n) asm volatile("s_waitcnt lgkmcnt(" #n ")" ::: "memory")
; #define PG8_BAR __builtin_amdgcn_s_barrier()
; #define PG8_SCHED __builtin_amdgcn_sched_barrier(0)
; template <class Epi>
; __device__ __forceinline__ void gemm_phase(LAS unsigned char* lds, const Gemm g, const StaticOrder& S, const Epi& E, const int tid) {
;     ...
;             PG8_WAIT_V(8); PG8_WAIT_L(0); PG8_BAR; PG8_MMA(0, 0, At, B0); PG8_MMA(0, 1, At, B1); PG8_BAR; PG8_SCHED;
;             PG8_LDA(At, 1, 1); PG8_STAGE(PG8_SB(1, 0), b3, voffB); PG8_STAGE(PG8_SB(1, 1), b3 + hsB, voffB); PG8_STAGE(PG8_SA(1, 0), a3, voffA);
;             PG8_WAIT_V(8); PG8_WAIT_L(0); PG8_BAR; PG8_MMA(1, 0, At, B0); PG8_MMA(1, 1, At, B1); PG8_BAR; PG8_SCHED;
	s_add_i32 s2, s2, s27
	v_lshl_add_u64 v[170:171], v[170:171], 0, s[28:29]
	s_mov_b32 m0, s2
	ds_read_b128 v[194:197], v189 offset:49152
	ds_read_b128 v[198:201], v189 offset:50176
	ds_read_b128 v[202:205], v189 offset:51200
	ds_read_b128 v[206:209], v189 offset:52224
	ds_read_b128 v[210:213], v189 offset:53248
	ds_read_b128 v[230:233], v189 offset:54272
	ds_read_b128 v[234:237], v189 offset:55296
	ds_read_b128 v[238:241], v189 offset:56320
	global_load_lds_dwordx4 v[170:171], off
	s_add_i32 m0, s2, 0x2000
	s_add_u32 s12, s14, 0x160080
	v_lshl_add_u64 v[170:171], v[172:173], 0, s[28:29]
	s_addc_u32 s13, s15, 0
	s_add_i32 s2, s24, s27
	global_load_lds_dwordx4 v[170:171], off
	v_lshl_add_u64 v[170:171], s[12:13], 0, v[136:137]
	s_mov_b32 m0, s2
	s_nop 0
	global_load_lds_dwordx4 v[170:171], off
	v_lshl_add_u64 v[170:171], s[12:13], 0, v[132:133]
	s_add_i32 m0, s2, 0x2000
	s_nop 0
	global_load_lds_dwordx4 v[170:171], off
	v_lshl_add_u64 v[170:171], v[242:243], 0, s[28:29]
	s_mov_b32 m0, s44
	s_nop 0
	global_load_lds_dwordx4 v[170:171], off
	v_lshl_add_u64 v[170:171], v[244:245], 0, s[28:29]
	s_mov_b32 m0, s45
	s_nop 0
	global_load_lds_dwordx4 v[170:171], off
	s_waitcnt vmcnt(8)
	s_waitcnt lgkmcnt(0)
	s_barrier
	v_mfma_f32_16x16x32_bf16 v[60:63], v[128:131], v[194:197], v[60:63]
	v_mfma_f32_16x16x32_bf16 v[56:59], v[148:151], v[194:197], v[56:59]
	v_mfma_f32_16x16x32_bf16 v[44:47], v[128:131], v[202:205], v[44:47]
	v_mfma_f32_16x16x32_bf16 v[40:43], v[148:151], v[202:205], v[40:43]
	v_mfma_f32_16x16x32_bf16 v[28:31], v[128:131], v[210:213], v[28:31]
	v_mfma_f32_16x16x32_bf16 v[24:27], v[148:151], v[210:213], v[24:27]
	v_mfma_f32_16x16x32_bf16 v[12:15], v[128:131], v[234:237], v[12:15]
	v_mfma_f32_16x16x32_bf16 v[8:11], v[148:151], v[234:237], v[8:11]
	v_mfma_f32_16x16x32_bf16 v[60:63], v[144:147], v[198:201], v[60:63]
	v_mfma_f32_16x16x32_bf16 v[56:59], v[152:155], v[198:201], v[56:59]
	v_mfma_f32_16x16x32_bf16 v[44:47], v[144:147], v[206:209], v[44:47]
	v_mfma_f32_16x16x32_bf16 v[40:43], v[152:155], v[206:209], v[40:43]
	v_mfma_f32_16x16x32_bf16 v[28:31], v[144:147], v[230:233], v[28:31]
	v_mfma_f32_16x16x32_bf16 v[24:27], v[152:155], v[230:233], v[24:27]
	v_mfma_f32_16x16x32_bf16 v[12:15], v[144:147], v[238:241], v[12:15]
	v_mfma_f32_16x16x32_bf16 v[8:11], v[152:155], v[238:241], v[8:11]
	v_mfma_f32_16x16x32_bf16 v[52:55], v[156:159], v[194:197], v[52:55]
	v_mfma_f32_16x16x32_bf16 v[48:51], v[164:167], v[194:197], v[48:51]
	v_mfma_f32_16x16x32_bf16 v[36:39], v[156:159], v[202:205], v[36:39]
	v_mfma_f32_16x16x32_bf16 v[32:35], v[164:167], v[202:205], v[32:35]
	v_mfma_f32_16x16x32_bf16 v[20:23], v[156:159], v[210:213], v[20:23]
	v_mfma_f32_16x16x32_bf16 v[16:19], v[164:167], v[210:213], v[16:19]
	v_mfma_f32_16x16x32_bf16 v[4:7], v[156:159], v[234:237], v[4:7]
	v_mfma_f32_16x16x32_bf16 v[0:3], v[164:167], v[234:237], v[0:3]
	v_mfma_f32_16x16x32_bf16 v[52:55], v[160:163], v[198:201], v[52:55]
	v_mfma_f32_16x16x32_bf16 v[48:51], v[190:193], v[198:201], v[48:51]
	v_mfma_f32_16x16x32_bf16 v[36:39], v[160:163], v[206:209], v[36:39]
	v_mfma_f32_16x16x32_bf16 v[32:35], v[190:193], v[206:209], v[32:35]
	v_mfma_f32_16x16x32_bf16 v[20:23], v[160:163], v[230:233], v[20:23]
	v_mfma_f32_16x16x32_bf16 v[16:19], v[190:193], v[230:233], v[16:19]
	v_mfma_f32_16x16x32_bf16 v[4:7], v[160:163], v[238:241], v[4:7]
	v_mfma_f32_16x16x32_bf16 v[0:3], v[190:193], v[238:241], v[0:3]
	s_barrier
	s_add_i32 s53, s53, 2
	s_add_u32 s38, s38, 0x100
	s_addc_u32 s39, s39, 0
	s_cmpk_gt_u32 s53, 0x55
	s_mov_b64 s[12:13], s[0:1]
